# GEMM K-loops: static priority raise for waves 4-7 instead of per-segment toggling (on v73)
# speedup vs baseline: 1.0082x; 1.0034x over previous
; #define PG8_STAGE(bufoff, gbase, voff) do { _Pragma("unroll") for (int _i = 0; _i < 2; ++_i) \
;         __builtin_amdgcn_global_load_lds((const unsigned*)((const char*)(gbase) + (voff)[_i]), (LAS unsigned*)(lds + (bufoff) + ldsw + _i * 8192), 16, 0, 0); } while (0)
; #define PG8_LDA(dst, b, h) do { _Pragma("unroll") for (int m = 0; m < 4; ++m) _Pragma("unroll") for (int k = 0; k < 2; ++k) dst[m][k] = *(const LAS bf16x8*)(lds + PG8_SA(b, h) + aoff + m * 2048 + k * 1024); } while (0)
; #define PG8_LDB(dst, b, h) do { _Pragma("unroll") for (int n = 0; n < 2; ++n) _Pragma("unroll") for (int k = 0; k < 2; ++k) dst[n][k] = *(const LAS bf16x8*)(lds + PG8_SB(b, h) + boff + n * 2048 + k * 1024); } while (0)
; #define PG8_MMA(ai, bj, At, Bt) do { __builtin_amdgcn_s_setprio(1); _Pragma("unroll") for (int m = 0; m < 4; ++m) _Pragma("unroll") for (int n = 0; n < 2; ++n) _Pragma("unroll") for (int k = 0; k < 2; ++k) \
;         acc[ai][bj][m][n] = __builtin_amdgcn_mfma_f32_16x16x32_bf16(Bt[n][k], At[m][k], acc[ai][bj][m][n], 0, 0, 0); __builtin_amdgcn_s_setprio(0); } while (0)
; template <class Epi, bool ALIGN_EPI, int K, int LDA, int LDB>
; __device__ __forceinline__ void gemm_phase(LAS unsigned char* lds, const int wid, const Gemm g, const StaticOrder& S, const Epi& E) {
;     ...
;         const bool has_next = S.next(ui + 1, nxt);
;         const char* nA = has_next ? (const char*)g.A + (size_t)nxt.pm * tA : cA; const char* nB = has_next ? (const char*)g.Bt + (size_t)nxt.pn * tB : cB;
;         for (int t = 0; t < nt; t += 2) {
;             const bool last = (t == nt - 2);
;             const char* a1 = cA + (size_t)(t + 1) * kstep;
;             const char* a2 = last ? nA : cA + (size_t)(t + 2) * kstep; const char* b2 = last ? nB : cB + (size_t)(t + 2) * kstep;
;             const char* a3 = a2 + kstep; const char* b3 = b2 + kstep;
;             PG8_LDB(B0, 0, 0); PG8_LDB(B1, 0, 1); PG8_SCHED; PG8_LDA(At, 0, 0); PG8_STAGE(PG8_SA(1, 1), a1 + hA, voffA);
;             PG8_WAIT_V(8); PG8_WAIT_L(0); PG8_BAR; PG8_MMA(0, 0, At, B0); PG8_MMA(0, 1, At, B1); PG8_BAR; PG8_SCHED;
;             PG8_LDA(At, 0, 1); PG8_STAGE(PG8_SB(0, 0), b2, voffB); PG8_STAGE(PG8_SB(0, 1), b2 + hB, voffB); PG8_STAGE(PG8_SA(0, 0), a2, voffA);
;             PG8_WAIT_V(8); PG8_WAIT_L(0); PG8_BAR; PG8_MMA(1, 0, At, B0); PG8_MMA(1, 1, At, B1); PG8_BAR; PG8_SCHED;
.LBB0_231:
	s_ashr_i32 s17, s16, 31
	s_lshl_b64 s[18:19], s[16:17], 19
	v_readlane_b32 s15, v254, 0
	s_add_u32 s18, s15, s18
	v_readlane_b32 s15, v254, 1
	s_addc_u32 s19, s15, s19
	s_and_b64 s[20:21], s[4:5], exec
	s_cselect_b32 s17, s19, s23
	s_cselect_b32 s48, s18, s22
	s_ashr_i32 s15, s14, 31
	s_lshl_b64 s[20:21], s[14:15], 19
	s_add_u32 s20, s0, s20
	s_addc_u32 s21, s1, s21
	s_and_b64 s[26:27], s[4:5], exec
	s_cselect_b32 s15, s21, s25
	s_cselect_b32 s49, s20, s24
	s_add_u32 s22, s22, 0x40080
	s_addc_u32 s23, s23, 0
	s_add_u32 s51, s24, 0x100
	s_addc_u32 s54, s25, 0
	s_mov_b32 s55, -2
	s_add_u32 s24, s22, 0xfffc0080
	s_addc_u32 s25, s23, -1
	s_cmp_eq_u32 s55, 12
	s_cselect_b32 s27, s17, s25
	s_cselect_b32 s26, s48, s24
	s_cselect_b32 s25, s15, s54
	s_cselect_b32 s24, s49, s51
	s_add_i32 m0, s13, 0xc000
	global_load_lds_dwordx4 v136, s[22:23]
	s_add_i32 m0, s13, 0xe000
	s_nop 0
	global_load_lds_dwordx4 v138, s[22:23]
	s_waitcnt vmcnt(8)
	s_barrier
	s_waitcnt lgkmcnt(0)
	v_mfma_f32_16x16x32_bf16 v[124:127], v[148:151], v[180:183], 0
	v_mfma_f32_16x16x32_bf16 v[120:123], v[156:159], v[180:183], 0
	v_mfma_f32_16x16x32_bf16 v[116:119], v[148:151], v[188:191], 0
	v_mfma_f32_16x16x32_bf16 v[112:115], v[156:159], v[188:191], 0
	v_mfma_f32_16x16x32_bf16 v[100:103], v[148:151], v[196:199], 0
	v_mfma_f32_16x16x32_bf16 v[96:99], v[156:159], v[196:199], 0
	v_mfma_f32_16x16x32_bf16 v[84:87], v[148:151], v[204:207], 0
	v_mfma_f32_16x16x32_bf16 v[80:83], v[156:159], v[204:207], 0
	v_mfma_f32_16x16x32_bf16 v[124:127], v[152:155], v[184:187], v[124:127]
	v_mfma_f32_16x16x32_bf16 v[120:123], v[160:163], v[184:187], v[120:123]
	v_mfma_f32_16x16x32_bf16 v[116:119], v[152:155], v[192:195], v[116:119]
	v_mfma_f32_16x16x32_bf16 v[112:115], v[160:163], v[192:195], v[112:115]
	v_mfma_f32_16x16x32_bf16 v[100:103], v[152:155], v[200:203], v[100:103]
	v_mfma_f32_16x16x32_bf16 v[96:99], v[160:163], v[200:203], v[96:99]
	v_mfma_f32_16x16x32_bf16 v[84:87], v[152:155], v[208:211], v[84:87]
	v_mfma_f32_16x16x32_bf16 v[80:83], v[160:163], v[208:211], v[80:83]
	v_mfma_f32_16x16x32_bf16 v[108:111], v[164:167], v[180:183], 0
	v_mfma_f32_16x16x32_bf16 v[104:107], v[172:175], v[180:183], 0
	v_mfma_f32_16x16x32_bf16 v[92:95], v[164:167], v[188:191], 0
	v_mfma_f32_16x16x32_bf16 v[88:91], v[172:175], v[188:191], 0
	v_mfma_f32_16x16x32_bf16 v[76:79], v[164:167], v[196:199], 0
	v_mfma_f32_16x16x32_bf16 v[72:75], v[172:175], v[196:199], 0
	v_mfma_f32_16x16x32_bf16 v[68:71], v[164:167], v[204:207], 0
	v_mfma_f32_16x16x32_bf16 v[64:67], v[172:175], v[204:207], 0
	v_mfma_f32_16x16x32_bf16 v[108:111], v[168:171], v[184:187], v[108:111]
	v_mfma_f32_16x16x32_bf16 v[104:107], v[176:179], v[184:187], v[104:107]
	v_mfma_f32_16x16x32_bf16 v[92:95], v[168:171], v[192:195], v[92:95]
	v_mfma_f32_16x16x32_bf16 v[88:91], v[176:179], v[192:195], v[88:91]
	v_mfma_f32_16x16x32_bf16 v[76:79], v[168:171], v[200:203], v[76:79]
	v_mfma_f32_16x16x32_bf16 v[72:75], v[176:179], v[200:203], v[72:75]
	v_mfma_f32_16x16x32_bf16 v[68:71], v[168:171], v[208:211], v[68:71]
	v_mfma_f32_16x16x32_bf16 v[64:67], v[176:179], v[208:211], v[64:67]
	s_barrier
	s_add_u32 s98, s24, s10
	s_addc_u32 s99, s25, s11
	s_add_u32 s100, s26, s10
	s_addc_u32 s101, s27, s11
	s_add_i32 s56, s40, s3
	s_mov_b32 m0, s56
	ds_read_b128 v[180:183], v147 offset:16384
	ds_read_b128 v[184:187], v147 offset:17408
	ds_read_b128 v[188:191], v147 offset:18432
	ds_read_b128 v[192:195], v147 offset:19456
	ds_read_b128 v[196:199], v147 offset:20480
	ds_read_b128 v[200:203], v147 offset:21504
	ds_read_b128 v[204:207], v147 offset:22528
	ds_read_b128 v[208:211], v147 offset:23552
	global_load_lds_dwordx4 v132, s[24:25]
	s_add_i32 m0, s56, 0x2000
	s_add_u32 s56, s24, 0x40000
	s_addc_u32 s57, s25, 0
	s_add_i32 s58, s41, s3
	global_load_lds_dwordx4 v128, s[24:25]
	s_mov_b32 m0, s58
	s_nop 0
	global_load_lds_dwordx4 v132, s[56:57]
	s_add_i32 m0, s58, 0x2000
	s_nop 0
	global_load_lds_dwordx4 v128, s[56:57]
	s_mov_b32 m0, s13
	s_nop 0
	global_load_lds_dwordx4 v134, s[26:27]
	s_mov_b32 m0, s30
	s_nop 0
	global_load_lds_dwordx4 v130, s[26:27]
	s_waitcnt vmcnt(8)
	s_barrier
	s_waitcnt lgkmcnt(0)
	v_mfma_f32_16x16x32_bf16 v[60:63], v[148:151], v[180:183], 0
	v_mfma_f32_16x16x32_bf16 v[56:59], v[156:159], v[180:183], 0
	v_mfma_f32_16x16x32_bf16 v[52:55], v[148:151], v[188:191], 0
	v_mfma_f32_16x16x32_bf16 v[48:51], v[156:159], v[188:191], 0
	v_mfma_f32_16x16x32_bf16 v[36:39], v[148:151], v[196:199], 0
	v_mfma_f32_16x16x32_bf16 v[32:35], v[156:159], v[196:199], 0
	v_mfma_f32_16x16x32_bf16 v[20:23], v[148:151], v[204:207], 0
	v_mfma_f32_16x16x32_bf16 v[16:19], v[156:159], v[204:207], 0
	v_mfma_f32_16x16x32_bf16 v[60:63], v[152:155], v[184:187], v[60:63]
	v_mfma_f32_16x16x32_bf16 v[56:59], v[160:163], v[184:187], v[56:59]
	v_mfma_f32_16x16x32_bf16 v[52:55], v[152:155], v[192:195], v[52:55]
	v_mfma_f32_16x16x32_bf16 v[48:51], v[160:163], v[192:195], v[48:51]
	v_mfma_f32_16x16x32_bf16 v[36:39], v[152:155], v[200:203], v[36:39]
	v_mfma_f32_16x16x32_bf16 v[32:35], v[160:163], v[200:203], v[32:35]
	v_mfma_f32_16x16x32_bf16 v[20:23], v[152:155], v[208:211], v[20:23]
	v_mfma_f32_16x16x32_bf16 v[16:19], v[160:163], v[208:211], v[16:19]
	v_mfma_f32_16x16x32_bf16 v[44:47], v[164:167], v[180:183], 0
	v_mfma_f32_16x16x32_bf16 v[40:43], v[172:175], v[180:183], 0
	v_mfma_f32_16x16x32_bf16 v[28:31], v[164:167], v[188:191], 0
	v_mfma_f32_16x16x32_bf16 v[24:27], v[172:175], v[188:191], 0
	v_mfma_f32_16x16x32_bf16 v[12:15], v[164:167], v[196:199], 0
	v_mfma_f32_16x16x32_bf16 v[8:11], v[172:175], v[196:199], 0
	v_mfma_f32_16x16x32_bf16 v[4:7], v[164:167], v[204:207], 0
	v_mfma_f32_16x16x32_bf16 v[0:3], v[172:175], v[204:207], 0
	v_mfma_f32_16x16x32_bf16 v[44:47], v[168:171], v[184:187], v[44:47]
	v_mfma_f32_16x16x32_bf16 v[40:43], v[176:179], v[184:187], v[40:43]
	v_mfma_f32_16x16x32_bf16 v[28:31], v[168:171], v[192:195], v[28:31]
	v_mfma_f32_16x16x32_bf16 v[24:27], v[176:179], v[192:195], v[24:27]
	v_mfma_f32_16x16x32_bf16 v[12:15], v[168:171], v[200:203], v[12:15]
	v_mfma_f32_16x16x32_bf16 v[8:11], v[176:179], v[200:203], v[8:11]
	v_mfma_f32_16x16x32_bf16 v[4:7], v[168:171], v[208:211], v[4:7]
	v_mfma_f32_16x16x32_bf16 v[0:3], v[176:179], v[208:211], v[0:3]
	s_barrier
; #define PG8_STAGE(bufoff, gbase, voff) do { _Pragma("unroll") for (int _i = 0; _i < 2; ++_i) \
;         __builtin_amdgcn_global_load_lds((const unsigned*)((const char*)(gbase) + (voff)[_i]), (LAS unsigned*)(lds + (bufoff) + ldsw + _i * 8192), 16, 0, 0); } while (0)
; #define PG8_LDA(dst, b, h) do { _Pragma("unroll") for (int m = 0; m < 4; ++m) _Pragma("unroll") for (int k = 0; k < 2; ++k) dst[m][k] = *(const LAS bf16x8*)(lds + PG8_SA(b, h) + aoff + m * 2048 + k * 1024); } while (0)
; #define PG8_LDB(dst, b, h) do { _Pragma("unroll") for (int n = 0; n < 2; ++n) _Pragma("unroll") for (int k = 0; k < 2; ++k) dst[n][k] = *(const LAS bf16x8*)(lds + PG8_SB(b, h) + boff + n * 2048 + k * 1024); } while (0)
; #define PG8_MMA(ai, bj, At, Bt) do { __builtin_amdgcn_s_setprio(1); _Pragma("unroll") for (int m = 0; m < 4; ++m) _Pragma("unroll") for (int n = 0; n < 2; ++n) _Pragma("unroll") for (int k = 0; k < 2; ++k) \
;         acc[ai][bj][m][n] = __builtin_amdgcn_mfma_f32_16x16x32_bf16(Bt[n][k], At[m][k], acc[ai][bj][m][n], 0, 0, 0); __builtin_amdgcn_s_setprio(0); } while (0)
; #define PG8_WAIT_V(n) asm volatile("s_waitcnt vmcnt(" #n ")" ::: "memory")
; #define PG8_WAIT_L(n) asm volatile("s_waitcnt lgkmcnt(" #n ")" ::: "memory")
; #define PG8_BAR __builtin_amdgcn_s_barrier()
; #define PG8_SCHED __builtin_amdgcn_sched_barrier(0)
; template <class Epi, bool ALIGN_EPI, int K, int LDA, int LDB>
; __device__ __forceinline__ void gemm_phase(LAS unsigned char* lds, const int wid, const Gemm g, const StaticOrder& S, const Epi& E) {
;     ...
;             PG8_LDB(B0, 1, 0); PG8_LDB(B1, 1, 1); PG8_SCHED; PG8_LDA(At, 1, 0); PG8_STAGE(PG8_SA(0, 1), a2 + hA, voffA);
;             PG8_WAIT_V(8); PG8_WAIT_L(0); PG8_BAR; PG8_MMA(0, 0, At, B0); PG8_MMA(0, 1, At, B1); PG8_BAR; PG8_SCHED;
;             PG8_LDA(At, 1, 1); PG8_STAGE(PG8_SB(1, 0), b3, voffB); PG8_STAGE(PG8_SB(1, 1), b3 + hB, voffB); PG8_STAGE(PG8_SA(1, 0), a3, voffA);
;             PG8_WAIT_V(8); PG8_WAIT_L(0); PG8_BAR; PG8_MMA(1, 0, At, B0); PG8_MMA(1, 1, At, B1); PG8_BAR; PG8_SCHED;
	s_add_i32 s56, 0, 0x18000
	s_add_i32 s57, 0, 0x1c000
	v_add_u32_e32 v160, s56, v144
	v_add_u32_e32 v176, s57, v144
	ds_read_b128 v[148:151], v160
	ds_read_b128 v[152:155], v160 offset:1024
	ds_read_b128 v[156:159], v160 offset:2048
	ds_read_b128 v[160:163], v160 offset:3072
	ds_read_b128 v[164:167], v176
	ds_read_b128 v[168:171], v176 offset:1024
	ds_read_b128 v[172:175], v176 offset:2048
	ds_read_b128 v[176:179], v176 offset:3072
	s_add_u32 s26, s26, 0x40000
	s_addc_u32 s27, s27, 0
	s_mov_b32 m0, s31
	ds_read_b128 v[180:183], v147 offset:32768
	ds_read_b128 v[184:187], v147 offset:33792
	ds_read_b128 v[188:191], v147 offset:34816
	ds_read_b128 v[192:195], v147 offset:35840
	ds_read_b128 v[196:199], v147 offset:36864
	ds_read_b128 v[200:203], v147 offset:37888
	ds_read_b128 v[204:207], v147 offset:38912
	ds_read_b128 v[208:211], v147 offset:39936
	global_load_lds_dwordx4 v134, s[26:27]
	s_mov_b32 m0, s33
	s_nop 0
	global_load_lds_dwordx4 v130, s[26:27]
	s_waitcnt vmcnt(8)
	s_barrier
	s_waitcnt lgkmcnt(0)
	v_mfma_f32_16x16x32_bf16 v[124:127], v[148:151], v[180:183], v[124:127]
	v_mfma_f32_16x16x32_bf16 v[120:123], v[156:159], v[180:183], v[120:123]
	v_mfma_f32_16x16x32_bf16 v[116:119], v[148:151], v[188:191], v[116:119]
	v_mfma_f32_16x16x32_bf16 v[112:115], v[156:159], v[188:191], v[112:115]
	v_mfma_f32_16x16x32_bf16 v[100:103], v[148:151], v[196:199], v[100:103]
	v_mfma_f32_16x16x32_bf16 v[96:99], v[156:159], v[196:199], v[96:99]
	v_mfma_f32_16x16x32_bf16 v[84:87], v[148:151], v[204:207], v[84:87]
	v_mfma_f32_16x16x32_bf16 v[80:83], v[156:159], v[204:207], v[80:83]
	v_mfma_f32_16x16x32_bf16 v[124:127], v[152:155], v[184:187], v[124:127]
	v_mfma_f32_16x16x32_bf16 v[120:123], v[160:163], v[184:187], v[120:123]
	v_mfma_f32_16x16x32_bf16 v[116:119], v[152:155], v[192:195], v[116:119]
	v_mfma_f32_16x16x32_bf16 v[112:115], v[160:163], v[192:195], v[112:115]
	v_mfma_f32_16x16x32_bf16 v[100:103], v[152:155], v[200:203], v[100:103]
	v_mfma_f32_16x16x32_bf16 v[96:99], v[160:163], v[200:203], v[96:99]
	v_mfma_f32_16x16x32_bf16 v[84:87], v[152:155], v[208:211], v[84:87]
	v_mfma_f32_16x16x32_bf16 v[80:83], v[160:163], v[208:211], v[80:83]
	v_mfma_f32_16x16x32_bf16 v[108:111], v[164:167], v[180:183], v[108:111]
	v_mfma_f32_16x16x32_bf16 v[104:107], v[172:175], v[180:183], v[104:107]
	v_mfma_f32_16x16x32_bf16 v[92:95], v[164:167], v[188:191], v[92:95]
	v_mfma_f32_16x16x32_bf16 v[88:91], v[172:175], v[188:191], v[88:91]
	v_mfma_f32_16x16x32_bf16 v[76:79], v[164:167], v[196:199], v[76:79]
	v_mfma_f32_16x16x32_bf16 v[72:75], v[172:175], v[196:199], v[72:75]
	v_mfma_f32_16x16x32_bf16 v[68:71], v[164:167], v[204:207], v[68:71]
	v_mfma_f32_16x16x32_bf16 v[64:67], v[172:175], v[204:207], v[64:67]
	v_mfma_f32_16x16x32_bf16 v[108:111], v[168:171], v[184:187], v[108:111]
	v_mfma_f32_16x16x32_bf16 v[104:107], v[176:179], v[184:187], v[104:107]
	v_mfma_f32_16x16x32_bf16 v[92:95], v[168:171], v[192:195], v[92:95]
	v_mfma_f32_16x16x32_bf16 v[88:91], v[176:179], v[192:195], v[88:91]
	v_mfma_f32_16x16x32_bf16 v[76:79], v[168:171], v[200:203], v[76:79]
	v_mfma_f32_16x16x32_bf16 v[72:75], v[176:179], v[200:203], v[72:75]
	v_mfma_f32_16x16x32_bf16 v[68:71], v[168:171], v[208:211], v[68:71]
	v_mfma_f32_16x16x32_bf16 v[64:67], v[176:179], v[208:211], v[64:67]
	s_barrier
	s_add_i32 s26, s56, s3
	s_mov_b32 m0, s26
	ds_read_b128 v[180:183], v147 offset:49152
	ds_read_b128 v[184:187], v147 offset:50176
	ds_read_b128 v[188:191], v147 offset:51200
	ds_read_b128 v[192:195], v147 offset:52224
	ds_read_b128 v[196:199], v147 offset:53248
	ds_read_b128 v[200:203], v147 offset:54272
	ds_read_b128 v[204:207], v147 offset:55296
	ds_read_b128 v[208:211], v147 offset:56320
	global_load_lds_dwordx4 v132, s[98:99]
	s_add_i32 m0, s26, 0x2000
	s_add_u32 s24, s24, 0x40080
	s_addc_u32 s25, s25, 0
	s_add_i32 s26, s57, s3
	global_load_lds_dwordx4 v128, s[98:99]
	s_mov_b32 m0, s26
	s_nop 0
	global_load_lds_dwordx4 v132, s[24:25]
	s_add_i32 m0, s26, 0x2000
	s_nop 0
	global_load_lds_dwordx4 v128, s[24:25]
	s_mov_b32 m0, s38
	s_nop 0
	global_load_lds_dwordx4 v134, s[100:101]
	s_mov_b32 m0, s39
	s_nop 0
	global_load_lds_dwordx4 v130, s[100:101]
	s_waitcnt vmcnt(8)
	s_barrier
	s_waitcnt lgkmcnt(0)
	v_mfma_f32_16x16x32_bf16 v[60:63], v[148:151], v[180:183], v[60:63]
	v_mfma_f32_16x16x32_bf16 v[56:59], v[156:159], v[180:183], v[56:59]
	v_mfma_f32_16x16x32_bf16 v[52:55], v[148:151], v[188:191], v[52:55]
	v_mfma_f32_16x16x32_bf16 v[48:51], v[156:159], v[188:191], v[48:51]
	v_mfma_f32_16x16x32_bf16 v[36:39], v[148:151], v[196:199], v[36:39]
	v_mfma_f32_16x16x32_bf16 v[32:35], v[156:159], v[196:199], v[32:35]
	v_mfma_f32_16x16x32_bf16 v[20:23], v[148:151], v[204:207], v[20:23]
	v_mfma_f32_16x16x32_bf16 v[16:19], v[156:159], v[204:207], v[16:19]
	v_mfma_f32_16x16x32_bf16 v[60:63], v[152:155], v[184:187], v[60:63]
	v_mfma_f32_16x16x32_bf16 v[56:59], v[160:163], v[184:187], v[56:59]
	v_mfma_f32_16x16x32_bf16 v[52:55], v[152:155], v[192:195], v[52:55]
	v_mfma_f32_16x16x32_bf16 v[48:51], v[160:163], v[192:195], v[48:51]
	v_mfma_f32_16x16x32_bf16 v[36:39], v[152:155], v[200:203], v[36:39]
	v_mfma_f32_16x16x32_bf16 v[32:35], v[160:163], v[200:203], v[32:35]
	v_mfma_f32_16x16x32_bf16 v[20:23], v[152:155], v[208:211], v[20:23]
	v_mfma_f32_16x16x32_bf16 v[16:19], v[160:163], v[208:211], v[16:19]
	v_mfma_f32_16x16x32_bf16 v[44:47], v[164:167], v[180:183], v[44:47]
	v_mfma_f32_16x16x32_bf16 v[40:43], v[172:175], v[180:183], v[40:43]
	v_mfma_f32_16x16x32_bf16 v[28:31], v[164:167], v[188:191], v[28:31]
	v_mfma_f32_16x16x32_bf16 v[24:27], v[172:175], v[188:191], v[24:27]
	v_mfma_f32_16x16x32_bf16 v[12:15], v[164:167], v[196:199], v[12:15]
	v_mfma_f32_16x16x32_bf16 v[8:11], v[172:175], v[196:199], v[8:11]
	v_mfma_f32_16x16x32_bf16 v[4:7], v[164:167], v[204:207], v[4:7]
	v_mfma_f32_16x16x32_bf16 v[0:3], v[172:175], v[204:207], v[0:3]
	v_mfma_f32_16x16x32_bf16 v[44:47], v[168:171], v[184:187], v[44:47]
	v_mfma_f32_16x16x32_bf16 v[40:43], v[176:179], v[184:187], v[40:43]
	v_mfma_f32_16x16x32_bf16 v[28:31], v[168:171], v[192:195], v[28:31]
	v_mfma_f32_16x16x32_bf16 v[24:27], v[176:179], v[192:195], v[24:27]
	v_mfma_f32_16x16x32_bf16 v[12:15], v[168:171], v[200:203], v[12:15]
	v_mfma_f32_16x16x32_bf16 v[8:11], v[176:179], v[200:203], v[8:11]
	v_mfma_f32_16x16x32_bf16 v[4:7], v[168:171], v[208:211], v[4:7]
	v_mfma_f32_16x16x32_bf16 v[0:3], v[176:179], v[208:211], v[0:3]
	s_barrier
	s_add_i32 s55, s55, 2
	s_add_u32 s22, s22, 0x100
	s_addc_u32 s23, s23, 0
	s_add_u32 s51, s51, 0x100
	s_addc_u32 s54, s54, 0
; #define PG8_STAGE(bufoff, gbase, voff) do { _Pragma("unroll") for (int _i = 0; _i < 2; ++_i) \
;         __builtin_amdgcn_global_load_lds((const unsigned*)((const char*)(gbase) + (voff)[_i]), (LAS unsigned*)(lds + (bufoff) + ldsw + _i * 8192), 16, 0, 0); } while (0)
; #define PG8_LDA(dst, b, h) do { _Pragma("unroll") for (int m = 0; m < 4; ++m) _Pragma("unroll") for (int k = 0; k < 2; ++k) dst[m][k] = *(const LAS bf16x8*)(lds + PG8_SA(b, h) + aoff + m * 2048 + k * 1024); } while (0)
; #define PG8_LDB(dst, b, h) do { _Pragma("unroll") for (int n = 0; n < 2; ++n) _Pragma("unroll") for (int k = 0; k < 2; ++k) dst[n][k] = *(const LAS bf16x8*)(lds + PG8_SB(b, h) + boff + n * 2048 + k * 1024); } while (0)
; #define PG8_MMA(ai, bj, At, Bt) do { __builtin_amdgcn_s_setprio(1); _Pragma("unroll") for (int m = 0; m < 4; ++m) _Pragma("unroll") for (int n = 0; n < 2; ++n) _Pragma("unroll") for (int k = 0; k < 2; ++k) \
;         acc[ai][bj][m][n] = __builtin_amdgcn_mfma_f32_16x16x32_bf16(Bt[n][k], At[m][k], acc[ai][bj][m][n], 0, 0, 0); __builtin_amdgcn_s_setprio(0); } while (0)
; #define PG8_WAIT_V(n) asm volatile("s_waitcnt vmcnt(" #n ")" ::: "memory")
; #define PG8_WAIT_L(n) asm volatile("s_waitcnt lgkmcnt(" #n ")" ::: "memory")
; #define PG8_BAR __builtin_amdgcn_s_barrier()
; template <class Epi, bool ALIGN_EPI, int K, int LDA, int LDB>
; __device__ __forceinline__ void gemm_phase(LAS unsigned char* lds, const int wid, const Gemm g, const StaticOrder& S, const Epi& E) {
;     ...
;         for (int t = 0; t < nt; t += 2) {
;             const bool last = (t == nt - 2);
;             const char* a1 = cA + (size_t)(t + 1) * kstep;
;             const char* a2 = last ? nA : cA + (size_t)(t + 2) * kstep; const char* b2 = last ? nB : cB + (size_t)(t + 2) * kstep;
;             const char* a3 = a2 + kstep; const char* b3 = b2 + kstep;
;             PG8_LDB(B0, 0, 0); PG8_LDB(B1, 0, 1); PG8_SCHED; PG8_LDA(At, 0, 0); PG8_STAGE(PG8_SA(1, 1), a1 + hA, voffA);
;             PG8_WAIT_V(8); PG8_WAIT_L(0); PG8_BAR; PG8_MMA(0, 0, At, B0); PG8_MMA(0, 1, At, B1); PG8_BAR; PG8_SCHED;
;             PG8_LDA(At, 0, 1); PG8_STAGE(PG8_SB(0, 0), b2, voffB); PG8_STAGE(PG8_SB(0, 1), b2 + hB, voffB); PG8_STAGE(PG8_SA(0, 0), a2, voffA);
;             PG8_WAIT_V(8); PG8_WAIT_L(0); PG8_BAR; PG8_MMA(1, 0, At, B0); PG8_MMA(1, 1, At, B1); PG8_BAR; PG8_SCHED;
.LBB0_232:
	ds_read_b128 v[148:151], v145
	ds_read_b128 v[152:155], v145 offset:1024
	ds_read_b128 v[156:159], v145 offset:2048
	ds_read_b128 v[160:163], v145 offset:3072
	ds_read_b128 v[164:167], v146
	ds_read_b128 v[168:171], v146 offset:1024
	ds_read_b128 v[172:175], v146 offset:2048
	ds_read_b128 v[176:179], v146 offset:3072
	s_add_u32 s24, s22, 0xfffc0080
	s_addc_u32 s25, s23, -1
	s_cmp_eq_u32 s55, 12
	s_cselect_b32 s27, s17, s25
	s_cselect_b32 s26, s48, s24
	s_cselect_b32 s25, s15, s54
	s_cselect_b32 s24, s49, s51
	s_add_i32 m0, s13, 0xc000
	ds_read_b128 v[180:183], v147
	ds_read_b128 v[184:187], v147 offset:1024
	ds_read_b128 v[188:191], v147 offset:2048
	ds_read_b128 v[192:195], v147 offset:3072
	ds_read_b128 v[196:199], v147 offset:4096
	ds_read_b128 v[200:203], v147 offset:5120
	ds_read_b128 v[204:207], v147 offset:6144
	ds_read_b128 v[208:211], v147 offset:7168
	global_load_lds_dwordx4 v136, s[22:23]
	s_add_i32 m0, s13, 0xe000
	s_nop 0
	global_load_lds_dwordx4 v138, s[22:23]
	s_waitcnt vmcnt(8)
	s_barrier
	s_waitcnt lgkmcnt(0)
	v_mfma_f32_16x16x32_bf16 v[124:127], v[148:151], v[180:183], v[124:127]
	v_mfma_f32_16x16x32_bf16 v[120:123], v[156:159], v[180:183], v[120:123]
	v_mfma_f32_16x16x32_bf16 v[116:119], v[148:151], v[188:191], v[116:119]
	v_mfma_f32_16x16x32_bf16 v[112:115], v[156:159], v[188:191], v[112:115]
	v_mfma_f32_16x16x32_bf16 v[100:103], v[148:151], v[196:199], v[100:103]
	v_mfma_f32_16x16x32_bf16 v[96:99], v[156:159], v[196:199], v[96:99]
	v_mfma_f32_16x16x32_bf16 v[84:87], v[148:151], v[204:207], v[84:87]
	v_mfma_f32_16x16x32_bf16 v[80:83], v[156:159], v[204:207], v[80:83]
	v_mfma_f32_16x16x32_bf16 v[124:127], v[152:155], v[184:187], v[124:127]
	v_mfma_f32_16x16x32_bf16 v[120:123], v[160:163], v[184:187], v[120:123]
	v_mfma_f32_16x16x32_bf16 v[116:119], v[152:155], v[192:195], v[116:119]
	v_mfma_f32_16x16x32_bf16 v[112:115], v[160:163], v[192:195], v[112:115]
	v_mfma_f32_16x16x32_bf16 v[100:103], v[152:155], v[200:203], v[100:103]
	v_mfma_f32_16x16x32_bf16 v[96:99], v[160:163], v[200:203], v[96:99]
	v_mfma_f32_16x16x32_bf16 v[84:87], v[152:155], v[208:211], v[84:87]
	v_mfma_f32_16x16x32_bf16 v[80:83], v[160:163], v[208:211], v[80:83]
	v_mfma_f32_16x16x32_bf16 v[108:111], v[164:167], v[180:183], v[108:111]
	v_mfma_f32_16x16x32_bf16 v[104:107], v[172:175], v[180:183], v[104:107]
	v_mfma_f32_16x16x32_bf16 v[92:95], v[164:167], v[188:191], v[92:95]
	v_mfma_f32_16x16x32_bf16 v[88:91], v[172:175], v[188:191], v[88:91]
	v_mfma_f32_16x16x32_bf16 v[76:79], v[164:167], v[196:199], v[76:79]
	v_mfma_f32_16x16x32_bf16 v[72:75], v[172:175], v[196:199], v[72:75]
	v_mfma_f32_16x16x32_bf16 v[68:71], v[164:167], v[204:207], v[68:71]
	v_mfma_f32_16x16x32_bf16 v[64:67], v[172:175], v[204:207], v[64:67]
	v_mfma_f32_16x16x32_bf16 v[108:111], v[168:171], v[184:187], v[108:111]
	v_mfma_f32_16x16x32_bf16 v[104:107], v[176:179], v[184:187], v[104:107]
	v_mfma_f32_16x16x32_bf16 v[92:95], v[168:171], v[192:195], v[92:95]
	v_mfma_f32_16x16x32_bf16 v[88:91], v[176:179], v[192:195], v[88:91]
	v_mfma_f32_16x16x32_bf16 v[76:79], v[168:171], v[200:203], v[76:79]
	v_mfma_f32_16x16x32_bf16 v[72:75], v[176:179], v[200:203], v[72:75]
	v_mfma_f32_16x16x32_bf16 v[68:71], v[168:171], v[208:211], v[68:71]
	v_mfma_f32_16x16x32_bf16 v[64:67], v[176:179], v[208:211], v[64:67]
	s_barrier
	s_add_u32 s98, s24, s10
	s_addc_u32 s99, s25, s11
	s_add_u32 s100, s26, s10
	s_addc_u32 s101, s27, s11
	s_add_i32 s56, s40, s3
	s_mov_b32 m0, s56
	ds_read_b128 v[180:183], v147 offset:16384
	ds_read_b128 v[184:187], v147 offset:17408
	ds_read_b128 v[188:191], v147 offset:18432
	ds_read_b128 v[192:195], v147 offset:19456
	ds_read_b128 v[196:199], v147 offset:20480
	ds_read_b128 v[200:203], v147 offset:21504
	ds_read_b128 v[204:207], v147 offset:22528
	ds_read_b128 v[208:211], v147 offset:23552
	global_load_lds_dwordx4 v132, s[24:25]
	s_add_i32 m0, s56, 0x2000
	s_add_u32 s56, s24, 0x40000
	s_addc_u32 s57, s25, 0
	s_add_i32 s58, s41, s3
	global_load_lds_dwordx4 v128, s[24:25]
	s_mov_b32 m0, s58
	s_nop 0
	global_load_lds_dwordx4 v132, s[56:57]
	s_add_i32 m0, s58, 0x2000
	s_nop 0
	global_load_lds_dwordx4 v128, s[56:57]
	s_mov_b32 m0, s13
	s_nop 0
	global_load_lds_dwordx4 v134, s[26:27]
	s_mov_b32 m0, s30
	s_nop 0
	global_load_lds_dwordx4 v130, s[26:27]
	s_waitcnt vmcnt(8)
	s_barrier
	s_waitcnt lgkmcnt(0)
	v_mfma_f32_16x16x32_bf16 v[60:63], v[148:151], v[180:183], v[60:63]
	v_mfma_f32_16x16x32_bf16 v[56:59], v[156:159], v[180:183], v[56:59]
	v_mfma_f32_16x16x32_bf16 v[52:55], v[148:151], v[188:191], v[52:55]
	v_mfma_f32_16x16x32_bf16 v[48:51], v[156:159], v[188:191], v[48:51]
	v_mfma_f32_16x16x32_bf16 v[36:39], v[148:151], v[196:199], v[36:39]
	v_mfma_f32_16x16x32_bf16 v[32:35], v[156:159], v[196:199], v[32:35]
	v_mfma_f32_16x16x32_bf16 v[20:23], v[148:151], v[204:207], v[20:23]
	v_mfma_f32_16x16x32_bf16 v[16:19], v[156:159], v[204:207], v[16:19]
	v_mfma_f32_16x16x32_bf16 v[60:63], v[152:155], v[184:187], v[60:63]
	v_mfma_f32_16x16x32_bf16 v[56:59], v[160:163], v[184:187], v[56:59]
	v_mfma_f32_16x16x32_bf16 v[52:55], v[152:155], v[192:195], v[52:55]
	v_mfma_f32_16x16x32_bf16 v[48:51], v[160:163], v[192:195], v[48:51]
	v_mfma_f32_16x16x32_bf16 v[36:39], v[152:155], v[200:203], v[36:39]
	v_mfma_f32_16x16x32_bf16 v[32:35], v[160:163], v[200:203], v[32:35]
	v_mfma_f32_16x16x32_bf16 v[20:23], v[152:155], v[208:211], v[20:23]
	v_mfma_f32_16x16x32_bf16 v[16:19], v[160:163], v[208:211], v[16:19]
	v_mfma_f32_16x16x32_bf16 v[44:47], v[164:167], v[180:183], v[44:47]
	v_mfma_f32_16x16x32_bf16 v[40:43], v[172:175], v[180:183], v[40:43]
	v_mfma_f32_16x16x32_bf16 v[28:31], v[164:167], v[188:191], v[28:31]
	v_mfma_f32_16x16x32_bf16 v[24:27], v[172:175], v[188:191], v[24:27]
	v_mfma_f32_16x16x32_bf16 v[12:15], v[164:167], v[196:199], v[12:15]
	v_mfma_f32_16x16x32_bf16 v[8:11], v[172:175], v[196:199], v[8:11]
	v_mfma_f32_16x16x32_bf16 v[4:7], v[164:167], v[204:207], v[4:7]
	v_mfma_f32_16x16x32_bf16 v[0:3], v[172:175], v[204:207], v[0:3]
	v_mfma_f32_16x16x32_bf16 v[44:47], v[168:171], v[184:187], v[44:47]
	v_mfma_f32_16x16x32_bf16 v[40:43], v[176:179], v[184:187], v[40:43]
	v_mfma_f32_16x16x32_bf16 v[28:31], v[168:171], v[192:195], v[28:31]
	v_mfma_f32_16x16x32_bf16 v[24:27], v[176:179], v[192:195], v[24:27]
	v_mfma_f32_16x16x32_bf16 v[12:15], v[168:171], v[200:203], v[12:15]
	v_mfma_f32_16x16x32_bf16 v[8:11], v[176:179], v[200:203], v[8:11]
	v_mfma_f32_16x16x32_bf16 v[4:7], v[168:171], v[208:211], v[4:7]
	v_mfma_f32_16x16x32_bf16 v[0:3], v[176:179], v[208:211], v[0:3]
	s_barrier
; #define PG8_STAGE(bufoff, gbase, voff) do { _Pragma("unroll") for (int _i = 0; _i < 2; ++_i) \
;         __builtin_amdgcn_global_load_lds((const unsigned*)((const char*)(gbase) + (voff)[_i]), (LAS unsigned*)(lds + (bufoff) + ldsw + _i * 8192), 16, 0, 0); } while (0)
; #define PG8_LDA(dst, b, h) do { _Pragma("unroll") for (int m = 0; m < 4; ++m) _Pragma("unroll") for (int k = 0; k < 2; ++k) dst[m][k] = *(const LAS bf16x8*)(lds + PG8_SA(b, h) + aoff + m * 2048 + k * 1024); } while (0)
; #define PG8_LDB(dst, b, h) do { _Pragma("unroll") for (int n = 0; n < 2; ++n) _Pragma("unroll") for (int k = 0; k < 2; ++k) dst[n][k] = *(const LAS bf16x8*)(lds + PG8_SB(b, h) + boff + n * 2048 + k * 1024); } while (0)
; #define PG8_MMA(ai, bj, At, Bt) do { __builtin_amdgcn_s_setprio(1); _Pragma("unroll") for (int m = 0; m < 4; ++m) _Pragma("unroll") for (int n = 0; n < 2; ++n) _Pragma("unroll") for (int k = 0; k < 2; ++k) \
;         acc[ai][bj][m][n] = __builtin_amdgcn_mfma_f32_16x16x32_bf16(Bt[n][k], At[m][k], acc[ai][bj][m][n], 0, 0, 0); __builtin_amdgcn_s_setprio(0); } while (0)
; #define PG8_WAIT_V(n) asm volatile("s_waitcnt vmcnt(" #n ")" ::: "memory")
; #define PG8_WAIT_L(n) asm volatile("s_waitcnt lgkmcnt(" #n ")" ::: "memory")
; #define PG8_BAR __builtin_amdgcn_s_barrier()
; #define PG8_SCHED __builtin_amdgcn_sched_barrier(0)
; template <class Epi, bool ALIGN_EPI, int K, int LDA, int LDB>
; __device__ __forceinline__ void gemm_phase(LAS unsigned char* lds, const int wid, const Gemm g, const StaticOrder& S, const Epi& E) {
;     ...
;             PG8_LDB(B0, 1, 0); PG8_LDB(B1, 1, 1); PG8_SCHED; PG8_LDA(At, 1, 0); PG8_STAGE(PG8_SA(0, 1), a2 + hA, voffA);
;             PG8_WAIT_V(8); PG8_WAIT_L(0); PG8_BAR; PG8_MMA(0, 0, At, B0); PG8_MMA(0, 1, At, B1); PG8_BAR; PG8_SCHED;
;             PG8_LDA(At, 1, 1); PG8_STAGE(PG8_SB(1, 0), b3, voffB); PG8_STAGE(PG8_SB(1, 1), b3 + hB, voffB); PG8_STAGE(PG8_SA(1, 0), a3, voffA);
;             PG8_WAIT_V(8); PG8_WAIT_L(0); PG8_BAR; PG8_MMA(1, 0, At, B0); PG8_MMA(1, 1, At, B1); PG8_BAR; PG8_SCHED;
;         }
;         if constexpr (ALIGN_EPI) { if (wr == 0) PG8_BAR; }
	s_add_i32 s56, 0, 0x18000
	s_add_i32 s57, 0, 0x1c000
	v_add_u32_e32 v160, s56, v144
	v_add_u32_e32 v176, s57, v144
	ds_read_b128 v[148:151], v160
	ds_read_b128 v[152:155], v160 offset:1024
	ds_read_b128 v[156:159], v160 offset:2048
	ds_read_b128 v[160:163], v160 offset:3072
	ds_read_b128 v[164:167], v176
	ds_read_b128 v[168:171], v176 offset:1024
	ds_read_b128 v[172:175], v176 offset:2048
	ds_read_b128 v[176:179], v176 offset:3072
	s_add_u32 s26, s26, 0x40000
	s_addc_u32 s27, s27, 0
	s_mov_b32 m0, s31
	ds_read_b128 v[180:183], v147 offset:32768
	ds_read_b128 v[184:187], v147 offset:33792
	ds_read_b128 v[188:191], v147 offset:34816
	ds_read_b128 v[192:195], v147 offset:35840
	ds_read_b128 v[196:199], v147 offset:36864
	ds_read_b128 v[200:203], v147 offset:37888
	ds_read_b128 v[204:207], v147 offset:38912
	ds_read_b128 v[208:211], v147 offset:39936
	global_load_lds_dwordx4 v134, s[26:27]
	s_mov_b32 m0, s33
	s_nop 0
	global_load_lds_dwordx4 v130, s[26:27]
	s_waitcnt vmcnt(8)
	s_barrier
	s_waitcnt lgkmcnt(0)
	v_mfma_f32_16x16x32_bf16 v[124:127], v[148:151], v[180:183], v[124:127]
	v_mfma_f32_16x16x32_bf16 v[120:123], v[156:159], v[180:183], v[120:123]
	v_mfma_f32_16x16x32_bf16 v[116:119], v[148:151], v[188:191], v[116:119]
	v_mfma_f32_16x16x32_bf16 v[112:115], v[156:159], v[188:191], v[112:115]
	v_mfma_f32_16x16x32_bf16 v[100:103], v[148:151], v[196:199], v[100:103]
	v_mfma_f32_16x16x32_bf16 v[96:99], v[156:159], v[196:199], v[96:99]
	v_mfma_f32_16x16x32_bf16 v[84:87], v[148:151], v[204:207], v[84:87]
	v_mfma_f32_16x16x32_bf16 v[80:83], v[156:159], v[204:207], v[80:83]
	v_mfma_f32_16x16x32_bf16 v[124:127], v[152:155], v[184:187], v[124:127]
	v_mfma_f32_16x16x32_bf16 v[120:123], v[160:163], v[184:187], v[120:123]
	v_mfma_f32_16x16x32_bf16 v[116:119], v[152:155], v[192:195], v[116:119]
	v_mfma_f32_16x16x32_bf16 v[112:115], v[160:163], v[192:195], v[112:115]
	v_mfma_f32_16x16x32_bf16 v[100:103], v[152:155], v[200:203], v[100:103]
	v_mfma_f32_16x16x32_bf16 v[96:99], v[160:163], v[200:203], v[96:99]
	v_mfma_f32_16x16x32_bf16 v[84:87], v[152:155], v[208:211], v[84:87]
	v_mfma_f32_16x16x32_bf16 v[80:83], v[160:163], v[208:211], v[80:83]
	v_mfma_f32_16x16x32_bf16 v[108:111], v[164:167], v[180:183], v[108:111]
	v_mfma_f32_16x16x32_bf16 v[104:107], v[172:175], v[180:183], v[104:107]
	v_mfma_f32_16x16x32_bf16 v[92:95], v[164:167], v[188:191], v[92:95]
	v_mfma_f32_16x16x32_bf16 v[88:91], v[172:175], v[188:191], v[88:91]
	v_mfma_f32_16x16x32_bf16 v[76:79], v[164:167], v[196:199], v[76:79]
	v_mfma_f32_16x16x32_bf16 v[72:75], v[172:175], v[196:199], v[72:75]
	v_mfma_f32_16x16x32_bf16 v[68:71], v[164:167], v[204:207], v[68:71]
	v_mfma_f32_16x16x32_bf16 v[64:67], v[172:175], v[204:207], v[64:67]
	v_mfma_f32_16x16x32_bf16 v[108:111], v[168:171], v[184:187], v[108:111]
	v_mfma_f32_16x16x32_bf16 v[104:107], v[176:179], v[184:187], v[104:107]
	v_mfma_f32_16x16x32_bf16 v[92:95], v[168:171], v[192:195], v[92:95]
	v_mfma_f32_16x16x32_bf16 v[88:91], v[176:179], v[192:195], v[88:91]
	v_mfma_f32_16x16x32_bf16 v[76:79], v[168:171], v[200:203], v[76:79]
	v_mfma_f32_16x16x32_bf16 v[72:75], v[176:179], v[200:203], v[72:75]
	v_mfma_f32_16x16x32_bf16 v[68:71], v[168:171], v[208:211], v[68:71]
	v_mfma_f32_16x16x32_bf16 v[64:67], v[176:179], v[208:211], v[64:67]
	s_barrier
	s_add_i32 s26, s56, s3
	s_mov_b32 m0, s26
	ds_read_b128 v[180:183], v147 offset:49152
	ds_read_b128 v[184:187], v147 offset:50176
	ds_read_b128 v[188:191], v147 offset:51200
	ds_read_b128 v[192:195], v147 offset:52224
	ds_read_b128 v[196:199], v147 offset:53248
	ds_read_b128 v[200:203], v147 offset:54272
	ds_read_b128 v[204:207], v147 offset:55296
	ds_read_b128 v[208:211], v147 offset:56320
	global_load_lds_dwordx4 v132, s[98:99]
	s_add_i32 m0, s26, 0x2000
	s_add_u32 s24, s24, 0x40080
	s_addc_u32 s25, s25, 0
	s_add_i32 s26, s57, s3
	global_load_lds_dwordx4 v128, s[98:99]
	s_mov_b32 m0, s26
	s_nop 0
	global_load_lds_dwordx4 v132, s[24:25]
	s_add_i32 m0, s26, 0x2000
	s_nop 0
	global_load_lds_dwordx4 v128, s[24:25]
	s_mov_b32 m0, s38
	s_nop 0
	global_load_lds_dwordx4 v134, s[100:101]
	s_mov_b32 m0, s39
	s_nop 0
	global_load_lds_dwordx4 v130, s[100:101]
	s_waitcnt vmcnt(8)
	s_barrier
	s_waitcnt lgkmcnt(0)
	v_mfma_f32_16x16x32_bf16 v[60:63], v[148:151], v[180:183], v[60:63]
	v_mfma_f32_16x16x32_bf16 v[56:59], v[156:159], v[180:183], v[56:59]
	v_mfma_f32_16x16x32_bf16 v[52:55], v[148:151], v[188:191], v[52:55]
	v_mfma_f32_16x16x32_bf16 v[48:51], v[156:159], v[188:191], v[48:51]
	v_mfma_f32_16x16x32_bf16 v[36:39], v[148:151], v[196:199], v[36:39]
	v_mfma_f32_16x16x32_bf16 v[32:35], v[156:159], v[196:199], v[32:35]
	v_mfma_f32_16x16x32_bf16 v[20:23], v[148:151], v[204:207], v[20:23]
	v_mfma_f32_16x16x32_bf16 v[16:19], v[156:159], v[204:207], v[16:19]
	v_mfma_f32_16x16x32_bf16 v[60:63], v[152:155], v[184:187], v[60:63]
	v_mfma_f32_16x16x32_bf16 v[56:59], v[160:163], v[184:187], v[56:59]
	v_mfma_f32_16x16x32_bf16 v[52:55], v[152:155], v[192:195], v[52:55]
	v_mfma_f32_16x16x32_bf16 v[48:51], v[160:163], v[192:195], v[48:51]
	v_mfma_f32_16x16x32_bf16 v[36:39], v[152:155], v[200:203], v[36:39]
	v_mfma_f32_16x16x32_bf16 v[32:35], v[160:163], v[200:203], v[32:35]
	v_mfma_f32_16x16x32_bf16 v[20:23], v[152:155], v[208:211], v[20:23]
	v_mfma_f32_16x16x32_bf16 v[16:19], v[160:163], v[208:211], v[16:19]
	v_mfma_f32_16x16x32_bf16 v[44:47], v[164:167], v[180:183], v[44:47]
	v_mfma_f32_16x16x32_bf16 v[40:43], v[172:175], v[180:183], v[40:43]
	v_mfma_f32_16x16x32_bf16 v[28:31], v[164:167], v[188:191], v[28:31]
	v_mfma_f32_16x16x32_bf16 v[24:27], v[172:175], v[188:191], v[24:27]
	v_mfma_f32_16x16x32_bf16 v[12:15], v[164:167], v[196:199], v[12:15]
	v_mfma_f32_16x16x32_bf16 v[8:11], v[172:175], v[196:199], v[8:11]
	v_mfma_f32_16x16x32_bf16 v[4:7], v[164:167], v[204:207], v[4:7]
	v_mfma_f32_16x16x32_bf16 v[0:3], v[172:175], v[204:207], v[0:3]
	v_mfma_f32_16x16x32_bf16 v[44:47], v[168:171], v[184:187], v[44:47]
	v_mfma_f32_16x16x32_bf16 v[40:43], v[176:179], v[184:187], v[40:43]
	v_mfma_f32_16x16x32_bf16 v[28:31], v[168:171], v[192:195], v[28:31]
	v_mfma_f32_16x16x32_bf16 v[24:27], v[176:179], v[192:195], v[24:27]
	v_mfma_f32_16x16x32_bf16 v[12:15], v[168:171], v[200:203], v[12:15]
	v_mfma_f32_16x16x32_bf16 v[8:11], v[176:179], v[200:203], v[8:11]
	v_mfma_f32_16x16x32_bf16 v[4:7], v[168:171], v[208:211], v[4:7]
	v_mfma_f32_16x16x32_bf16 v[0:3], v[176:179], v[208:211], v[0:3]
	s_barrier
	s_add_i32 s55, s55, 2
	s_add_u32 s22, s22, 0x100
	s_addc_u32 s23, s23, 0
	s_add_u32 s51, s51, 0x100
	s_addc_u32 s54, s54, 0
	s_cmp_gt_u32 s55, 13
	s_cbranch_scc0 .LBB0_232
	s_and_b64 vcc, exec, s[8:9]
	s_cbranch_vccz .LBB0_235
	s_barrier

; #define PG8_STAGE(bufoff, gbase, voff) do { _Pragma("unroll") for (int _i = 0; _i < 2; ++_i) \
;         __builtin_amdgcn_global_load_lds((const unsigned*)((const char*)(gbase) + (voff)[_i]), (LAS unsigned*)(lds + (bufoff) + ldsw + _i * 8192), 16, 0, 0); } while (0)
; #define PG8_LDA(dst, b, h) do { _Pragma("unroll") for (int m = 0; m < 4; ++m) _Pragma("unroll") for (int k = 0; k < 2; ++k) dst[m][k] = *(const LAS bf16x8*)(lds + PG8_SA(b, h) + aoff + m * 2048 + k * 1024); } while (0)
; #define PG8_LDB(dst, b, h) do { _Pragma("unroll") for (int n = 0; n < 2; ++n) _Pragma("unroll") for (int k = 0; k < 2; ++k) dst[n][k] = *(const LAS bf16x8*)(lds + PG8_SB(b, h) + boff + n * 2048 + k * 1024); } while (0)
; #define PG8_MMA(ai, bj, At, Bt) do { __builtin_amdgcn_s_setprio(1); _Pragma("unroll") for (int m = 0; m < 4; ++m) _Pragma("unroll") for (int n = 0; n < 2; ++n) _Pragma("unroll") for (int k = 0; k < 2; ++k) \
;         acc[ai][bj][m][n] = __builtin_amdgcn_mfma_f32_16x16x32_bf16(Bt[n][k], At[m][k], acc[ai][bj][m][n], 0, 0, 0); __builtin_amdgcn_s_setprio(0); } while (0)
; template <class Epi, bool ALIGN_EPI, int K, int LDA, int LDB>
; __device__ __forceinline__ void gemm_phase(LAS unsigned char* lds, const int wid, const Gemm g, const StaticOrder& S, const Epi& E) {
;     ...
;         const bool has_next = S.next(ui + 1, nxt);
;         const char* nA = has_next ? (const char*)g.A + (size_t)nxt.pm * tA : cA; const char* nB = has_next ? (const char*)g.Bt + (size_t)nxt.pn * tB : cB;
;         for (int t = 0; t < nt; t += 2) {
;             const bool last = (t == nt - 2);
;             const char* a1 = cA + (size_t)(t + 1) * kstep;
;             const char* a2 = last ? nA : cA + (size_t)(t + 2) * kstep; const char* b2 = last ? nB : cB + (size_t)(t + 2) * kstep;
;             const char* a3 = a2 + kstep; const char* b3 = b2 + kstep;
;             PG8_LDB(B0, 0, 0); PG8_LDB(B1, 0, 1); PG8_SCHED; PG8_LDA(At, 0, 0); PG8_STAGE(PG8_SA(1, 1), a1 + hA, voffA);
;             PG8_WAIT_V(8); PG8_WAIT_L(0); PG8_BAR; PG8_MMA(0, 0, At, B0); PG8_MMA(0, 1, At, B1); PG8_BAR; PG8_SCHED;
;             PG8_LDA(At, 0, 1); PG8_STAGE(PG8_SB(0, 0), b2, voffB); PG8_STAGE(PG8_SB(0, 1), b2 + hB, voffB); PG8_STAGE(PG8_SA(0, 0), a2, voffA);
;             PG8_WAIT_V(8); PG8_WAIT_L(0); PG8_BAR; PG8_MMA(1, 0, At, B0); PG8_MMA(1, 1, At, B1); PG8_BAR; PG8_SCHED;
.LBB0_916:
	s_ashr_i32 s27, s26, 31
	s_lshl_b64 s[28:29], s[26:27], 19
	v_readlane_b32 s25, v254, 0
	s_add_u32 s28, s25, s28
	v_readlane_b32 s25, v254, 1
	s_addc_u32 s29, s25, s29
	s_and_b64 s[30:31], s[4:5], exec
	s_cselect_b32 s27, s29, s37
	s_cselect_b32 s63, s28, s36
	s_ashr_i32 s25, s24, 31
	s_lshl_b64 s[30:31], s[24:25], 19
	s_add_u32 s30, s1, s30
	s_addc_u32 s31, s3, s31
	s_and_b64 s[40:41], s[4:5], exec
	s_cselect_b32 s25, s31, s39
	s_cselect_b32 s64, s30, s38
	s_add_u32 s36, s36, 0x40080
	s_addc_u32 s37, s37, 0
	s_add_u32 s65, s38, 0x100
	s_addc_u32 s66, s39, 0
	s_mov_b32 s67, -2
	s_add_u32 s38, s36, 0xfffc0080
	s_addc_u32 s39, s37, -1
	s_cmp_eq_u32 s67, 12
	s_cselect_b32 s41, s27, s39
	s_cselect_b32 s40, s63, s38
	s_cselect_b32 s39, s25, s66
	s_cselect_b32 s38, s64, s65
	s_add_i32 m0, s35, 0xc000
	global_load_lds_dwordx4 v152, s[36:37]
	s_add_i32 m0, s35, 0xe000
	s_nop 0
	global_load_lds_dwordx4 v154, s[36:37]
	s_waitcnt vmcnt(8)
	s_barrier
	s_waitcnt lgkmcnt(0)
	v_mfma_f32_16x16x32_bf16 v[124:127], v[128:131], v[182:185], 0
	v_mfma_f32_16x16x32_bf16 v[120:123], v[136:139], v[182:185], 0
	v_mfma_f32_16x16x32_bf16 v[108:111], v[128:131], v[190:193], 0
	v_mfma_f32_16x16x32_bf16 v[104:107], v[136:139], v[190:193], 0
	v_mfma_f32_16x16x32_bf16 v[92:95], v[128:131], v[198:201], 0
	v_mfma_f32_16x16x32_bf16 v[88:91], v[136:139], v[198:201], 0
	v_mfma_f32_16x16x32_bf16 v[76:79], v[128:131], v[206:209], 0
	v_mfma_f32_16x16x32_bf16 v[72:75], v[136:139], v[206:209], 0
	v_mfma_f32_16x16x32_bf16 v[124:127], v[132:135], v[186:189], v[124:127]
	v_mfma_f32_16x16x32_bf16 v[120:123], v[140:143], v[186:189], v[120:123]
	v_mfma_f32_16x16x32_bf16 v[108:111], v[132:135], v[194:197], v[108:111]
	v_mfma_f32_16x16x32_bf16 v[104:107], v[140:143], v[194:197], v[104:107]
	v_mfma_f32_16x16x32_bf16 v[92:95], v[132:135], v[202:205], v[92:95]
	v_mfma_f32_16x16x32_bf16 v[88:91], v[140:143], v[202:205], v[88:91]
	v_mfma_f32_16x16x32_bf16 v[76:79], v[132:135], v[210:213], v[76:79]
	v_mfma_f32_16x16x32_bf16 v[72:75], v[140:143], v[210:213], v[72:75]
	v_mfma_f32_16x16x32_bf16 v[116:119], v[166:169], v[182:185], 0
	v_mfma_f32_16x16x32_bf16 v[112:115], v[174:177], v[182:185], 0
	v_mfma_f32_16x16x32_bf16 v[100:103], v[166:169], v[190:193], 0
	v_mfma_f32_16x16x32_bf16 v[96:99], v[174:177], v[190:193], 0
	v_mfma_f32_16x16x32_bf16 v[84:87], v[166:169], v[198:201], 0
	v_mfma_f32_16x16x32_bf16 v[80:83], v[174:177], v[198:201], 0
	v_mfma_f32_16x16x32_bf16 v[68:71], v[166:169], v[206:209], 0
	v_mfma_f32_16x16x32_bf16 v[64:67], v[174:177], v[206:209], 0
	v_mfma_f32_16x16x32_bf16 v[116:119], v[170:173], v[186:189], v[116:119]
	v_mfma_f32_16x16x32_bf16 v[112:115], v[178:181], v[186:189], v[112:115]
	v_mfma_f32_16x16x32_bf16 v[100:103], v[170:173], v[194:197], v[100:103]
	v_mfma_f32_16x16x32_bf16 v[96:99], v[178:181], v[194:197], v[96:99]
	v_mfma_f32_16x16x32_bf16 v[84:87], v[170:173], v[202:205], v[84:87]
	v_mfma_f32_16x16x32_bf16 v[80:83], v[178:181], v[202:205], v[80:83]
	v_mfma_f32_16x16x32_bf16 v[68:71], v[170:173], v[210:213], v[68:71]
	v_mfma_f32_16x16x32_bf16 v[64:67], v[178:181], v[210:213], v[64:67]
	s_barrier
	s_add_u32 s98, s38, s12
	s_addc_u32 s99, s39, s13
	s_add_u32 s100, s40, s12
	s_addc_u32 s101, s41, s13
	s_add_i32 s52, s58, s33
	s_mov_b32 m0, s52
	ds_read_b128 v[182:185], v165 offset:16384
	ds_read_b128 v[186:189], v165 offset:17408
	ds_read_b128 v[190:193], v165 offset:18432
	ds_read_b128 v[194:197], v165 offset:19456
	ds_read_b128 v[198:201], v165 offset:20480
	ds_read_b128 v[202:205], v165 offset:21504
	ds_read_b128 v[206:209], v165 offset:22528
	ds_read_b128 v[210:213], v165 offset:23552
	global_load_lds_dwordx4 v146, s[38:39]
	s_add_i32 m0, s52, 0x2000
	s_add_u32 s68, s38, 0x40000
	s_addc_u32 s69, s39, 0
	s_add_i32 s52, s59, s33
	global_load_lds_dwordx4 v150, s[38:39]
	s_mov_b32 m0, s52
	s_nop 0
	global_load_lds_dwordx4 v146, s[68:69]
	s_add_i32 m0, s52, 0x2000
	s_nop 0
	global_load_lds_dwordx4 v150, s[68:69]
	s_mov_b32 m0, s35
	s_nop 0
	global_load_lds_dwordx4 v144, s[40:41]
	s_mov_b32 m0, s42
	s_nop 0
	global_load_lds_dwordx4 v148, s[40:41]
	s_waitcnt vmcnt(8)
	s_barrier
	s_waitcnt lgkmcnt(0)
	v_mfma_f32_16x16x32_bf16 v[60:63], v[128:131], v[182:185], 0
	v_mfma_f32_16x16x32_bf16 v[56:59], v[136:139], v[182:185], 0
	v_mfma_f32_16x16x32_bf16 v[44:47], v[128:131], v[190:193], 0
	v_mfma_f32_16x16x32_bf16 v[40:43], v[136:139], v[190:193], 0
	v_mfma_f32_16x16x32_bf16 v[28:31], v[128:131], v[198:201], 0
	v_mfma_f32_16x16x32_bf16 v[24:27], v[136:139], v[198:201], 0
	v_mfma_f32_16x16x32_bf16 v[12:15], v[128:131], v[206:209], 0
	v_mfma_f32_16x16x32_bf16 v[8:11], v[136:139], v[206:209], 0
	v_mfma_f32_16x16x32_bf16 v[60:63], v[132:135], v[186:189], v[60:63]
	v_mfma_f32_16x16x32_bf16 v[56:59], v[140:143], v[186:189], v[56:59]
	v_mfma_f32_16x16x32_bf16 v[44:47], v[132:135], v[194:197], v[44:47]
	v_mfma_f32_16x16x32_bf16 v[40:43], v[140:143], v[194:197], v[40:43]
	v_mfma_f32_16x16x32_bf16 v[28:31], v[132:135], v[202:205], v[28:31]
	v_mfma_f32_16x16x32_bf16 v[24:27], v[140:143], v[202:205], v[24:27]
	v_mfma_f32_16x16x32_bf16 v[12:15], v[132:135], v[210:213], v[12:15]
	v_mfma_f32_16x16x32_bf16 v[8:11], v[140:143], v[210:213], v[8:11]
	v_mfma_f32_16x16x32_bf16 v[52:55], v[166:169], v[182:185], 0
	v_mfma_f32_16x16x32_bf16 v[48:51], v[174:177], v[182:185], 0
	v_mfma_f32_16x16x32_bf16 v[36:39], v[166:169], v[190:193], 0
	v_mfma_f32_16x16x32_bf16 v[32:35], v[174:177], v[190:193], 0
	v_mfma_f32_16x16x32_bf16 v[20:23], v[166:169], v[198:201], 0
	v_mfma_f32_16x16x32_bf16 v[16:19], v[174:177], v[198:201], 0
	v_mfma_f32_16x16x32_bf16 v[4:7], v[166:169], v[206:209], 0
	v_mfma_f32_16x16x32_bf16 v[0:3], v[174:177], v[206:209], 0
	v_mfma_f32_16x16x32_bf16 v[52:55], v[170:173], v[186:189], v[52:55]
	v_mfma_f32_16x16x32_bf16 v[48:51], v[178:181], v[186:189], v[48:51]
	v_mfma_f32_16x16x32_bf16 v[36:39], v[170:173], v[194:197], v[36:39]
	v_mfma_f32_16x16x32_bf16 v[32:35], v[178:181], v[194:197], v[32:35]
	v_mfma_f32_16x16x32_bf16 v[20:23], v[170:173], v[202:205], v[20:23]
	v_mfma_f32_16x16x32_bf16 v[16:19], v[178:181], v[202:205], v[16:19]
	v_mfma_f32_16x16x32_bf16 v[4:7], v[170:173], v[210:213], v[4:7]
	v_mfma_f32_16x16x32_bf16 v[0:3], v[178:181], v[210:213], v[0:3]
	s_barrier
; #define PG8_STAGE(bufoff, gbase, voff) do { _Pragma("unroll") for (int _i = 0; _i < 2; ++_i) \
;         __builtin_amdgcn_global_load_lds((const unsigned*)((const char*)(gbase) + (voff)[_i]), (LAS unsigned*)(lds + (bufoff) + ldsw + _i * 8192), 16, 0, 0); } while (0)
; #define PG8_LDA(dst, b, h) do { _Pragma("unroll") for (int m = 0; m < 4; ++m) _Pragma("unroll") for (int k = 0; k < 2; ++k) dst[m][k] = *(const LAS bf16x8*)(lds + PG8_SA(b, h) + aoff + m * 2048 + k * 1024); } while (0)
; #define PG8_LDB(dst, b, h) do { _Pragma("unroll") for (int n = 0; n < 2; ++n) _Pragma("unroll") for (int k = 0; k < 2; ++k) dst[n][k] = *(const LAS bf16x8*)(lds + PG8_SB(b, h) + boff + n * 2048 + k * 1024); } while (0)
; #define PG8_MMA(ai, bj, At, Bt) do { __builtin_amdgcn_s_setprio(1); _Pragma("unroll") for (int m = 0; m < 4; ++m) _Pragma("unroll") for (int n = 0; n < 2; ++n) _Pragma("unroll") for (int k = 0; k < 2; ++k) \
;         acc[ai][bj][m][n] = __builtin_amdgcn_mfma_f32_16x16x32_bf16(Bt[n][k], At[m][k], acc[ai][bj][m][n], 0, 0, 0); __builtin_amdgcn_s_setprio(0); } while (0)
; #define PG8_WAIT_V(n) asm volatile("s_waitcnt vmcnt(" #n ")" ::: "memory")
; #define PG8_WAIT_L(n) asm volatile("s_waitcnt lgkmcnt(" #n ")" ::: "memory")
; #define PG8_BAR __builtin_amdgcn_s_barrier()
; #define PG8_SCHED __builtin_amdgcn_sched_barrier(0)
; template <class Epi, bool ALIGN_EPI, int K, int LDA, int LDB>
; __device__ __forceinline__ void gemm_phase(LAS unsigned char* lds, const int wid, const Gemm g, const StaticOrder& S, const Epi& E) {
;     ...
;             PG8_LDB(B0, 1, 0); PG8_LDB(B1, 1, 1); PG8_SCHED; PG8_LDA(At, 1, 0); PG8_STAGE(PG8_SA(0, 1), a2 + hA, voffA);
;             PG8_WAIT_V(8); PG8_WAIT_L(0); PG8_BAR; PG8_MMA(0, 0, At, B0); PG8_MMA(0, 1, At, B1); PG8_BAR; PG8_SCHED;
;             PG8_LDA(At, 1, 1); PG8_STAGE(PG8_SB(1, 0), b3, voffB); PG8_STAGE(PG8_SB(1, 1), b3 + hB, voffB); PG8_STAGE(PG8_SA(1, 0), a3, voffA);
;             PG8_WAIT_V(8); PG8_WAIT_L(0); PG8_BAR; PG8_MMA(1, 0, At, B0); PG8_MMA(1, 1, At, B1); PG8_BAR; PG8_SCHED;
	s_add_i32 s52, 0, 0x18000
	s_add_i32 s53, 0, 0x1c000
	v_add_u32_e32 v140, s52, v162
	v_add_u32_e32 v178, s53, v162
	ds_read_b128 v[128:131], v140
	ds_read_b128 v[132:135], v140 offset:1024
	ds_read_b128 v[136:139], v140 offset:2048
	ds_read_b128 v[140:143], v140 offset:3072
	ds_read_b128 v[166:169], v178
	ds_read_b128 v[170:173], v178 offset:1024
	ds_read_b128 v[174:177], v178 offset:2048
	ds_read_b128 v[178:181], v178 offset:3072
	s_add_u32 s40, s40, 0x40000
	s_addc_u32 s41, s41, 0
	s_mov_b32 m0, s43
	ds_read_b128 v[182:185], v165 offset:32768
	ds_read_b128 v[186:189], v165 offset:33792
	ds_read_b128 v[190:193], v165 offset:34816
	ds_read_b128 v[194:197], v165 offset:35840
	ds_read_b128 v[198:201], v165 offset:36864
	ds_read_b128 v[202:205], v165 offset:37888
	ds_read_b128 v[206:209], v165 offset:38912
	ds_read_b128 v[210:213], v165 offset:39936
	global_load_lds_dwordx4 v144, s[40:41]
	s_mov_b32 m0, s48
	s_nop 0
	global_load_lds_dwordx4 v148, s[40:41]
	s_waitcnt vmcnt(8)
	s_barrier
	s_waitcnt lgkmcnt(0)
	v_mfma_f32_16x16x32_bf16 v[124:127], v[128:131], v[182:185], v[124:127]
	v_mfma_f32_16x16x32_bf16 v[120:123], v[136:139], v[182:185], v[120:123]
	v_mfma_f32_16x16x32_bf16 v[108:111], v[128:131], v[190:193], v[108:111]
	v_mfma_f32_16x16x32_bf16 v[104:107], v[136:139], v[190:193], v[104:107]
	v_mfma_f32_16x16x32_bf16 v[92:95], v[128:131], v[198:201], v[92:95]
	v_mfma_f32_16x16x32_bf16 v[88:91], v[136:139], v[198:201], v[88:91]
	v_mfma_f32_16x16x32_bf16 v[76:79], v[128:131], v[206:209], v[76:79]
	v_mfma_f32_16x16x32_bf16 v[72:75], v[136:139], v[206:209], v[72:75]
	v_mfma_f32_16x16x32_bf16 v[124:127], v[132:135], v[186:189], v[124:127]
	v_mfma_f32_16x16x32_bf16 v[120:123], v[140:143], v[186:189], v[120:123]
	v_mfma_f32_16x16x32_bf16 v[108:111], v[132:135], v[194:197], v[108:111]
	v_mfma_f32_16x16x32_bf16 v[104:107], v[140:143], v[194:197], v[104:107]
	v_mfma_f32_16x16x32_bf16 v[92:95], v[132:135], v[202:205], v[92:95]
	v_mfma_f32_16x16x32_bf16 v[88:91], v[140:143], v[202:205], v[88:91]
	v_mfma_f32_16x16x32_bf16 v[76:79], v[132:135], v[210:213], v[76:79]
	v_mfma_f32_16x16x32_bf16 v[72:75], v[140:143], v[210:213], v[72:75]
	v_mfma_f32_16x16x32_bf16 v[116:119], v[166:169], v[182:185], v[116:119]
	v_mfma_f32_16x16x32_bf16 v[112:115], v[174:177], v[182:185], v[112:115]
	v_mfma_f32_16x16x32_bf16 v[100:103], v[166:169], v[190:193], v[100:103]
	v_mfma_f32_16x16x32_bf16 v[96:99], v[174:177], v[190:193], v[96:99]
	v_mfma_f32_16x16x32_bf16 v[84:87], v[166:169], v[198:201], v[84:87]
	v_mfma_f32_16x16x32_bf16 v[80:83], v[174:177], v[198:201], v[80:83]
	v_mfma_f32_16x16x32_bf16 v[68:71], v[166:169], v[206:209], v[68:71]
	v_mfma_f32_16x16x32_bf16 v[64:67], v[174:177], v[206:209], v[64:67]
	v_mfma_f32_16x16x32_bf16 v[116:119], v[170:173], v[186:189], v[116:119]
	v_mfma_f32_16x16x32_bf16 v[112:115], v[178:181], v[186:189], v[112:115]
	v_mfma_f32_16x16x32_bf16 v[100:103], v[170:173], v[194:197], v[100:103]
	v_mfma_f32_16x16x32_bf16 v[96:99], v[178:181], v[194:197], v[96:99]
	v_mfma_f32_16x16x32_bf16 v[84:87], v[170:173], v[202:205], v[84:87]
	v_mfma_f32_16x16x32_bf16 v[80:83], v[178:181], v[202:205], v[80:83]
	v_mfma_f32_16x16x32_bf16 v[68:71], v[170:173], v[210:213], v[68:71]
	v_mfma_f32_16x16x32_bf16 v[64:67], v[178:181], v[210:213], v[64:67]
	s_barrier
	s_add_i32 s40, s52, s33
	s_mov_b32 m0, s40
	ds_read_b128 v[182:185], v165 offset:49152
	ds_read_b128 v[186:189], v165 offset:50176
	ds_read_b128 v[190:193], v165 offset:51200
	ds_read_b128 v[194:197], v165 offset:52224
	ds_read_b128 v[198:201], v165 offset:53248
	ds_read_b128 v[202:205], v165 offset:54272
	ds_read_b128 v[206:209], v165 offset:55296
	ds_read_b128 v[210:213], v165 offset:56320
	global_load_lds_dwordx4 v146, s[98:99]
	s_add_i32 m0, s40, 0x2000
	s_add_u32 s38, s38, 0x40080
	s_addc_u32 s39, s39, 0
	s_add_i32 s40, s53, s33
	global_load_lds_dwordx4 v150, s[98:99]
	s_mov_b32 m0, s40
	s_nop 0
	global_load_lds_dwordx4 v146, s[38:39]
	s_add_i32 m0, s40, 0x2000
	s_nop 0
	global_load_lds_dwordx4 v150, s[38:39]
	s_mov_b32 m0, s55
	s_nop 0
	global_load_lds_dwordx4 v144, s[100:101]
	s_mov_b32 m0, s56
	s_nop 0
	global_load_lds_dwordx4 v148, s[100:101]
	s_waitcnt vmcnt(8)
	s_barrier
	s_waitcnt lgkmcnt(0)
	v_mfma_f32_16x16x32_bf16 v[60:63], v[128:131], v[182:185], v[60:63]
	v_mfma_f32_16x16x32_bf16 v[56:59], v[136:139], v[182:185], v[56:59]
	v_mfma_f32_16x16x32_bf16 v[44:47], v[128:131], v[190:193], v[44:47]
	v_mfma_f32_16x16x32_bf16 v[40:43], v[136:139], v[190:193], v[40:43]
	v_mfma_f32_16x16x32_bf16 v[28:31], v[128:131], v[198:201], v[28:31]
	v_mfma_f32_16x16x32_bf16 v[24:27], v[136:139], v[198:201], v[24:27]
	v_mfma_f32_16x16x32_bf16 v[12:15], v[128:131], v[206:209], v[12:15]
	v_mfma_f32_16x16x32_bf16 v[8:11], v[136:139], v[206:209], v[8:11]
	v_mfma_f32_16x16x32_bf16 v[60:63], v[132:135], v[186:189], v[60:63]
	v_mfma_f32_16x16x32_bf16 v[56:59], v[140:143], v[186:189], v[56:59]
	v_mfma_f32_16x16x32_bf16 v[44:47], v[132:135], v[194:197], v[44:47]
	v_mfma_f32_16x16x32_bf16 v[40:43], v[140:143], v[194:197], v[40:43]
	v_mfma_f32_16x16x32_bf16 v[28:31], v[132:135], v[202:205], v[28:31]
	v_mfma_f32_16x16x32_bf16 v[24:27], v[140:143], v[202:205], v[24:27]
	v_mfma_f32_16x16x32_bf16 v[12:15], v[132:135], v[210:213], v[12:15]
	v_mfma_f32_16x16x32_bf16 v[8:11], v[140:143], v[210:213], v[8:11]
	v_mfma_f32_16x16x32_bf16 v[52:55], v[166:169], v[182:185], v[52:55]
	v_mfma_f32_16x16x32_bf16 v[48:51], v[174:177], v[182:185], v[48:51]
	v_mfma_f32_16x16x32_bf16 v[36:39], v[166:169], v[190:193], v[36:39]
	v_mfma_f32_16x16x32_bf16 v[32:35], v[174:177], v[190:193], v[32:35]
	v_mfma_f32_16x16x32_bf16 v[20:23], v[166:169], v[198:201], v[20:23]
	v_mfma_f32_16x16x32_bf16 v[16:19], v[174:177], v[198:201], v[16:19]
	v_mfma_f32_16x16x32_bf16 v[4:7], v[166:169], v[206:209], v[4:7]
	v_mfma_f32_16x16x32_bf16 v[0:3], v[174:177], v[206:209], v[0:3]
	v_mfma_f32_16x16x32_bf16 v[52:55], v[170:173], v[186:189], v[52:55]
	v_mfma_f32_16x16x32_bf16 v[48:51], v[178:181], v[186:189], v[48:51]
	v_mfma_f32_16x16x32_bf16 v[36:39], v[170:173], v[194:197], v[36:39]
	v_mfma_f32_16x16x32_bf16 v[32:35], v[178:181], v[194:197], v[32:35]
	v_mfma_f32_16x16x32_bf16 v[20:23], v[170:173], v[202:205], v[20:23]
	v_mfma_f32_16x16x32_bf16 v[16:19], v[178:181], v[202:205], v[16:19]
	v_mfma_f32_16x16x32_bf16 v[4:7], v[170:173], v[210:213], v[4:7]
	v_mfma_f32_16x16x32_bf16 v[0:3], v[178:181], v[210:213], v[0:3]
	s_barrier
	s_add_i32 s67, s67, 2
	s_add_u32 s36, s36, 0x100
	s_addc_u32 s37, s37, 0
	s_add_u32 s65, s65, 0x100
	s_addc_u32 s66, s66, 0
; #define PG8_STAGE(bufoff, gbase, voff) do { _Pragma("unroll") for (int _i = 0; _i < 2; ++_i) \
;         __builtin_amdgcn_global_load_lds((const unsigned*)((const char*)(gbase) + (voff)[_i]), (LAS unsigned*)(lds + (bufoff) + ldsw + _i * 8192), 16, 0, 0); } while (0)
; #define PG8_LDA(dst, b, h) do { _Pragma("unroll") for (int m = 0; m < 4; ++m) _Pragma("unroll") for (int k = 0; k < 2; ++k) dst[m][k] = *(const LAS bf16x8*)(lds + PG8_SA(b, h) + aoff + m * 2048 + k * 1024); } while (0)
; #define PG8_LDB(dst, b, h) do { _Pragma("unroll") for (int n = 0; n < 2; ++n) _Pragma("unroll") for (int k = 0; k < 2; ++k) dst[n][k] = *(const LAS bf16x8*)(lds + PG8_SB(b, h) + boff + n * 2048 + k * 1024); } while (0)
; #define PG8_MMA(ai, bj, At, Bt) do { __builtin_amdgcn_s_setprio(1); _Pragma("unroll") for (int m = 0; m < 4; ++m) _Pragma("unroll") for (int n = 0; n < 2; ++n) _Pragma("unroll") for (int k = 0; k < 2; ++k) \
;         acc[ai][bj][m][n] = __builtin_amdgcn_mfma_f32_16x16x32_bf16(Bt[n][k], At[m][k], acc[ai][bj][m][n], 0, 0, 0); __builtin_amdgcn_s_setprio(0); } while (0)
; #define PG8_WAIT_V(n) asm volatile("s_waitcnt vmcnt(" #n ")" ::: "memory")
; #define PG8_WAIT_L(n) asm volatile("s_waitcnt lgkmcnt(" #n ")" ::: "memory")
; #define PG8_BAR __builtin_amdgcn_s_barrier()
; template <class Epi, bool ALIGN_EPI, int K, int LDA, int LDB>
; __device__ __forceinline__ void gemm_phase(LAS unsigned char* lds, const int wid, const Gemm g, const StaticOrder& S, const Epi& E) {
;     ...
;         for (int t = 0; t < nt; t += 2) {
;             const bool last = (t == nt - 2);
;             const char* a1 = cA + (size_t)(t + 1) * kstep;
;             const char* a2 = last ? nA : cA + (size_t)(t + 2) * kstep; const char* b2 = last ? nB : cB + (size_t)(t + 2) * kstep;
;             const char* a3 = a2 + kstep; const char* b3 = b2 + kstep;
;             PG8_LDB(B0, 0, 0); PG8_LDB(B1, 0, 1); PG8_SCHED; PG8_LDA(At, 0, 0); PG8_STAGE(PG8_SA(1, 1), a1 + hA, voffA);
;             PG8_WAIT_V(8); PG8_WAIT_L(0); PG8_BAR; PG8_MMA(0, 0, At, B0); PG8_MMA(0, 1, At, B1); PG8_BAR; PG8_SCHED;
;             PG8_LDA(At, 0, 1); PG8_STAGE(PG8_SB(0, 0), b2, voffB); PG8_STAGE(PG8_SB(0, 1), b2 + hB, voffB); PG8_STAGE(PG8_SA(0, 0), a2, voffA);
;             PG8_WAIT_V(8); PG8_WAIT_L(0); PG8_BAR; PG8_MMA(1, 0, At, B0); PG8_MMA(1, 1, At, B1); PG8_BAR; PG8_SCHED;
.LBB0_917:
	ds_read_b128 v[128:131], v163
	ds_read_b128 v[132:135], v163 offset:1024
	ds_read_b128 v[136:139], v163 offset:2048
	ds_read_b128 v[140:143], v163 offset:3072
	ds_read_b128 v[166:169], v164
	ds_read_b128 v[170:173], v164 offset:1024
	ds_read_b128 v[174:177], v164 offset:2048
	ds_read_b128 v[178:181], v164 offset:3072
	s_add_u32 s38, s36, 0xfffc0080
	s_addc_u32 s39, s37, -1
	s_cmp_eq_u32 s67, 12
	s_cselect_b32 s41, s27, s39
	s_cselect_b32 s40, s63, s38
	s_cselect_b32 s39, s25, s66
	s_cselect_b32 s38, s64, s65
	s_add_i32 m0, s35, 0xc000
	ds_read_b128 v[182:185], v165
	ds_read_b128 v[186:189], v165 offset:1024
	ds_read_b128 v[190:193], v165 offset:2048
	ds_read_b128 v[194:197], v165 offset:3072
	ds_read_b128 v[198:201], v165 offset:4096
	ds_read_b128 v[202:205], v165 offset:5120
	ds_read_b128 v[206:209], v165 offset:6144
	ds_read_b128 v[210:213], v165 offset:7168
	global_load_lds_dwordx4 v152, s[36:37]
	s_add_i32 m0, s35, 0xe000
	s_nop 0
	global_load_lds_dwordx4 v154, s[36:37]
	s_waitcnt vmcnt(8)
	s_barrier
	s_waitcnt lgkmcnt(0)
	v_mfma_f32_16x16x32_bf16 v[124:127], v[128:131], v[182:185], v[124:127]
	v_mfma_f32_16x16x32_bf16 v[120:123], v[136:139], v[182:185], v[120:123]
	v_mfma_f32_16x16x32_bf16 v[108:111], v[128:131], v[190:193], v[108:111]
	v_mfma_f32_16x16x32_bf16 v[104:107], v[136:139], v[190:193], v[104:107]
	v_mfma_f32_16x16x32_bf16 v[92:95], v[128:131], v[198:201], v[92:95]
	v_mfma_f32_16x16x32_bf16 v[88:91], v[136:139], v[198:201], v[88:91]
	v_mfma_f32_16x16x32_bf16 v[76:79], v[128:131], v[206:209], v[76:79]
	v_mfma_f32_16x16x32_bf16 v[72:75], v[136:139], v[206:209], v[72:75]
	v_mfma_f32_16x16x32_bf16 v[124:127], v[132:135], v[186:189], v[124:127]
	v_mfma_f32_16x16x32_bf16 v[120:123], v[140:143], v[186:189], v[120:123]
	v_mfma_f32_16x16x32_bf16 v[108:111], v[132:135], v[194:197], v[108:111]
	v_mfma_f32_16x16x32_bf16 v[104:107], v[140:143], v[194:197], v[104:107]
	v_mfma_f32_16x16x32_bf16 v[92:95], v[132:135], v[202:205], v[92:95]
	v_mfma_f32_16x16x32_bf16 v[88:91], v[140:143], v[202:205], v[88:91]
	v_mfma_f32_16x16x32_bf16 v[76:79], v[132:135], v[210:213], v[76:79]
	v_mfma_f32_16x16x32_bf16 v[72:75], v[140:143], v[210:213], v[72:75]
	v_mfma_f32_16x16x32_bf16 v[116:119], v[166:169], v[182:185], v[116:119]
	v_mfma_f32_16x16x32_bf16 v[112:115], v[174:177], v[182:185], v[112:115]
	v_mfma_f32_16x16x32_bf16 v[100:103], v[166:169], v[190:193], v[100:103]
	v_mfma_f32_16x16x32_bf16 v[96:99], v[174:177], v[190:193], v[96:99]
	v_mfma_f32_16x16x32_bf16 v[84:87], v[166:169], v[198:201], v[84:87]
	v_mfma_f32_16x16x32_bf16 v[80:83], v[174:177], v[198:201], v[80:83]
	v_mfma_f32_16x16x32_bf16 v[68:71], v[166:169], v[206:209], v[68:71]
	v_mfma_f32_16x16x32_bf16 v[64:67], v[174:177], v[206:209], v[64:67]
	v_mfma_f32_16x16x32_bf16 v[116:119], v[170:173], v[186:189], v[116:119]
	v_mfma_f32_16x16x32_bf16 v[112:115], v[178:181], v[186:189], v[112:115]
	v_mfma_f32_16x16x32_bf16 v[100:103], v[170:173], v[194:197], v[100:103]
	v_mfma_f32_16x16x32_bf16 v[96:99], v[178:181], v[194:197], v[96:99]
	v_mfma_f32_16x16x32_bf16 v[84:87], v[170:173], v[202:205], v[84:87]
	v_mfma_f32_16x16x32_bf16 v[80:83], v[178:181], v[202:205], v[80:83]
	v_mfma_f32_16x16x32_bf16 v[68:71], v[170:173], v[210:213], v[68:71]
	v_mfma_f32_16x16x32_bf16 v[64:67], v[178:181], v[210:213], v[64:67]
	s_barrier
	s_add_u32 s98, s38, s12
	s_addc_u32 s99, s39, s13
	s_add_u32 s100, s40, s12
	s_addc_u32 s101, s41, s13
	s_add_i32 s52, s58, s33
	s_mov_b32 m0, s52
	ds_read_b128 v[182:185], v165 offset:16384
	ds_read_b128 v[186:189], v165 offset:17408
	ds_read_b128 v[190:193], v165 offset:18432
	ds_read_b128 v[194:197], v165 offset:19456
	ds_read_b128 v[198:201], v165 offset:20480
	ds_read_b128 v[202:205], v165 offset:21504
	ds_read_b128 v[206:209], v165 offset:22528
	ds_read_b128 v[210:213], v165 offset:23552
	global_load_lds_dwordx4 v146, s[38:39]
	s_add_i32 m0, s52, 0x2000
	s_add_u32 s68, s38, 0x40000
	s_addc_u32 s69, s39, 0
	s_add_i32 s52, s59, s33
	global_load_lds_dwordx4 v150, s[38:39]
	s_mov_b32 m0, s52
	s_nop 0
	global_load_lds_dwordx4 v146, s[68:69]
	s_add_i32 m0, s52, 0x2000
	s_nop 0
	global_load_lds_dwordx4 v150, s[68:69]
	s_mov_b32 m0, s35
	s_nop 0
	global_load_lds_dwordx4 v144, s[40:41]
	s_mov_b32 m0, s42
	s_nop 0
	global_load_lds_dwordx4 v148, s[40:41]
	s_waitcnt vmcnt(8)
	s_barrier
	s_waitcnt lgkmcnt(0)
	v_mfma_f32_16x16x32_bf16 v[60:63], v[128:131], v[182:185], v[60:63]
	v_mfma_f32_16x16x32_bf16 v[56:59], v[136:139], v[182:185], v[56:59]
	v_mfma_f32_16x16x32_bf16 v[44:47], v[128:131], v[190:193], v[44:47]
	v_mfma_f32_16x16x32_bf16 v[40:43], v[136:139], v[190:193], v[40:43]
	v_mfma_f32_16x16x32_bf16 v[28:31], v[128:131], v[198:201], v[28:31]
	v_mfma_f32_16x16x32_bf16 v[24:27], v[136:139], v[198:201], v[24:27]
	v_mfma_f32_16x16x32_bf16 v[12:15], v[128:131], v[206:209], v[12:15]
	v_mfma_f32_16x16x32_bf16 v[8:11], v[136:139], v[206:209], v[8:11]
	v_mfma_f32_16x16x32_bf16 v[60:63], v[132:135], v[186:189], v[60:63]
	v_mfma_f32_16x16x32_bf16 v[56:59], v[140:143], v[186:189], v[56:59]
	v_mfma_f32_16x16x32_bf16 v[44:47], v[132:135], v[194:197], v[44:47]
	v_mfma_f32_16x16x32_bf16 v[40:43], v[140:143], v[194:197], v[40:43]
	v_mfma_f32_16x16x32_bf16 v[28:31], v[132:135], v[202:205], v[28:31]
	v_mfma_f32_16x16x32_bf16 v[24:27], v[140:143], v[202:205], v[24:27]
	v_mfma_f32_16x16x32_bf16 v[12:15], v[132:135], v[210:213], v[12:15]
	v_mfma_f32_16x16x32_bf16 v[8:11], v[140:143], v[210:213], v[8:11]
	v_mfma_f32_16x16x32_bf16 v[52:55], v[166:169], v[182:185], v[52:55]
	v_mfma_f32_16x16x32_bf16 v[48:51], v[174:177], v[182:185], v[48:51]
	v_mfma_f32_16x16x32_bf16 v[36:39], v[166:169], v[190:193], v[36:39]
	v_mfma_f32_16x16x32_bf16 v[32:35], v[174:177], v[190:193], v[32:35]
	v_mfma_f32_16x16x32_bf16 v[20:23], v[166:169], v[198:201], v[20:23]
	v_mfma_f32_16x16x32_bf16 v[16:19], v[174:177], v[198:201], v[16:19]
	v_mfma_f32_16x16x32_bf16 v[4:7], v[166:169], v[206:209], v[4:7]
	v_mfma_f32_16x16x32_bf16 v[0:3], v[174:177], v[206:209], v[0:3]
	v_mfma_f32_16x16x32_bf16 v[52:55], v[170:173], v[186:189], v[52:55]
	v_mfma_f32_16x16x32_bf16 v[48:51], v[178:181], v[186:189], v[48:51]
	v_mfma_f32_16x16x32_bf16 v[36:39], v[170:173], v[194:197], v[36:39]
	v_mfma_f32_16x16x32_bf16 v[32:35], v[178:181], v[194:197], v[32:35]
	v_mfma_f32_16x16x32_bf16 v[20:23], v[170:173], v[202:205], v[20:23]
	v_mfma_f32_16x16x32_bf16 v[16:19], v[178:181], v[202:205], v[16:19]
	v_mfma_f32_16x16x32_bf16 v[4:7], v[170:173], v[210:213], v[4:7]
	v_mfma_f32_16x16x32_bf16 v[0:3], v[178:181], v[210:213], v[0:3]
	s_barrier
; #define PG8_STAGE(bufoff, gbase, voff) do { _Pragma("unroll") for (int _i = 0; _i < 2; ++_i) \
;         __builtin_amdgcn_global_load_lds((const unsigned*)((const char*)(gbase) + (voff)[_i]), (LAS unsigned*)(lds + (bufoff) + ldsw + _i * 8192), 16, 0, 0); } while (0)
; #define PG8_LDA(dst, b, h) do { _Pragma("unroll") for (int m = 0; m < 4; ++m) _Pragma("unroll") for (int k = 0; k < 2; ++k) dst[m][k] = *(const LAS bf16x8*)(lds + PG8_SA(b, h) + aoff + m * 2048 + k * 1024); } while (0)
; #define PG8_LDB(dst, b, h) do { _Pragma("unroll") for (int n = 0; n < 2; ++n) _Pragma("unroll") for (int k = 0; k < 2; ++k) dst[n][k] = *(const LAS bf16x8*)(lds + PG8_SB(b, h) + boff + n * 2048 + k * 1024); } while (0)
; #define PG8_MMA(ai, bj, At, Bt) do { __builtin_amdgcn_s_setprio(1); _Pragma("unroll") for (int m = 0; m < 4; ++m) _Pragma("unroll") for (int n = 0; n < 2; ++n) _Pragma("unroll") for (int k = 0; k < 2; ++k) \
;         acc[ai][bj][m][n] = __builtin_amdgcn_mfma_f32_16x16x32_bf16(Bt[n][k], At[m][k], acc[ai][bj][m][n], 0, 0, 0); __builtin_amdgcn_s_setprio(0); } while (0)
; #define PG8_WAIT_V(n) asm volatile("s_waitcnt vmcnt(" #n ")" ::: "memory")
; #define PG8_WAIT_L(n) asm volatile("s_waitcnt lgkmcnt(" #n ")" ::: "memory")
; #define PG8_BAR __builtin_amdgcn_s_barrier()
; #define PG8_SCHED __builtin_amdgcn_sched_barrier(0)
; template <class Epi, bool ALIGN_EPI, int K, int LDA, int LDB>
; __device__ __forceinline__ void gemm_phase(LAS unsigned char* lds, const int wid, const Gemm g, const StaticOrder& S, const Epi& E) {
;     ...
;             PG8_LDB(B0, 1, 0); PG8_LDB(B1, 1, 1); PG8_SCHED; PG8_LDA(At, 1, 0); PG8_STAGE(PG8_SA(0, 1), a2 + hA, voffA);
;             PG8_WAIT_V(8); PG8_WAIT_L(0); PG8_BAR; PG8_MMA(0, 0, At, B0); PG8_MMA(0, 1, At, B1); PG8_BAR; PG8_SCHED;
;             PG8_LDA(At, 1, 1); PG8_STAGE(PG8_SB(1, 0), b3, voffB); PG8_STAGE(PG8_SB(1, 1), b3 + hB, voffB); PG8_STAGE(PG8_SA(1, 0), a3, voffA);
;             PG8_WAIT_V(8); PG8_WAIT_L(0); PG8_BAR; PG8_MMA(1, 0, At, B0); PG8_MMA(1, 1, At, B1); PG8_BAR; PG8_SCHED;
;         }
;         if constexpr (ALIGN_EPI) { if (wr == 0) PG8_BAR; }
	s_add_i32 s52, 0, 0x18000
	s_add_i32 s53, 0, 0x1c000
	v_add_u32_e32 v140, s52, v162
	v_add_u32_e32 v178, s53, v162
	ds_read_b128 v[128:131], v140
	ds_read_b128 v[132:135], v140 offset:1024
	ds_read_b128 v[136:139], v140 offset:2048
	ds_read_b128 v[140:143], v140 offset:3072
	ds_read_b128 v[166:169], v178
	ds_read_b128 v[170:173], v178 offset:1024
	ds_read_b128 v[174:177], v178 offset:2048
	ds_read_b128 v[178:181], v178 offset:3072
	s_add_u32 s40, s40, 0x40000
	s_addc_u32 s41, s41, 0
	s_mov_b32 m0, s43
	ds_read_b128 v[182:185], v165 offset:32768
	ds_read_b128 v[186:189], v165 offset:33792
	ds_read_b128 v[190:193], v165 offset:34816
	ds_read_b128 v[194:197], v165 offset:35840
	ds_read_b128 v[198:201], v165 offset:36864
	ds_read_b128 v[202:205], v165 offset:37888
	ds_read_b128 v[206:209], v165 offset:38912
	ds_read_b128 v[210:213], v165 offset:39936
	global_load_lds_dwordx4 v144, s[40:41]
	s_mov_b32 m0, s48
	s_nop 0
	global_load_lds_dwordx4 v148, s[40:41]
	s_waitcnt vmcnt(8)
	s_barrier
	s_waitcnt lgkmcnt(0)
	v_mfma_f32_16x16x32_bf16 v[124:127], v[128:131], v[182:185], v[124:127]
	v_mfma_f32_16x16x32_bf16 v[120:123], v[136:139], v[182:185], v[120:123]
	v_mfma_f32_16x16x32_bf16 v[108:111], v[128:131], v[190:193], v[108:111]
	v_mfma_f32_16x16x32_bf16 v[104:107], v[136:139], v[190:193], v[104:107]
	v_mfma_f32_16x16x32_bf16 v[92:95], v[128:131], v[198:201], v[92:95]
	v_mfma_f32_16x16x32_bf16 v[88:91], v[136:139], v[198:201], v[88:91]
	v_mfma_f32_16x16x32_bf16 v[76:79], v[128:131], v[206:209], v[76:79]
	v_mfma_f32_16x16x32_bf16 v[72:75], v[136:139], v[206:209], v[72:75]
	v_mfma_f32_16x16x32_bf16 v[124:127], v[132:135], v[186:189], v[124:127]
	v_mfma_f32_16x16x32_bf16 v[120:123], v[140:143], v[186:189], v[120:123]
	v_mfma_f32_16x16x32_bf16 v[108:111], v[132:135], v[194:197], v[108:111]
	v_mfma_f32_16x16x32_bf16 v[104:107], v[140:143], v[194:197], v[104:107]
	v_mfma_f32_16x16x32_bf16 v[92:95], v[132:135], v[202:205], v[92:95]
	v_mfma_f32_16x16x32_bf16 v[88:91], v[140:143], v[202:205], v[88:91]
	v_mfma_f32_16x16x32_bf16 v[76:79], v[132:135], v[210:213], v[76:79]
	v_mfma_f32_16x16x32_bf16 v[72:75], v[140:143], v[210:213], v[72:75]
	v_mfma_f32_16x16x32_bf16 v[116:119], v[166:169], v[182:185], v[116:119]
	v_mfma_f32_16x16x32_bf16 v[112:115], v[174:177], v[182:185], v[112:115]
	v_mfma_f32_16x16x32_bf16 v[100:103], v[166:169], v[190:193], v[100:103]
	v_mfma_f32_16x16x32_bf16 v[96:99], v[174:177], v[190:193], v[96:99]
	v_mfma_f32_16x16x32_bf16 v[84:87], v[166:169], v[198:201], v[84:87]
	v_mfma_f32_16x16x32_bf16 v[80:83], v[174:177], v[198:201], v[80:83]
	v_mfma_f32_16x16x32_bf16 v[68:71], v[166:169], v[206:209], v[68:71]
	v_mfma_f32_16x16x32_bf16 v[64:67], v[174:177], v[206:209], v[64:67]
	v_mfma_f32_16x16x32_bf16 v[116:119], v[170:173], v[186:189], v[116:119]
	v_mfma_f32_16x16x32_bf16 v[112:115], v[178:181], v[186:189], v[112:115]
	v_mfma_f32_16x16x32_bf16 v[100:103], v[170:173], v[194:197], v[100:103]
	v_mfma_f32_16x16x32_bf16 v[96:99], v[178:181], v[194:197], v[96:99]
	v_mfma_f32_16x16x32_bf16 v[84:87], v[170:173], v[202:205], v[84:87]
	v_mfma_f32_16x16x32_bf16 v[80:83], v[178:181], v[202:205], v[80:83]
	v_mfma_f32_16x16x32_bf16 v[68:71], v[170:173], v[210:213], v[68:71]
	v_mfma_f32_16x16x32_bf16 v[64:67], v[178:181], v[210:213], v[64:67]
	s_barrier
	s_add_i32 s40, s52, s33
	s_mov_b32 m0, s40
	ds_read_b128 v[182:185], v165 offset:49152
	ds_read_b128 v[186:189], v165 offset:50176
	ds_read_b128 v[190:193], v165 offset:51200
	ds_read_b128 v[194:197], v165 offset:52224
	ds_read_b128 v[198:201], v165 offset:53248
	ds_read_b128 v[202:205], v165 offset:54272
	ds_read_b128 v[206:209], v165 offset:55296
	ds_read_b128 v[210:213], v165 offset:56320
	global_load_lds_dwordx4 v146, s[98:99]
	s_add_i32 m0, s40, 0x2000
	s_add_u32 s38, s38, 0x40080
	s_addc_u32 s39, s39, 0
	s_add_i32 s40, s53, s33
	global_load_lds_dwordx4 v150, s[98:99]
	s_mov_b32 m0, s40
	s_nop 0
	global_load_lds_dwordx4 v146, s[38:39]
	s_add_i32 m0, s40, 0x2000
	s_nop 0
	global_load_lds_dwordx4 v150, s[38:39]
	s_mov_b32 m0, s55
	s_nop 0
	global_load_lds_dwordx4 v144, s[100:101]
	s_mov_b32 m0, s56
	s_nop 0
	global_load_lds_dwordx4 v148, s[100:101]
	s_waitcnt vmcnt(8)
	s_barrier
	s_waitcnt lgkmcnt(0)
	v_mfma_f32_16x16x32_bf16 v[60:63], v[128:131], v[182:185], v[60:63]
	v_mfma_f32_16x16x32_bf16 v[56:59], v[136:139], v[182:185], v[56:59]
	v_mfma_f32_16x16x32_bf16 v[44:47], v[128:131], v[190:193], v[44:47]
	v_mfma_f32_16x16x32_bf16 v[40:43], v[136:139], v[190:193], v[40:43]
	v_mfma_f32_16x16x32_bf16 v[28:31], v[128:131], v[198:201], v[28:31]
	v_mfma_f32_16x16x32_bf16 v[24:27], v[136:139], v[198:201], v[24:27]
	v_mfma_f32_16x16x32_bf16 v[12:15], v[128:131], v[206:209], v[12:15]
	v_mfma_f32_16x16x32_bf16 v[8:11], v[136:139], v[206:209], v[8:11]
	v_mfma_f32_16x16x32_bf16 v[60:63], v[132:135], v[186:189], v[60:63]
	v_mfma_f32_16x16x32_bf16 v[56:59], v[140:143], v[186:189], v[56:59]
	v_mfma_f32_16x16x32_bf16 v[44:47], v[132:135], v[194:197], v[44:47]
	v_mfma_f32_16x16x32_bf16 v[40:43], v[140:143], v[194:197], v[40:43]
	v_mfma_f32_16x16x32_bf16 v[28:31], v[132:135], v[202:205], v[28:31]
	v_mfma_f32_16x16x32_bf16 v[24:27], v[140:143], v[202:205], v[24:27]
	v_mfma_f32_16x16x32_bf16 v[12:15], v[132:135], v[210:213], v[12:15]
	v_mfma_f32_16x16x32_bf16 v[8:11], v[140:143], v[210:213], v[8:11]
	v_mfma_f32_16x16x32_bf16 v[52:55], v[166:169], v[182:185], v[52:55]
	v_mfma_f32_16x16x32_bf16 v[48:51], v[174:177], v[182:185], v[48:51]
	v_mfma_f32_16x16x32_bf16 v[36:39], v[166:169], v[190:193], v[36:39]
	v_mfma_f32_16x16x32_bf16 v[32:35], v[174:177], v[190:193], v[32:35]
	v_mfma_f32_16x16x32_bf16 v[20:23], v[166:169], v[198:201], v[20:23]
	v_mfma_f32_16x16x32_bf16 v[16:19], v[174:177], v[198:201], v[16:19]
	v_mfma_f32_16x16x32_bf16 v[4:7], v[166:169], v[206:209], v[4:7]
	v_mfma_f32_16x16x32_bf16 v[0:3], v[174:177], v[206:209], v[0:3]
	v_mfma_f32_16x16x32_bf16 v[52:55], v[170:173], v[186:189], v[52:55]
	v_mfma_f32_16x16x32_bf16 v[48:51], v[178:181], v[186:189], v[48:51]
	v_mfma_f32_16x16x32_bf16 v[36:39], v[170:173], v[194:197], v[36:39]
	v_mfma_f32_16x16x32_bf16 v[32:35], v[178:181], v[194:197], v[32:35]
	v_mfma_f32_16x16x32_bf16 v[20:23], v[170:173], v[202:205], v[20:23]
	v_mfma_f32_16x16x32_bf16 v[16:19], v[178:181], v[202:205], v[16:19]
	v_mfma_f32_16x16x32_bf16 v[4:7], v[170:173], v[210:213], v[4:7]
	v_mfma_f32_16x16x32_bf16 v[0:3], v[178:181], v[210:213], v[0:3]
	s_barrier
	s_add_i32 s67, s67, 2
	s_add_u32 s36, s36, 0x100
	s_addc_u32 s37, s37, 0
	s_add_u32 s65, s65, 0x100
	s_addc_u32 s66, s66, 0
	s_cmp_gt_u32 s67, 13
	s_cbranch_scc0 .LBB0_917
	s_and_b64 vcc, exec, s[14:15]
	s_cbranch_vccz .LBB0_920
	s_barrier

; #define PG8_STAGE(bufoff, gbase, voff) do { _Pragma("unroll") for (int _i = 0; _i < 2; ++_i) \
;         __builtin_amdgcn_global_load_lds((const unsigned*)((const char*)(gbase) + (voff)[_i]), (LAS unsigned*)(lds + (bufoff) + ldsw + _i * 8192), 16, 0, 0); } while (0)
; #define PG8_LDA(dst, b, h) do { _Pragma("unroll") for (int m = 0; m < 4; ++m) _Pragma("unroll") for (int k = 0; k < 2; ++k) dst[m][k] = *(const LAS bf16x8*)(lds + PG8_SA(b, h) + aoff + m * 2048 + k * 1024); } while (0)
; #define PG8_LDB(dst, b, h) do { _Pragma("unroll") for (int n = 0; n < 2; ++n) _Pragma("unroll") for (int k = 0; k < 2; ++k) dst[n][k] = *(const LAS bf16x8*)(lds + PG8_SB(b, h) + boff + n * 2048 + k * 1024); } while (0)
; #define PG8_MMA(ai, bj, At, Bt) do { __builtin_amdgcn_s_setprio(1); _Pragma("unroll") for (int m = 0; m < 4; ++m) _Pragma("unroll") for (int n = 0; n < 2; ++n) _Pragma("unroll") for (int k = 0; k < 2; ++k) \
;         acc[ai][bj][m][n] = __builtin_amdgcn_mfma_f32_16x16x32_bf16(Bt[n][k], At[m][k], acc[ai][bj][m][n], 0, 0, 0); __builtin_amdgcn_s_setprio(0); } while (0)
; template <class Epi, bool ALIGN_EPI, int K, int LDA, int LDB>
; __device__ __forceinline__ void gemm_phase(LAS unsigned char* lds, const int wid, const Gemm g, const StaticOrder& S, const Epi& E) {
;     ...
;         const bool has_next = S.next(ui + 1, nxt);
;         const char* nA = has_next ? (const char*)g.A + (size_t)nxt.pm * tA : cA; const char* nB = has_next ? (const char*)g.Bt + (size_t)nxt.pn * tB : cB;
;         for (int t = 0; t < nt; t += 2) {
;             const bool last = (t == nt - 2);
;             const char* a1 = cA + (size_t)(t + 1) * kstep;
;             const char* a2 = last ? nA : cA + (size_t)(t + 2) * kstep; const char* b2 = last ? nB : cB + (size_t)(t + 2) * kstep;
;             const char* a3 = a2 + kstep; const char* b3 = b2 + kstep;
;             PG8_LDB(B0, 0, 0); PG8_LDB(B1, 0, 1); PG8_SCHED; PG8_LDA(At, 0, 0); PG8_STAGE(PG8_SA(1, 1), a1 + hA, voffA);
;             PG8_WAIT_V(8); PG8_WAIT_L(0); PG8_BAR; PG8_MMA(0, 0, At, B0); PG8_MMA(0, 1, At, B1); PG8_BAR; PG8_SCHED;
;             PG8_LDA(At, 0, 1); PG8_STAGE(PG8_SB(0, 0), b2, voffB); PG8_STAGE(PG8_SB(0, 1), b2 + hB, voffB); PG8_STAGE(PG8_SA(0, 0), a2, voffA);
;             PG8_WAIT_V(8); PG8_WAIT_L(0); PG8_BAR; PG8_MMA(1, 0, At, B0); PG8_MMA(1, 1, At, B1); PG8_BAR; PG8_SCHED;
.LBB0_1051:
	s_ashr_i32 s15, s14, 31
	s_lshl_b64 s[16:17], s[14:15], 19
	v_readlane_b32 s13, v254, 0
	s_add_u32 s16, s13, s16
	v_readlane_b32 s13, v254, 1
	s_addc_u32 s17, s13, s17
	s_and_b64 s[18:19], s[4:5], exec
	s_cselect_b32 s15, s17, s23
	s_cselect_b32 s48, s16, s22
	s_ashr_i32 s13, s12, 31
	s_lshl_b64 s[18:19], s[12:13], 19
	s_add_u32 s18, s0, s18
	s_addc_u32 s19, s1, s19
	s_and_b64 s[26:27], s[4:5], exec
	s_cselect_b32 s13, s19, s25
	s_cselect_b32 s49, s18, s24
	s_add_u32 s22, s22, 0x40080
	s_addc_u32 s23, s23, 0
	s_add_u32 s51, s24, 0x100
	s_addc_u32 s54, s25, 0
	s_mov_b32 s55, -2
	s_add_u32 s24, s22, 0xfffc0080
	s_addc_u32 s25, s23, -1
	s_cmp_eq_u32 s55, 12
	s_cselect_b32 s27, s15, s25
	s_cselect_b32 s26, s48, s24
	s_cselect_b32 s25, s13, s54
	s_cselect_b32 s24, s49, s51
	s_add_i32 m0, s21, 0xc000
	global_load_lds_dwordx4 v136, s[22:23]
	s_add_i32 m0, s21, 0xe000
	s_nop 0
	global_load_lds_dwordx4 v138, s[22:23]
	s_waitcnt vmcnt(8)
	s_barrier
	s_waitcnt lgkmcnt(0)
	v_mfma_f32_16x16x32_bf16 v[124:127], v[148:151], v[180:183], 0
	v_mfma_f32_16x16x32_bf16 v[120:123], v[156:159], v[180:183], 0
	v_mfma_f32_16x16x32_bf16 v[108:111], v[148:151], v[188:191], 0
	v_mfma_f32_16x16x32_bf16 v[104:107], v[156:159], v[188:191], 0
	v_mfma_f32_16x16x32_bf16 v[92:95], v[148:151], v[196:199], 0
	v_mfma_f32_16x16x32_bf16 v[88:91], v[156:159], v[196:199], 0
	v_mfma_f32_16x16x32_bf16 v[76:79], v[148:151], v[204:207], 0
	v_mfma_f32_16x16x32_bf16 v[72:75], v[156:159], v[204:207], 0
	v_mfma_f32_16x16x32_bf16 v[124:127], v[152:155], v[184:187], v[124:127]
	v_mfma_f32_16x16x32_bf16 v[120:123], v[160:163], v[184:187], v[120:123]
	v_mfma_f32_16x16x32_bf16 v[108:111], v[152:155], v[192:195], v[108:111]
	v_mfma_f32_16x16x32_bf16 v[104:107], v[160:163], v[192:195], v[104:107]
	v_mfma_f32_16x16x32_bf16 v[92:95], v[152:155], v[200:203], v[92:95]
	v_mfma_f32_16x16x32_bf16 v[88:91], v[160:163], v[200:203], v[88:91]
	v_mfma_f32_16x16x32_bf16 v[76:79], v[152:155], v[208:211], v[76:79]
	v_mfma_f32_16x16x32_bf16 v[72:75], v[160:163], v[208:211], v[72:75]
	v_mfma_f32_16x16x32_bf16 v[116:119], v[164:167], v[180:183], 0
	v_mfma_f32_16x16x32_bf16 v[112:115], v[172:175], v[180:183], 0
	v_mfma_f32_16x16x32_bf16 v[100:103], v[164:167], v[188:191], 0
	v_mfma_f32_16x16x32_bf16 v[96:99], v[172:175], v[188:191], 0
	v_mfma_f32_16x16x32_bf16 v[84:87], v[164:167], v[196:199], 0
	v_mfma_f32_16x16x32_bf16 v[80:83], v[172:175], v[196:199], 0
	v_mfma_f32_16x16x32_bf16 v[68:71], v[164:167], v[204:207], 0
	v_mfma_f32_16x16x32_bf16 v[64:67], v[172:175], v[204:207], 0
	v_mfma_f32_16x16x32_bf16 v[116:119], v[168:171], v[184:187], v[116:119]
	v_mfma_f32_16x16x32_bf16 v[112:115], v[176:179], v[184:187], v[112:115]
	v_mfma_f32_16x16x32_bf16 v[100:103], v[168:171], v[192:195], v[100:103]
	v_mfma_f32_16x16x32_bf16 v[96:99], v[176:179], v[192:195], v[96:99]
	v_mfma_f32_16x16x32_bf16 v[84:87], v[168:171], v[200:203], v[84:87]
	v_mfma_f32_16x16x32_bf16 v[80:83], v[176:179], v[200:203], v[80:83]
	v_mfma_f32_16x16x32_bf16 v[68:71], v[168:171], v[208:211], v[68:71]
	v_mfma_f32_16x16x32_bf16 v[64:67], v[176:179], v[208:211], v[64:67]
	s_barrier
	s_add_u32 s98, s24, s10
	s_addc_u32 s99, s25, s11
	s_add_u32 s100, s26, s10
	s_addc_u32 s101, s27, s11
	s_add_i32 s52, s40, s3
	s_mov_b32 m0, s52
	ds_read_b128 v[180:183], v147 offset:16384
	ds_read_b128 v[184:187], v147 offset:17408
	ds_read_b128 v[188:191], v147 offset:18432
	ds_read_b128 v[192:195], v147 offset:19456
	ds_read_b128 v[196:199], v147 offset:20480
	ds_read_b128 v[200:203], v147 offset:21504
	ds_read_b128 v[204:207], v147 offset:22528
	ds_read_b128 v[208:211], v147 offset:23552
	global_load_lds_dwordx4 v132, s[24:25]
	s_add_i32 m0, s52, 0x2000
	s_add_u32 s56, s24, 0x40000
	s_addc_u32 s57, s25, 0
	s_add_i32 s52, s41, s3
	global_load_lds_dwordx4 v128, s[24:25]
	s_mov_b32 m0, s52
	s_nop 0
	global_load_lds_dwordx4 v132, s[56:57]
	s_add_i32 m0, s52, 0x2000
	s_nop 0
	global_load_lds_dwordx4 v128, s[56:57]
	s_mov_b32 m0, s21
	s_nop 0
	global_load_lds_dwordx4 v134, s[26:27]
	s_mov_b32 m0, s30
	s_nop 0
	global_load_lds_dwordx4 v130, s[26:27]
	s_waitcnt vmcnt(8)
	s_barrier
	s_waitcnt lgkmcnt(0)
	v_mfma_f32_16x16x32_bf16 v[60:63], v[148:151], v[180:183], 0
	v_mfma_f32_16x16x32_bf16 v[56:59], v[156:159], v[180:183], 0
	v_mfma_f32_16x16x32_bf16 v[44:47], v[148:151], v[188:191], 0
	v_mfma_f32_16x16x32_bf16 v[40:43], v[156:159], v[188:191], 0
	v_mfma_f32_16x16x32_bf16 v[28:31], v[148:151], v[196:199], 0
	v_mfma_f32_16x16x32_bf16 v[24:27], v[156:159], v[196:199], 0
	v_mfma_f32_16x16x32_bf16 v[12:15], v[148:151], v[204:207], 0
	v_mfma_f32_16x16x32_bf16 v[8:11], v[156:159], v[204:207], 0
	v_mfma_f32_16x16x32_bf16 v[60:63], v[152:155], v[184:187], v[60:63]
	v_mfma_f32_16x16x32_bf16 v[56:59], v[160:163], v[184:187], v[56:59]
	v_mfma_f32_16x16x32_bf16 v[44:47], v[152:155], v[192:195], v[44:47]
	v_mfma_f32_16x16x32_bf16 v[40:43], v[160:163], v[192:195], v[40:43]
	v_mfma_f32_16x16x32_bf16 v[28:31], v[152:155], v[200:203], v[28:31]
	v_mfma_f32_16x16x32_bf16 v[24:27], v[160:163], v[200:203], v[24:27]
	v_mfma_f32_16x16x32_bf16 v[12:15], v[152:155], v[208:211], v[12:15]
	v_mfma_f32_16x16x32_bf16 v[8:11], v[160:163], v[208:211], v[8:11]
	v_mfma_f32_16x16x32_bf16 v[52:55], v[164:167], v[180:183], 0
	v_mfma_f32_16x16x32_bf16 v[48:51], v[172:175], v[180:183], 0
	v_mfma_f32_16x16x32_bf16 v[36:39], v[164:167], v[188:191], 0
	v_mfma_f32_16x16x32_bf16 v[32:35], v[172:175], v[188:191], 0
	v_mfma_f32_16x16x32_bf16 v[20:23], v[164:167], v[196:199], 0
	v_mfma_f32_16x16x32_bf16 v[16:19], v[172:175], v[196:199], 0
	v_mfma_f32_16x16x32_bf16 v[4:7], v[164:167], v[204:207], 0
	v_mfma_f32_16x16x32_bf16 v[0:3], v[172:175], v[204:207], 0
	v_mfma_f32_16x16x32_bf16 v[52:55], v[168:171], v[184:187], v[52:55]
	v_mfma_f32_16x16x32_bf16 v[48:51], v[176:179], v[184:187], v[48:51]
	v_mfma_f32_16x16x32_bf16 v[36:39], v[168:171], v[192:195], v[36:39]
	v_mfma_f32_16x16x32_bf16 v[32:35], v[176:179], v[192:195], v[32:35]
	v_mfma_f32_16x16x32_bf16 v[20:23], v[168:171], v[200:203], v[20:23]
	v_mfma_f32_16x16x32_bf16 v[16:19], v[176:179], v[200:203], v[16:19]
	v_mfma_f32_16x16x32_bf16 v[4:7], v[168:171], v[208:211], v[4:7]
	v_mfma_f32_16x16x32_bf16 v[0:3], v[176:179], v[208:211], v[0:3]
	s_barrier
; #define PG8_STAGE(bufoff, gbase, voff) do { _Pragma("unroll") for (int _i = 0; _i < 2; ++_i) \
;         __builtin_amdgcn_global_load_lds((const unsigned*)((const char*)(gbase) + (voff)[_i]), (LAS unsigned*)(lds + (bufoff) + ldsw + _i * 8192), 16, 0, 0); } while (0)
; #define PG8_LDA(dst, b, h) do { _Pragma("unroll") for (int m = 0; m < 4; ++m) _Pragma("unroll") for (int k = 0; k < 2; ++k) dst[m][k] = *(const LAS bf16x8*)(lds + PG8_SA(b, h) + aoff + m * 2048 + k * 1024); } while (0)
; #define PG8_LDB(dst, b, h) do { _Pragma("unroll") for (int n = 0; n < 2; ++n) _Pragma("unroll") for (int k = 0; k < 2; ++k) dst[n][k] = *(const LAS bf16x8*)(lds + PG8_SB(b, h) + boff + n * 2048 + k * 1024); } while (0)
; #define PG8_MMA(ai, bj, At, Bt) do { __builtin_amdgcn_s_setprio(1); _Pragma("unroll") for (int m = 0; m < 4; ++m) _Pragma("unroll") for (int n = 0; n < 2; ++n) _Pragma("unroll") for (int k = 0; k < 2; ++k) \
;         acc[ai][bj][m][n] = __builtin_amdgcn_mfma_f32_16x16x32_bf16(Bt[n][k], At[m][k], acc[ai][bj][m][n], 0, 0, 0); __builtin_amdgcn_s_setprio(0); } while (0)
; #define PG8_WAIT_V(n) asm volatile("s_waitcnt vmcnt(" #n ")" ::: "memory")
; #define PG8_WAIT_L(n) asm volatile("s_waitcnt lgkmcnt(" #n ")" ::: "memory")
; #define PG8_BAR __builtin_amdgcn_s_barrier()
; #define PG8_SCHED __builtin_amdgcn_sched_barrier(0)
; template <class Epi, bool ALIGN_EPI, int K, int LDA, int LDB>
; __device__ __forceinline__ void gemm_phase(LAS unsigned char* lds, const int wid, const Gemm g, const StaticOrder& S, const Epi& E) {
;     ...
;             PG8_LDB(B0, 1, 0); PG8_LDB(B1, 1, 1); PG8_SCHED; PG8_LDA(At, 1, 0); PG8_STAGE(PG8_SA(0, 1), a2 + hA, voffA);
;             PG8_WAIT_V(8); PG8_WAIT_L(0); PG8_BAR; PG8_MMA(0, 0, At, B0); PG8_MMA(0, 1, At, B1); PG8_BAR; PG8_SCHED;
;             PG8_LDA(At, 1, 1); PG8_STAGE(PG8_SB(1, 0), b3, voffB); PG8_STAGE(PG8_SB(1, 1), b3 + hB, voffB); PG8_STAGE(PG8_SA(1, 0), a3, voffA);
;             PG8_WAIT_V(8); PG8_WAIT_L(0); PG8_BAR; PG8_MMA(1, 0, At, B0); PG8_MMA(1, 1, At, B1); PG8_BAR; PG8_SCHED;
	s_add_i32 s52, 0, 0x18000
	s_add_i32 s53, 0, 0x1c000
	v_add_u32_e32 v160, s52, v144
	v_add_u32_e32 v176, s53, v144
	ds_read_b128 v[148:151], v160
	ds_read_b128 v[152:155], v160 offset:1024
	ds_read_b128 v[156:159], v160 offset:2048
	ds_read_b128 v[160:163], v160 offset:3072
	ds_read_b128 v[164:167], v176
	ds_read_b128 v[168:171], v176 offset:1024
	ds_read_b128 v[172:175], v176 offset:2048
	ds_read_b128 v[176:179], v176 offset:3072
	s_add_u32 s26, s26, 0x40000
	s_addc_u32 s27, s27, 0
	s_mov_b32 m0, s31
	ds_read_b128 v[180:183], v147 offset:32768
	ds_read_b128 v[184:187], v147 offset:33792
	ds_read_b128 v[188:191], v147 offset:34816
	ds_read_b128 v[192:195], v147 offset:35840
	ds_read_b128 v[196:199], v147 offset:36864
	ds_read_b128 v[200:203], v147 offset:37888
	ds_read_b128 v[204:207], v147 offset:38912
	ds_read_b128 v[208:211], v147 offset:39936
	global_load_lds_dwordx4 v134, s[26:27]
	s_mov_b32 m0, s33
	s_nop 0
	global_load_lds_dwordx4 v130, s[26:27]
	s_waitcnt vmcnt(8)
	s_barrier
	s_waitcnt lgkmcnt(0)
	v_mfma_f32_16x16x32_bf16 v[124:127], v[148:151], v[180:183], v[124:127]
	v_mfma_f32_16x16x32_bf16 v[120:123], v[156:159], v[180:183], v[120:123]
	v_mfma_f32_16x16x32_bf16 v[108:111], v[148:151], v[188:191], v[108:111]
	v_mfma_f32_16x16x32_bf16 v[104:107], v[156:159], v[188:191], v[104:107]
	v_mfma_f32_16x16x32_bf16 v[92:95], v[148:151], v[196:199], v[92:95]
	v_mfma_f32_16x16x32_bf16 v[88:91], v[156:159], v[196:199], v[88:91]
	v_mfma_f32_16x16x32_bf16 v[76:79], v[148:151], v[204:207], v[76:79]
	v_mfma_f32_16x16x32_bf16 v[72:75], v[156:159], v[204:207], v[72:75]
	v_mfma_f32_16x16x32_bf16 v[124:127], v[152:155], v[184:187], v[124:127]
	v_mfma_f32_16x16x32_bf16 v[120:123], v[160:163], v[184:187], v[120:123]
	v_mfma_f32_16x16x32_bf16 v[108:111], v[152:155], v[192:195], v[108:111]
	v_mfma_f32_16x16x32_bf16 v[104:107], v[160:163], v[192:195], v[104:107]
	v_mfma_f32_16x16x32_bf16 v[92:95], v[152:155], v[200:203], v[92:95]
	v_mfma_f32_16x16x32_bf16 v[88:91], v[160:163], v[200:203], v[88:91]
	v_mfma_f32_16x16x32_bf16 v[76:79], v[152:155], v[208:211], v[76:79]
	v_mfma_f32_16x16x32_bf16 v[72:75], v[160:163], v[208:211], v[72:75]
	v_mfma_f32_16x16x32_bf16 v[116:119], v[164:167], v[180:183], v[116:119]
	v_mfma_f32_16x16x32_bf16 v[112:115], v[172:175], v[180:183], v[112:115]
	v_mfma_f32_16x16x32_bf16 v[100:103], v[164:167], v[188:191], v[100:103]
	v_mfma_f32_16x16x32_bf16 v[96:99], v[172:175], v[188:191], v[96:99]
	v_mfma_f32_16x16x32_bf16 v[84:87], v[164:167], v[196:199], v[84:87]
	v_mfma_f32_16x16x32_bf16 v[80:83], v[172:175], v[196:199], v[80:83]
	v_mfma_f32_16x16x32_bf16 v[68:71], v[164:167], v[204:207], v[68:71]
	v_mfma_f32_16x16x32_bf16 v[64:67], v[172:175], v[204:207], v[64:67]
	v_mfma_f32_16x16x32_bf16 v[116:119], v[168:171], v[184:187], v[116:119]
	v_mfma_f32_16x16x32_bf16 v[112:115], v[176:179], v[184:187], v[112:115]
	v_mfma_f32_16x16x32_bf16 v[100:103], v[168:171], v[192:195], v[100:103]
	v_mfma_f32_16x16x32_bf16 v[96:99], v[176:179], v[192:195], v[96:99]
	v_mfma_f32_16x16x32_bf16 v[84:87], v[168:171], v[200:203], v[84:87]
	v_mfma_f32_16x16x32_bf16 v[80:83], v[176:179], v[200:203], v[80:83]
	v_mfma_f32_16x16x32_bf16 v[68:71], v[168:171], v[208:211], v[68:71]
	v_mfma_f32_16x16x32_bf16 v[64:67], v[176:179], v[208:211], v[64:67]
	s_barrier
	s_add_i32 s26, s52, s3
	s_mov_b32 m0, s26
	ds_read_b128 v[180:183], v147 offset:49152
	ds_read_b128 v[184:187], v147 offset:50176
	ds_read_b128 v[188:191], v147 offset:51200
	ds_read_b128 v[192:195], v147 offset:52224
	ds_read_b128 v[196:199], v147 offset:53248
	ds_read_b128 v[200:203], v147 offset:54272
	ds_read_b128 v[204:207], v147 offset:55296
	ds_read_b128 v[208:211], v147 offset:56320
	global_load_lds_dwordx4 v132, s[98:99]
	s_add_i32 m0, s26, 0x2000
	s_add_u32 s24, s24, 0x40080
	s_addc_u32 s25, s25, 0
	s_add_i32 s26, s53, s3
	global_load_lds_dwordx4 v128, s[98:99]
	s_mov_b32 m0, s26
	s_nop 0
	global_load_lds_dwordx4 v132, s[24:25]
	s_add_i32 m0, s26, 0x2000
	s_nop 0
	global_load_lds_dwordx4 v128, s[24:25]
	s_mov_b32 m0, s38
	s_nop 0
	global_load_lds_dwordx4 v134, s[100:101]
	s_mov_b32 m0, s39
	s_nop 0
	global_load_lds_dwordx4 v130, s[100:101]
	s_waitcnt vmcnt(8)
	s_barrier
	s_waitcnt lgkmcnt(0)
	v_mfma_f32_16x16x32_bf16 v[60:63], v[148:151], v[180:183], v[60:63]
	v_mfma_f32_16x16x32_bf16 v[56:59], v[156:159], v[180:183], v[56:59]
	v_mfma_f32_16x16x32_bf16 v[44:47], v[148:151], v[188:191], v[44:47]
	v_mfma_f32_16x16x32_bf16 v[40:43], v[156:159], v[188:191], v[40:43]
	v_mfma_f32_16x16x32_bf16 v[28:31], v[148:151], v[196:199], v[28:31]
	v_mfma_f32_16x16x32_bf16 v[24:27], v[156:159], v[196:199], v[24:27]
	v_mfma_f32_16x16x32_bf16 v[12:15], v[148:151], v[204:207], v[12:15]
	v_mfma_f32_16x16x32_bf16 v[8:11], v[156:159], v[204:207], v[8:11]
	v_mfma_f32_16x16x32_bf16 v[60:63], v[152:155], v[184:187], v[60:63]
	v_mfma_f32_16x16x32_bf16 v[56:59], v[160:163], v[184:187], v[56:59]
	v_mfma_f32_16x16x32_bf16 v[44:47], v[152:155], v[192:195], v[44:47]
	v_mfma_f32_16x16x32_bf16 v[40:43], v[160:163], v[192:195], v[40:43]
	v_mfma_f32_16x16x32_bf16 v[28:31], v[152:155], v[200:203], v[28:31]
	v_mfma_f32_16x16x32_bf16 v[24:27], v[160:163], v[200:203], v[24:27]
	v_mfma_f32_16x16x32_bf16 v[12:15], v[152:155], v[208:211], v[12:15]
	v_mfma_f32_16x16x32_bf16 v[8:11], v[160:163], v[208:211], v[8:11]
	v_mfma_f32_16x16x32_bf16 v[52:55], v[164:167], v[180:183], v[52:55]
	v_mfma_f32_16x16x32_bf16 v[48:51], v[172:175], v[180:183], v[48:51]
	v_mfma_f32_16x16x32_bf16 v[36:39], v[164:167], v[188:191], v[36:39]
	v_mfma_f32_16x16x32_bf16 v[32:35], v[172:175], v[188:191], v[32:35]
	v_mfma_f32_16x16x32_bf16 v[20:23], v[164:167], v[196:199], v[20:23]
	v_mfma_f32_16x16x32_bf16 v[16:19], v[172:175], v[196:199], v[16:19]
	v_mfma_f32_16x16x32_bf16 v[4:7], v[164:167], v[204:207], v[4:7]
	v_mfma_f32_16x16x32_bf16 v[0:3], v[172:175], v[204:207], v[0:3]
	v_mfma_f32_16x16x32_bf16 v[52:55], v[168:171], v[184:187], v[52:55]
	v_mfma_f32_16x16x32_bf16 v[48:51], v[176:179], v[184:187], v[48:51]
	v_mfma_f32_16x16x32_bf16 v[36:39], v[168:171], v[192:195], v[36:39]
	v_mfma_f32_16x16x32_bf16 v[32:35], v[176:179], v[192:195], v[32:35]
	v_mfma_f32_16x16x32_bf16 v[20:23], v[168:171], v[200:203], v[20:23]
	v_mfma_f32_16x16x32_bf16 v[16:19], v[176:179], v[200:203], v[16:19]
	v_mfma_f32_16x16x32_bf16 v[4:7], v[168:171], v[208:211], v[4:7]
	v_mfma_f32_16x16x32_bf16 v[0:3], v[176:179], v[208:211], v[0:3]
	s_barrier
	s_add_i32 s55, s55, 2
	s_add_u32 s22, s22, 0x100
	s_addc_u32 s23, s23, 0
	s_add_u32 s51, s51, 0x100
	s_addc_u32 s54, s54, 0
; #define PG8_STAGE(bufoff, gbase, voff) do { _Pragma("unroll") for (int _i = 0; _i < 2; ++_i) \
;         __builtin_amdgcn_global_load_lds((const unsigned*)((const char*)(gbase) + (voff)[_i]), (LAS unsigned*)(lds + (bufoff) + ldsw + _i * 8192), 16, 0, 0); } while (0)
; #define PG8_LDA(dst, b, h) do { _Pragma("unroll") for (int m = 0; m < 4; ++m) _Pragma("unroll") for (int k = 0; k < 2; ++k) dst[m][k] = *(const LAS bf16x8*)(lds + PG8_SA(b, h) + aoff + m * 2048 + k * 1024); } while (0)
; #define PG8_LDB(dst, b, h) do { _Pragma("unroll") for (int n = 0; n < 2; ++n) _Pragma("unroll") for (int k = 0; k < 2; ++k) dst[n][k] = *(const LAS bf16x8*)(lds + PG8_SB(b, h) + boff + n * 2048 + k * 1024); } while (0)
; #define PG8_MMA(ai, bj, At, Bt) do { __builtin_amdgcn_s_setprio(1); _Pragma("unroll") for (int m = 0; m < 4; ++m) _Pragma("unroll") for (int n = 0; n < 2; ++n) _Pragma("unroll") for (int k = 0; k < 2; ++k) \
;         acc[ai][bj][m][n] = __builtin_amdgcn_mfma_f32_16x16x32_bf16(Bt[n][k], At[m][k], acc[ai][bj][m][n], 0, 0, 0); __builtin_amdgcn_s_setprio(0); } while (0)
; #define PG8_WAIT_V(n) asm volatile("s_waitcnt vmcnt(" #n ")" ::: "memory")
; #define PG8_WAIT_L(n) asm volatile("s_waitcnt lgkmcnt(" #n ")" ::: "memory")
; #define PG8_BAR __builtin_amdgcn_s_barrier()
; template <class Epi, bool ALIGN_EPI, int K, int LDA, int LDB>
; __device__ __forceinline__ void gemm_phase(LAS unsigned char* lds, const int wid, const Gemm g, const StaticOrder& S, const Epi& E) {
;     ...
;         for (int t = 0; t < nt; t += 2) {
;             const bool last = (t == nt - 2);
;             const char* a1 = cA + (size_t)(t + 1) * kstep;
;             const char* a2 = last ? nA : cA + (size_t)(t + 2) * kstep; const char* b2 = last ? nB : cB + (size_t)(t + 2) * kstep;
;             const char* a3 = a2 + kstep; const char* b3 = b2 + kstep;
;             PG8_LDB(B0, 0, 0); PG8_LDB(B1, 0, 1); PG8_SCHED; PG8_LDA(At, 0, 0); PG8_STAGE(PG8_SA(1, 1), a1 + hA, voffA);
;             PG8_WAIT_V(8); PG8_WAIT_L(0); PG8_BAR; PG8_MMA(0, 0, At, B0); PG8_MMA(0, 1, At, B1); PG8_BAR; PG8_SCHED;
;             PG8_LDA(At, 0, 1); PG8_STAGE(PG8_SB(0, 0), b2, voffB); PG8_STAGE(PG8_SB(0, 1), b2 + hB, voffB); PG8_STAGE(PG8_SA(0, 0), a2, voffA);
;             PG8_WAIT_V(8); PG8_WAIT_L(0); PG8_BAR; PG8_MMA(1, 0, At, B0); PG8_MMA(1, 1, At, B1); PG8_BAR; PG8_SCHED;
.LBB0_1052:
	ds_read_b128 v[148:151], v145
	ds_read_b128 v[152:155], v145 offset:1024
	ds_read_b128 v[156:159], v145 offset:2048
	ds_read_b128 v[160:163], v145 offset:3072
	ds_read_b128 v[164:167], v146
	ds_read_b128 v[168:171], v146 offset:1024
	ds_read_b128 v[172:175], v146 offset:2048
	ds_read_b128 v[176:179], v146 offset:3072
	s_add_u32 s24, s22, 0xfffc0080
	s_addc_u32 s25, s23, -1
	s_cmp_eq_u32 s55, 12
	s_cselect_b32 s27, s15, s25
	s_cselect_b32 s26, s48, s24
	s_cselect_b32 s25, s13, s54
	s_cselect_b32 s24, s49, s51
	s_add_i32 m0, s21, 0xc000
	ds_read_b128 v[180:183], v147
	ds_read_b128 v[184:187], v147 offset:1024
	ds_read_b128 v[188:191], v147 offset:2048
	ds_read_b128 v[192:195], v147 offset:3072
	ds_read_b128 v[196:199], v147 offset:4096
	ds_read_b128 v[200:203], v147 offset:5120
	ds_read_b128 v[204:207], v147 offset:6144
	ds_read_b128 v[208:211], v147 offset:7168
	global_load_lds_dwordx4 v136, s[22:23]
	s_add_i32 m0, s21, 0xe000
	s_nop 0
	global_load_lds_dwordx4 v138, s[22:23]
	s_waitcnt vmcnt(8)
	s_barrier
	s_waitcnt lgkmcnt(0)
	v_mfma_f32_16x16x32_bf16 v[124:127], v[148:151], v[180:183], v[124:127]
	v_mfma_f32_16x16x32_bf16 v[120:123], v[156:159], v[180:183], v[120:123]
	v_mfma_f32_16x16x32_bf16 v[108:111], v[148:151], v[188:191], v[108:111]
	v_mfma_f32_16x16x32_bf16 v[104:107], v[156:159], v[188:191], v[104:107]
	v_mfma_f32_16x16x32_bf16 v[92:95], v[148:151], v[196:199], v[92:95]
	v_mfma_f32_16x16x32_bf16 v[88:91], v[156:159], v[196:199], v[88:91]
	v_mfma_f32_16x16x32_bf16 v[76:79], v[148:151], v[204:207], v[76:79]
	v_mfma_f32_16x16x32_bf16 v[72:75], v[156:159], v[204:207], v[72:75]
	v_mfma_f32_16x16x32_bf16 v[124:127], v[152:155], v[184:187], v[124:127]
	v_mfma_f32_16x16x32_bf16 v[120:123], v[160:163], v[184:187], v[120:123]
	v_mfma_f32_16x16x32_bf16 v[108:111], v[152:155], v[192:195], v[108:111]
	v_mfma_f32_16x16x32_bf16 v[104:107], v[160:163], v[192:195], v[104:107]
	v_mfma_f32_16x16x32_bf16 v[92:95], v[152:155], v[200:203], v[92:95]
	v_mfma_f32_16x16x32_bf16 v[88:91], v[160:163], v[200:203], v[88:91]
	v_mfma_f32_16x16x32_bf16 v[76:79], v[152:155], v[208:211], v[76:79]
	v_mfma_f32_16x16x32_bf16 v[72:75], v[160:163], v[208:211], v[72:75]
	v_mfma_f32_16x16x32_bf16 v[116:119], v[164:167], v[180:183], v[116:119]
	v_mfma_f32_16x16x32_bf16 v[112:115], v[172:175], v[180:183], v[112:115]
	v_mfma_f32_16x16x32_bf16 v[100:103], v[164:167], v[188:191], v[100:103]
	v_mfma_f32_16x16x32_bf16 v[96:99], v[172:175], v[188:191], v[96:99]
	v_mfma_f32_16x16x32_bf16 v[84:87], v[164:167], v[196:199], v[84:87]
	v_mfma_f32_16x16x32_bf16 v[80:83], v[172:175], v[196:199], v[80:83]
	v_mfma_f32_16x16x32_bf16 v[68:71], v[164:167], v[204:207], v[68:71]
	v_mfma_f32_16x16x32_bf16 v[64:67], v[172:175], v[204:207], v[64:67]
	v_mfma_f32_16x16x32_bf16 v[116:119], v[168:171], v[184:187], v[116:119]
	v_mfma_f32_16x16x32_bf16 v[112:115], v[176:179], v[184:187], v[112:115]
	v_mfma_f32_16x16x32_bf16 v[100:103], v[168:171], v[192:195], v[100:103]
	v_mfma_f32_16x16x32_bf16 v[96:99], v[176:179], v[192:195], v[96:99]
	v_mfma_f32_16x16x32_bf16 v[84:87], v[168:171], v[200:203], v[84:87]
	v_mfma_f32_16x16x32_bf16 v[80:83], v[176:179], v[200:203], v[80:83]
	v_mfma_f32_16x16x32_bf16 v[68:71], v[168:171], v[208:211], v[68:71]
	v_mfma_f32_16x16x32_bf16 v[64:67], v[176:179], v[208:211], v[64:67]
	s_barrier
	s_add_u32 s98, s24, s10
	s_addc_u32 s99, s25, s11
	s_add_u32 s100, s26, s10
	s_addc_u32 s101, s27, s11
	s_add_i32 s52, s40, s3
	s_mov_b32 m0, s52
	ds_read_b128 v[180:183], v147 offset:16384
	ds_read_b128 v[184:187], v147 offset:17408
	ds_read_b128 v[188:191], v147 offset:18432
	ds_read_b128 v[192:195], v147 offset:19456
	ds_read_b128 v[196:199], v147 offset:20480
	ds_read_b128 v[200:203], v147 offset:21504
	ds_read_b128 v[204:207], v147 offset:22528
	ds_read_b128 v[208:211], v147 offset:23552
	global_load_lds_dwordx4 v132, s[24:25]
	s_add_i32 m0, s52, 0x2000
	s_add_u32 s56, s24, 0x40000
	s_addc_u32 s57, s25, 0
	s_add_i32 s52, s41, s3
	global_load_lds_dwordx4 v128, s[24:25]
	s_mov_b32 m0, s52
	s_nop 0
	global_load_lds_dwordx4 v132, s[56:57]
	s_add_i32 m0, s52, 0x2000
	s_nop 0
	global_load_lds_dwordx4 v128, s[56:57]
	s_mov_b32 m0, s21
	s_nop 0
	global_load_lds_dwordx4 v134, s[26:27]
	s_mov_b32 m0, s30
	s_nop 0
	global_load_lds_dwordx4 v130, s[26:27]
	s_waitcnt vmcnt(8)
	s_barrier
	s_waitcnt lgkmcnt(0)
	v_mfma_f32_16x16x32_bf16 v[60:63], v[148:151], v[180:183], v[60:63]
	v_mfma_f32_16x16x32_bf16 v[56:59], v[156:159], v[180:183], v[56:59]
	v_mfma_f32_16x16x32_bf16 v[44:47], v[148:151], v[188:191], v[44:47]
	v_mfma_f32_16x16x32_bf16 v[40:43], v[156:159], v[188:191], v[40:43]
	v_mfma_f32_16x16x32_bf16 v[28:31], v[148:151], v[196:199], v[28:31]
	v_mfma_f32_16x16x32_bf16 v[24:27], v[156:159], v[196:199], v[24:27]
	v_mfma_f32_16x16x32_bf16 v[12:15], v[148:151], v[204:207], v[12:15]
	v_mfma_f32_16x16x32_bf16 v[8:11], v[156:159], v[204:207], v[8:11]
	v_mfma_f32_16x16x32_bf16 v[60:63], v[152:155], v[184:187], v[60:63]
	v_mfma_f32_16x16x32_bf16 v[56:59], v[160:163], v[184:187], v[56:59]
	v_mfma_f32_16x16x32_bf16 v[44:47], v[152:155], v[192:195], v[44:47]
	v_mfma_f32_16x16x32_bf16 v[40:43], v[160:163], v[192:195], v[40:43]
	v_mfma_f32_16x16x32_bf16 v[28:31], v[152:155], v[200:203], v[28:31]
	v_mfma_f32_16x16x32_bf16 v[24:27], v[160:163], v[200:203], v[24:27]
	v_mfma_f32_16x16x32_bf16 v[12:15], v[152:155], v[208:211], v[12:15]
	v_mfma_f32_16x16x32_bf16 v[8:11], v[160:163], v[208:211], v[8:11]
	v_mfma_f32_16x16x32_bf16 v[52:55], v[164:167], v[180:183], v[52:55]
	v_mfma_f32_16x16x32_bf16 v[48:51], v[172:175], v[180:183], v[48:51]
	v_mfma_f32_16x16x32_bf16 v[36:39], v[164:167], v[188:191], v[36:39]
	v_mfma_f32_16x16x32_bf16 v[32:35], v[172:175], v[188:191], v[32:35]
	v_mfma_f32_16x16x32_bf16 v[20:23], v[164:167], v[196:199], v[20:23]
	v_mfma_f32_16x16x32_bf16 v[16:19], v[172:175], v[196:199], v[16:19]
	v_mfma_f32_16x16x32_bf16 v[4:7], v[164:167], v[204:207], v[4:7]
	v_mfma_f32_16x16x32_bf16 v[0:3], v[172:175], v[204:207], v[0:3]
	v_mfma_f32_16x16x32_bf16 v[52:55], v[168:171], v[184:187], v[52:55]
	v_mfma_f32_16x16x32_bf16 v[48:51], v[176:179], v[184:187], v[48:51]
	v_mfma_f32_16x16x32_bf16 v[36:39], v[168:171], v[192:195], v[36:39]
	v_mfma_f32_16x16x32_bf16 v[32:35], v[176:179], v[192:195], v[32:35]
	v_mfma_f32_16x16x32_bf16 v[20:23], v[168:171], v[200:203], v[20:23]
	v_mfma_f32_16x16x32_bf16 v[16:19], v[176:179], v[200:203], v[16:19]
	v_mfma_f32_16x16x32_bf16 v[4:7], v[168:171], v[208:211], v[4:7]
	v_mfma_f32_16x16x32_bf16 v[0:3], v[176:179], v[208:211], v[0:3]
	s_barrier
; #define PG8_STAGE(bufoff, gbase, voff) do { _Pragma("unroll") for (int _i = 0; _i < 2; ++_i) \
;         __builtin_amdgcn_global_load_lds((const unsigned*)((const char*)(gbase) + (voff)[_i]), (LAS unsigned*)(lds + (bufoff) + ldsw + _i * 8192), 16, 0, 0); } while (0)
; #define PG8_LDA(dst, b, h) do { _Pragma("unroll") for (int m = 0; m < 4; ++m) _Pragma("unroll") for (int k = 0; k < 2; ++k) dst[m][k] = *(const LAS bf16x8*)(lds + PG8_SA(b, h) + aoff + m * 2048 + k * 1024); } while (0)
; #define PG8_LDB(dst, b, h) do { _Pragma("unroll") for (int n = 0; n < 2; ++n) _Pragma("unroll") for (int k = 0; k < 2; ++k) dst[n][k] = *(const LAS bf16x8*)(lds + PG8_SB(b, h) + boff + n * 2048 + k * 1024); } while (0)
; #define PG8_MMA(ai, bj, At, Bt) do { __builtin_amdgcn_s_setprio(1); _Pragma("unroll") for (int m = 0; m < 4; ++m) _Pragma("unroll") for (int n = 0; n < 2; ++n) _Pragma("unroll") for (int k = 0; k < 2; ++k) \
;         acc[ai][bj][m][n] = __builtin_amdgcn_mfma_f32_16x16x32_bf16(Bt[n][k], At[m][k], acc[ai][bj][m][n], 0, 0, 0); __builtin_amdgcn_s_setprio(0); } while (0)
; #define PG8_WAIT_V(n) asm volatile("s_waitcnt vmcnt(" #n ")" ::: "memory")
; #define PG8_WAIT_L(n) asm volatile("s_waitcnt lgkmcnt(" #n ")" ::: "memory")
; #define PG8_BAR __builtin_amdgcn_s_barrier()
; #define PG8_SCHED __builtin_amdgcn_sched_barrier(0)
; template <class Epi, bool ALIGN_EPI, int K, int LDA, int LDB>
; __device__ __forceinline__ void gemm_phase(LAS unsigned char* lds, const int wid, const Gemm g, const StaticOrder& S, const Epi& E) {
;     ...
;             PG8_LDB(B0, 1, 0); PG8_LDB(B1, 1, 1); PG8_SCHED; PG8_LDA(At, 1, 0); PG8_STAGE(PG8_SA(0, 1), a2 + hA, voffA);
;             PG8_WAIT_V(8); PG8_WAIT_L(0); PG8_BAR; PG8_MMA(0, 0, At, B0); PG8_MMA(0, 1, At, B1); PG8_BAR; PG8_SCHED;
;             PG8_LDA(At, 1, 1); PG8_STAGE(PG8_SB(1, 0), b3, voffB); PG8_STAGE(PG8_SB(1, 1), b3 + hB, voffB); PG8_STAGE(PG8_SA(1, 0), a3, voffA);
;             PG8_WAIT_V(8); PG8_WAIT_L(0); PG8_BAR; PG8_MMA(1, 0, At, B0); PG8_MMA(1, 1, At, B1); PG8_BAR; PG8_SCHED;
;         }
;         if constexpr (ALIGN_EPI) { if (wr == 0) PG8_BAR; }
	s_add_i32 s52, 0, 0x18000
	s_add_i32 s53, 0, 0x1c000
	v_add_u32_e32 v160, s52, v144
	v_add_u32_e32 v176, s53, v144
	ds_read_b128 v[148:151], v160
	ds_read_b128 v[152:155], v160 offset:1024
	ds_read_b128 v[156:159], v160 offset:2048
	ds_read_b128 v[160:163], v160 offset:3072
	ds_read_b128 v[164:167], v176
	ds_read_b128 v[168:171], v176 offset:1024
	ds_read_b128 v[172:175], v176 offset:2048
	ds_read_b128 v[176:179], v176 offset:3072
	s_add_u32 s26, s26, 0x40000
	s_addc_u32 s27, s27, 0
	s_mov_b32 m0, s31
	ds_read_b128 v[180:183], v147 offset:32768
	ds_read_b128 v[184:187], v147 offset:33792
	ds_read_b128 v[188:191], v147 offset:34816
	ds_read_b128 v[192:195], v147 offset:35840
	ds_read_b128 v[196:199], v147 offset:36864
	ds_read_b128 v[200:203], v147 offset:37888
	ds_read_b128 v[204:207], v147 offset:38912
	ds_read_b128 v[208:211], v147 offset:39936
	global_load_lds_dwordx4 v134, s[26:27]
	s_mov_b32 m0, s33
	s_nop 0
	global_load_lds_dwordx4 v130, s[26:27]
	s_waitcnt vmcnt(8)
	s_barrier
	s_waitcnt lgkmcnt(0)
	v_mfma_f32_16x16x32_bf16 v[124:127], v[148:151], v[180:183], v[124:127]
	v_mfma_f32_16x16x32_bf16 v[120:123], v[156:159], v[180:183], v[120:123]
	v_mfma_f32_16x16x32_bf16 v[108:111], v[148:151], v[188:191], v[108:111]
	v_mfma_f32_16x16x32_bf16 v[104:107], v[156:159], v[188:191], v[104:107]
	v_mfma_f32_16x16x32_bf16 v[92:95], v[148:151], v[196:199], v[92:95]
	v_mfma_f32_16x16x32_bf16 v[88:91], v[156:159], v[196:199], v[88:91]
	v_mfma_f32_16x16x32_bf16 v[76:79], v[148:151], v[204:207], v[76:79]
	v_mfma_f32_16x16x32_bf16 v[72:75], v[156:159], v[204:207], v[72:75]
	v_mfma_f32_16x16x32_bf16 v[124:127], v[152:155], v[184:187], v[124:127]
	v_mfma_f32_16x16x32_bf16 v[120:123], v[160:163], v[184:187], v[120:123]
	v_mfma_f32_16x16x32_bf16 v[108:111], v[152:155], v[192:195], v[108:111]
	v_mfma_f32_16x16x32_bf16 v[104:107], v[160:163], v[192:195], v[104:107]
	v_mfma_f32_16x16x32_bf16 v[92:95], v[152:155], v[200:203], v[92:95]
	v_mfma_f32_16x16x32_bf16 v[88:91], v[160:163], v[200:203], v[88:91]
	v_mfma_f32_16x16x32_bf16 v[76:79], v[152:155], v[208:211], v[76:79]
	v_mfma_f32_16x16x32_bf16 v[72:75], v[160:163], v[208:211], v[72:75]
	v_mfma_f32_16x16x32_bf16 v[116:119], v[164:167], v[180:183], v[116:119]
	v_mfma_f32_16x16x32_bf16 v[112:115], v[172:175], v[180:183], v[112:115]
	v_mfma_f32_16x16x32_bf16 v[100:103], v[164:167], v[188:191], v[100:103]
	v_mfma_f32_16x16x32_bf16 v[96:99], v[172:175], v[188:191], v[96:99]
	v_mfma_f32_16x16x32_bf16 v[84:87], v[164:167], v[196:199], v[84:87]
	v_mfma_f32_16x16x32_bf16 v[80:83], v[172:175], v[196:199], v[80:83]
	v_mfma_f32_16x16x32_bf16 v[68:71], v[164:167], v[204:207], v[68:71]
	v_mfma_f32_16x16x32_bf16 v[64:67], v[172:175], v[204:207], v[64:67]
	v_mfma_f32_16x16x32_bf16 v[116:119], v[168:171], v[184:187], v[116:119]
	v_mfma_f32_16x16x32_bf16 v[112:115], v[176:179], v[184:187], v[112:115]
	v_mfma_f32_16x16x32_bf16 v[100:103], v[168:171], v[192:195], v[100:103]
	v_mfma_f32_16x16x32_bf16 v[96:99], v[176:179], v[192:195], v[96:99]
	v_mfma_f32_16x16x32_bf16 v[84:87], v[168:171], v[200:203], v[84:87]
	v_mfma_f32_16x16x32_bf16 v[80:83], v[176:179], v[200:203], v[80:83]
	v_mfma_f32_16x16x32_bf16 v[68:71], v[168:171], v[208:211], v[68:71]
	v_mfma_f32_16x16x32_bf16 v[64:67], v[176:179], v[208:211], v[64:67]
	s_barrier
	s_add_i32 s26, s52, s3
	s_mov_b32 m0, s26
	ds_read_b128 v[180:183], v147 offset:49152
	ds_read_b128 v[184:187], v147 offset:50176
	ds_read_b128 v[188:191], v147 offset:51200
	ds_read_b128 v[192:195], v147 offset:52224
	ds_read_b128 v[196:199], v147 offset:53248
	ds_read_b128 v[200:203], v147 offset:54272
	ds_read_b128 v[204:207], v147 offset:55296
	ds_read_b128 v[208:211], v147 offset:56320
	global_load_lds_dwordx4 v132, s[98:99]
	s_add_i32 m0, s26, 0x2000
	s_add_u32 s24, s24, 0x40080
	s_addc_u32 s25, s25, 0
	s_add_i32 s26, s53, s3
	global_load_lds_dwordx4 v128, s[98:99]
	s_mov_b32 m0, s26
	s_nop 0
	global_load_lds_dwordx4 v132, s[24:25]
	s_add_i32 m0, s26, 0x2000
	s_nop 0
	global_load_lds_dwordx4 v128, s[24:25]
	s_mov_b32 m0, s38
	s_nop 0
	global_load_lds_dwordx4 v134, s[100:101]
	s_mov_b32 m0, s39
	s_nop 0
	global_load_lds_dwordx4 v130, s[100:101]
	s_waitcnt vmcnt(8)
	s_barrier
	s_waitcnt lgkmcnt(0)
	v_mfma_f32_16x16x32_bf16 v[60:63], v[148:151], v[180:183], v[60:63]
	v_mfma_f32_16x16x32_bf16 v[56:59], v[156:159], v[180:183], v[56:59]
	v_mfma_f32_16x16x32_bf16 v[44:47], v[148:151], v[188:191], v[44:47]
	v_mfma_f32_16x16x32_bf16 v[40:43], v[156:159], v[188:191], v[40:43]
	v_mfma_f32_16x16x32_bf16 v[28:31], v[148:151], v[196:199], v[28:31]
	v_mfma_f32_16x16x32_bf16 v[24:27], v[156:159], v[196:199], v[24:27]
	v_mfma_f32_16x16x32_bf16 v[12:15], v[148:151], v[204:207], v[12:15]
	v_mfma_f32_16x16x32_bf16 v[8:11], v[156:159], v[204:207], v[8:11]
	v_mfma_f32_16x16x32_bf16 v[60:63], v[152:155], v[184:187], v[60:63]
	v_mfma_f32_16x16x32_bf16 v[56:59], v[160:163], v[184:187], v[56:59]
	v_mfma_f32_16x16x32_bf16 v[44:47], v[152:155], v[192:195], v[44:47]
	v_mfma_f32_16x16x32_bf16 v[40:43], v[160:163], v[192:195], v[40:43]
	v_mfma_f32_16x16x32_bf16 v[28:31], v[152:155], v[200:203], v[28:31]
	v_mfma_f32_16x16x32_bf16 v[24:27], v[160:163], v[200:203], v[24:27]
	v_mfma_f32_16x16x32_bf16 v[12:15], v[152:155], v[208:211], v[12:15]
	v_mfma_f32_16x16x32_bf16 v[8:11], v[160:163], v[208:211], v[8:11]
	v_mfma_f32_16x16x32_bf16 v[52:55], v[164:167], v[180:183], v[52:55]
	v_mfma_f32_16x16x32_bf16 v[48:51], v[172:175], v[180:183], v[48:51]
	v_mfma_f32_16x16x32_bf16 v[36:39], v[164:167], v[188:191], v[36:39]
	v_mfma_f32_16x16x32_bf16 v[32:35], v[172:175], v[188:191], v[32:35]
	v_mfma_f32_16x16x32_bf16 v[20:23], v[164:167], v[196:199], v[20:23]
	v_mfma_f32_16x16x32_bf16 v[16:19], v[172:175], v[196:199], v[16:19]
	v_mfma_f32_16x16x32_bf16 v[4:7], v[164:167], v[204:207], v[4:7]
	v_mfma_f32_16x16x32_bf16 v[0:3], v[172:175], v[204:207], v[0:3]
	v_mfma_f32_16x16x32_bf16 v[52:55], v[168:171], v[184:187], v[52:55]
	v_mfma_f32_16x16x32_bf16 v[48:51], v[176:179], v[184:187], v[48:51]
	v_mfma_f32_16x16x32_bf16 v[36:39], v[168:171], v[192:195], v[36:39]
	v_mfma_f32_16x16x32_bf16 v[32:35], v[176:179], v[192:195], v[32:35]
	v_mfma_f32_16x16x32_bf16 v[20:23], v[168:171], v[200:203], v[20:23]
	v_mfma_f32_16x16x32_bf16 v[16:19], v[176:179], v[200:203], v[16:19]
	v_mfma_f32_16x16x32_bf16 v[4:7], v[168:171], v[208:211], v[4:7]
	v_mfma_f32_16x16x32_bf16 v[0:3], v[176:179], v[208:211], v[0:3]
	s_barrier
	s_add_i32 s55, s55, 2
	s_add_u32 s22, s22, 0x100
	s_addc_u32 s23, s23, 0
	s_add_u32 s51, s51, 0x100
	s_addc_u32 s54, s54, 0
	s_cmp_gt_u32 s55, 13
	s_cbranch_scc0 .LBB0_1052
	s_and_b64 vcc, exec, s[8:9]
	s_cbranch_vccz .LBB0_1055
	s_barrier

; #define PG8_STAGE(bufoff, gbase, voff) do { _Pragma("unroll") for (int _i = 0; _i < 2; ++_i) \
;         __builtin_amdgcn_global_load_lds((const unsigned*)((const char*)(gbase) + (voff)[_i]), (LAS unsigned*)(lds + (bufoff) + ldsw + _i * 8192), 16, 0, 0); } while (0)
; #define PG8_LDA(dst, b, h) do { _Pragma("unroll") for (int m = 0; m < 4; ++m) _Pragma("unroll") for (int k = 0; k < 2; ++k) dst[m][k] = *(const LAS bf16x8*)(lds + PG8_SA(b, h) + aoff + m * 2048 + k * 1024); } while (0)
; #define PG8_LDB(dst, b, h) do { _Pragma("unroll") for (int n = 0; n < 2; ++n) _Pragma("unroll") for (int k = 0; k < 2; ++k) dst[n][k] = *(const LAS bf16x8*)(lds + PG8_SB(b, h) + boff + n * 2048 + k * 1024); } while (0)
; #define PG8_MMA(ai, bj, At, Bt) do { __builtin_amdgcn_s_setprio(1); _Pragma("unroll") for (int m = 0; m < 4; ++m) _Pragma("unroll") for (int n = 0; n < 2; ++n) _Pragma("unroll") for (int k = 0; k < 2; ++k) \
;         acc[ai][bj][m][n] = __builtin_amdgcn_mfma_f32_16x16x32_bf16(Bt[n][k], At[m][k], acc[ai][bj][m][n], 0, 0, 0); __builtin_amdgcn_s_setprio(0); } while (0)
; template <class Epi, bool ALIGN_EPI, int K, int LDA, int LDB>
; __device__ __forceinline__ void gemm_phase(LAS unsigned char* lds, const int wid, const Gemm g, const StaticOrder& S, const Epi& E) {
;     ...
;         const bool has_next = S.next(ui + 1, nxt);
;         const char* nA = has_next ? (const char*)g.A + (size_t)nxt.pm * tA : cA; const char* nB = has_next ? (const char*)g.Bt + (size_t)nxt.pn * tB : cB;
;         for (int t = 0; t < nt; t += 2) {
;             const bool last = (t == nt - 2);
;             const char* a1 = cA + (size_t)(t + 1) * kstep;
;             const char* a2 = last ? nA : cA + (size_t)(t + 2) * kstep; const char* b2 = last ? nB : cB + (size_t)(t + 2) * kstep;
;             const char* a3 = a2 + kstep; const char* b3 = b2 + kstep;
;             PG8_LDB(B0, 0, 0); PG8_LDB(B1, 0, 1); PG8_SCHED; PG8_LDA(At, 0, 0); PG8_STAGE(PG8_SA(1, 1), a1 + hA, voffA);
;             PG8_WAIT_V(8); PG8_WAIT_L(0); PG8_BAR; PG8_MMA(0, 0, At, B0); PG8_MMA(0, 1, At, B1); PG8_BAR; PG8_SCHED;
;             PG8_LDA(At, 0, 1); PG8_STAGE(PG8_SB(0, 0), b2, voffB); PG8_STAGE(PG8_SB(0, 1), b2 + hB, voffB); PG8_STAGE(PG8_SA(0, 0), a2, voffA);
;             PG8_WAIT_V(8); PG8_WAIT_L(0); PG8_BAR; PG8_MMA(1, 0, At, B0); PG8_MMA(1, 1, At, B1); PG8_BAR; PG8_SCHED;
.LBB0_1136:
	s_add_u32 s65, s28, 0x100
	s_addc_u32 s66, s29, 0
	s_mov_b32 s67, -2
	s_add_u32 s28, s26, 0x100
	s_addc_u32 s29, s27, 0
	s_cmp_eq_u32 s67, 40
	s_cselect_b32 s35, s7, s29
	s_cselect_b32 s34, s6, s28
	s_cselect_b32 s31, s25, s66
	s_cselect_b32 s30, s24, s65
	s_add_i32 m0, s36, 0xc000
	global_load_lds_dwordx4 v156, s[26:27]
	s_add_i32 m0, s36, 0xe000
	s_nop 0
	global_load_lds_dwordx4 v158, s[26:27]
	s_waitcnt vmcnt(8)
	s_barrier
	s_waitcnt lgkmcnt(0)
	v_mfma_f32_16x16x32_bf16 v[124:127], v[128:131], v[182:185], 0
	v_mfma_f32_16x16x32_bf16 v[116:119], v[136:139], v[182:185], 0
	v_mfma_f32_16x16x32_bf16 v[120:123], v[128:131], v[190:193], 0
	v_mfma_f32_16x16x32_bf16 v[112:115], v[136:139], v[190:193], 0
	v_mfma_f32_16x16x32_bf16 v[92:95], v[128:131], v[198:201], 0
	v_mfma_f32_16x16x32_bf16 v[88:91], v[136:139], v[198:201], 0
	v_mfma_f32_16x16x32_bf16 v[76:79], v[128:131], v[206:209], 0
	v_mfma_f32_16x16x32_bf16 v[72:75], v[136:139], v[206:209], 0
	v_mfma_f32_16x16x32_bf16 v[124:127], v[132:135], v[186:189], v[124:127]
	v_mfma_f32_16x16x32_bf16 v[116:119], v[140:143], v[186:189], v[116:119]
	v_mfma_f32_16x16x32_bf16 v[120:123], v[132:135], v[194:197], v[120:123]
	v_mfma_f32_16x16x32_bf16 v[112:115], v[140:143], v[194:197], v[112:115]
	v_mfma_f32_16x16x32_bf16 v[92:95], v[132:135], v[202:205], v[92:95]
	v_mfma_f32_16x16x32_bf16 v[88:91], v[140:143], v[202:205], v[88:91]
	v_mfma_f32_16x16x32_bf16 v[76:79], v[132:135], v[210:213], v[76:79]
	v_mfma_f32_16x16x32_bf16 v[72:75], v[140:143], v[210:213], v[72:75]
	v_mfma_f32_16x16x32_bf16 v[108:111], v[144:147], v[182:185], 0
	v_mfma_f32_16x16x32_bf16 v[104:107], v[168:171], v[182:185], 0
	v_mfma_f32_16x16x32_bf16 v[100:103], v[144:147], v[190:193], 0
	v_mfma_f32_16x16x32_bf16 v[96:99], v[168:171], v[190:193], 0
	v_mfma_f32_16x16x32_bf16 v[84:87], v[144:147], v[198:201], 0
	v_mfma_f32_16x16x32_bf16 v[80:83], v[168:171], v[198:201], 0
	v_mfma_f32_16x16x32_bf16 v[68:71], v[144:147], v[206:209], 0
	v_mfma_f32_16x16x32_bf16 v[64:67], v[168:171], v[206:209], 0
	v_mfma_f32_16x16x32_bf16 v[108:111], v[164:167], v[186:189], v[108:111]
	v_mfma_f32_16x16x32_bf16 v[104:107], v[178:181], v[186:189], v[104:107]
	v_mfma_f32_16x16x32_bf16 v[100:103], v[164:167], v[194:197], v[100:103]
	v_mfma_f32_16x16x32_bf16 v[96:99], v[178:181], v[194:197], v[96:99]
	v_mfma_f32_16x16x32_bf16 v[84:87], v[164:167], v[202:205], v[84:87]
	v_mfma_f32_16x16x32_bf16 v[80:83], v[178:181], v[202:205], v[80:83]
	v_mfma_f32_16x16x32_bf16 v[68:71], v[164:167], v[210:213], v[68:71]
	v_mfma_f32_16x16x32_bf16 v[64:67], v[178:181], v[210:213], v[64:67]
	s_barrier
	s_add_u32 s98, s30, s12
	s_addc_u32 s99, s31, s13
	s_add_u32 s100, s34, s12
	s_addc_u32 s101, s35, s13
	s_add_i32 s26, s54, s33
	s_mov_b32 m0, s26
	ds_read_b128 v[182:185], v177 offset:16384
	ds_read_b128 v[186:189], v177 offset:17408
	ds_read_b128 v[190:193], v177 offset:18432
	ds_read_b128 v[194:197], v177 offset:19456
	ds_read_b128 v[198:201], v177 offset:20480
	ds_read_b128 v[202:205], v177 offset:21504
	ds_read_b128 v[206:209], v177 offset:22528
	ds_read_b128 v[210:213], v177 offset:23552
	global_load_lds_dwordx4 v150, s[30:31]
	s_add_i32 m0, s26, 0x2000
	s_add_u32 s26, s30, 0xb0000
	s_addc_u32 s27, s31, 0
	s_add_i32 s52, s55, s33
	global_load_lds_dwordx4 v154, s[30:31]
	s_mov_b32 m0, s52
	s_nop 0
	global_load_lds_dwordx4 v150, s[26:27]
	s_add_i32 m0, s52, 0x2000
	s_nop 0
	global_load_lds_dwordx4 v154, s[26:27]
	s_mov_b32 m0, s36
	s_nop 0
	global_load_lds_dwordx4 v148, s[34:35]
	s_mov_b32 m0, s37
	s_nop 0
	global_load_lds_dwordx4 v152, s[34:35]
	s_waitcnt vmcnt(8)
	s_barrier
	s_waitcnt lgkmcnt(0)
	v_mfma_f32_16x16x32_bf16 v[60:63], v[128:131], v[182:185], 0
	v_mfma_f32_16x16x32_bf16 v[56:59], v[136:139], v[182:185], 0
	v_mfma_f32_16x16x32_bf16 v[44:47], v[128:131], v[190:193], 0
	v_mfma_f32_16x16x32_bf16 v[40:43], v[136:139], v[190:193], 0
	v_mfma_f32_16x16x32_bf16 v[36:39], v[128:131], v[198:201], 0
	v_mfma_f32_16x16x32_bf16 v[32:35], v[136:139], v[198:201], 0
	v_mfma_f32_16x16x32_bf16 v[20:23], v[128:131], v[206:209], 0
	v_mfma_f32_16x16x32_bf16 v[16:19], v[136:139], v[206:209], 0
	v_mfma_f32_16x16x32_bf16 v[60:63], v[132:135], v[186:189], v[60:63]
	v_mfma_f32_16x16x32_bf16 v[56:59], v[140:143], v[186:189], v[56:59]
	v_mfma_f32_16x16x32_bf16 v[44:47], v[132:135], v[194:197], v[44:47]
	v_mfma_f32_16x16x32_bf16 v[40:43], v[140:143], v[194:197], v[40:43]
	v_mfma_f32_16x16x32_bf16 v[36:39], v[132:135], v[202:205], v[36:39]
	v_mfma_f32_16x16x32_bf16 v[32:35], v[140:143], v[202:205], v[32:35]
	v_mfma_f32_16x16x32_bf16 v[20:23], v[132:135], v[210:213], v[20:23]
	v_mfma_f32_16x16x32_bf16 v[16:19], v[140:143], v[210:213], v[16:19]
	v_mfma_f32_16x16x32_bf16 v[52:55], v[144:147], v[182:185], 0
	v_mfma_f32_16x16x32_bf16 v[48:51], v[168:171], v[182:185], 0
	v_mfma_f32_16x16x32_bf16 v[28:31], v[144:147], v[190:193], 0
	v_mfma_f32_16x16x32_bf16 v[24:27], v[168:171], v[190:193], 0
	v_mfma_f32_16x16x32_bf16 v[12:15], v[144:147], v[198:201], 0
	v_mfma_f32_16x16x32_bf16 v[8:11], v[168:171], v[198:201], 0
	v_mfma_f32_16x16x32_bf16 v[4:7], v[144:147], v[206:209], 0
	v_mfma_f32_16x16x32_bf16 v[0:3], v[168:171], v[206:209], 0
	v_mfma_f32_16x16x32_bf16 v[52:55], v[164:167], v[186:189], v[52:55]
	v_mfma_f32_16x16x32_bf16 v[48:51], v[178:181], v[186:189], v[48:51]
	v_mfma_f32_16x16x32_bf16 v[28:31], v[164:167], v[194:197], v[28:31]
	v_mfma_f32_16x16x32_bf16 v[24:27], v[178:181], v[194:197], v[24:27]
	v_mfma_f32_16x16x32_bf16 v[12:15], v[164:167], v[202:205], v[12:15]
	v_mfma_f32_16x16x32_bf16 v[8:11], v[178:181], v[202:205], v[8:11]
	v_mfma_f32_16x16x32_bf16 v[4:7], v[164:167], v[210:213], v[4:7]
	v_mfma_f32_16x16x32_bf16 v[0:3], v[178:181], v[210:213], v[0:3]
	s_barrier
; #define PG8_STAGE(bufoff, gbase, voff) do { _Pragma("unroll") for (int _i = 0; _i < 2; ++_i) \
;         __builtin_amdgcn_global_load_lds((const unsigned*)((const char*)(gbase) + (voff)[_i]), (LAS unsigned*)(lds + (bufoff) + ldsw + _i * 8192), 16, 0, 0); } while (0)
; #define PG8_LDA(dst, b, h) do { _Pragma("unroll") for (int m = 0; m < 4; ++m) _Pragma("unroll") for (int k = 0; k < 2; ++k) dst[m][k] = *(const LAS bf16x8*)(lds + PG8_SA(b, h) + aoff + m * 2048 + k * 1024); } while (0)
; #define PG8_LDB(dst, b, h) do { _Pragma("unroll") for (int n = 0; n < 2; ++n) _Pragma("unroll") for (int k = 0; k < 2; ++k) dst[n][k] = *(const LAS bf16x8*)(lds + PG8_SB(b, h) + boff + n * 2048 + k * 1024); } while (0)
; #define PG8_MMA(ai, bj, At, Bt) do { __builtin_amdgcn_s_setprio(1); _Pragma("unroll") for (int m = 0; m < 4; ++m) _Pragma("unroll") for (int n = 0; n < 2; ++n) _Pragma("unroll") for (int k = 0; k < 2; ++k) \
;         acc[ai][bj][m][n] = __builtin_amdgcn_mfma_f32_16x16x32_bf16(Bt[n][k], At[m][k], acc[ai][bj][m][n], 0, 0, 0); __builtin_amdgcn_s_setprio(0); } while (0)
; #define PG8_WAIT_V(n) asm volatile("s_waitcnt vmcnt(" #n ")" ::: "memory")
; #define PG8_WAIT_L(n) asm volatile("s_waitcnt lgkmcnt(" #n ")" ::: "memory")
; #define PG8_BAR __builtin_amdgcn_s_barrier()
; #define PG8_SCHED __builtin_amdgcn_sched_barrier(0)
; template <class Epi, bool ALIGN_EPI, int K, int LDA, int LDB>
; __device__ __forceinline__ void gemm_phase(LAS unsigned char* lds, const int wid, const Gemm g, const StaticOrder& S, const Epi& E) {
;     ...
;             PG8_LDB(B0, 1, 0); PG8_LDB(B1, 1, 1); PG8_SCHED; PG8_LDA(At, 1, 0); PG8_STAGE(PG8_SA(0, 1), a2 + hA, voffA);
;             PG8_WAIT_V(8); PG8_WAIT_L(0); PG8_BAR; PG8_MMA(0, 0, At, B0); PG8_MMA(0, 1, At, B1); PG8_BAR; PG8_SCHED;
;             PG8_LDA(At, 1, 1); PG8_STAGE(PG8_SB(1, 0), b3, voffB); PG8_STAGE(PG8_SB(1, 1), b3 + hB, voffB); PG8_STAGE(PG8_SA(1, 0), a3, voffA);
;             PG8_WAIT_V(8); PG8_WAIT_L(0); PG8_BAR; PG8_MMA(1, 0, At, B0); PG8_MMA(1, 1, At, B1); PG8_BAR; PG8_SCHED;
	s_add_i32 s52, 0, 0x18000
	s_add_i32 s53, 0, 0x1c000
	v_add_u32_e32 v140, s52, v174
	v_add_u32_e32 v178, s53, v174
	ds_read_b128 v[128:131], v140
	ds_read_b128 v[132:135], v140 offset:1024
	ds_read_b128 v[136:139], v140 offset:2048
	ds_read_b128 v[140:143], v140 offset:3072
	ds_read_b128 v[144:147], v178
	ds_read_b128 v[164:167], v178 offset:1024
	ds_read_b128 v[168:171], v178 offset:2048
	ds_read_b128 v[178:181], v178 offset:3072
	s_add_u32 s26, s34, 0xb0000
	s_addc_u32 s27, s35, 0
	s_mov_b32 m0, s38
	ds_read_b128 v[182:185], v177 offset:32768
	ds_read_b128 v[186:189], v177 offset:33792
	ds_read_b128 v[190:193], v177 offset:34816
	ds_read_b128 v[194:197], v177 offset:35840
	ds_read_b128 v[198:201], v177 offset:36864
	ds_read_b128 v[202:205], v177 offset:37888
	ds_read_b128 v[206:209], v177 offset:38912
	ds_read_b128 v[210:213], v177 offset:39936
	global_load_lds_dwordx4 v148, s[26:27]
	s_mov_b32 m0, s39
	s_nop 0
	global_load_lds_dwordx4 v152, s[26:27]
	s_waitcnt vmcnt(8)
	s_barrier
	s_waitcnt lgkmcnt(0)
	v_mfma_f32_16x16x32_bf16 v[124:127], v[128:131], v[182:185], v[124:127]
	v_mfma_f32_16x16x32_bf16 v[116:119], v[136:139], v[182:185], v[116:119]
	v_mfma_f32_16x16x32_bf16 v[120:123], v[128:131], v[190:193], v[120:123]
	v_mfma_f32_16x16x32_bf16 v[112:115], v[136:139], v[190:193], v[112:115]
	v_mfma_f32_16x16x32_bf16 v[92:95], v[128:131], v[198:201], v[92:95]
	v_mfma_f32_16x16x32_bf16 v[88:91], v[136:139], v[198:201], v[88:91]
	v_mfma_f32_16x16x32_bf16 v[76:79], v[128:131], v[206:209], v[76:79]
	v_mfma_f32_16x16x32_bf16 v[72:75], v[136:139], v[206:209], v[72:75]
	v_mfma_f32_16x16x32_bf16 v[124:127], v[132:135], v[186:189], v[124:127]
	v_mfma_f32_16x16x32_bf16 v[116:119], v[140:143], v[186:189], v[116:119]
	v_mfma_f32_16x16x32_bf16 v[120:123], v[132:135], v[194:197], v[120:123]
	v_mfma_f32_16x16x32_bf16 v[112:115], v[140:143], v[194:197], v[112:115]
	v_mfma_f32_16x16x32_bf16 v[92:95], v[132:135], v[202:205], v[92:95]
	v_mfma_f32_16x16x32_bf16 v[88:91], v[140:143], v[202:205], v[88:91]
	v_mfma_f32_16x16x32_bf16 v[76:79], v[132:135], v[210:213], v[76:79]
	v_mfma_f32_16x16x32_bf16 v[72:75], v[140:143], v[210:213], v[72:75]
	v_mfma_f32_16x16x32_bf16 v[108:111], v[144:147], v[182:185], v[108:111]
	v_mfma_f32_16x16x32_bf16 v[104:107], v[168:171], v[182:185], v[104:107]
	v_mfma_f32_16x16x32_bf16 v[100:103], v[144:147], v[190:193], v[100:103]
	v_mfma_f32_16x16x32_bf16 v[96:99], v[168:171], v[190:193], v[96:99]
	v_mfma_f32_16x16x32_bf16 v[84:87], v[144:147], v[198:201], v[84:87]
	v_mfma_f32_16x16x32_bf16 v[80:83], v[168:171], v[198:201], v[80:83]
	v_mfma_f32_16x16x32_bf16 v[68:71], v[144:147], v[206:209], v[68:71]
	v_mfma_f32_16x16x32_bf16 v[64:67], v[168:171], v[206:209], v[64:67]
	v_mfma_f32_16x16x32_bf16 v[108:111], v[164:167], v[186:189], v[108:111]
	v_mfma_f32_16x16x32_bf16 v[104:107], v[178:181], v[186:189], v[104:107]
	v_mfma_f32_16x16x32_bf16 v[100:103], v[164:167], v[194:197], v[100:103]
	v_mfma_f32_16x16x32_bf16 v[96:99], v[178:181], v[194:197], v[96:99]
	v_mfma_f32_16x16x32_bf16 v[84:87], v[164:167], v[202:205], v[84:87]
	v_mfma_f32_16x16x32_bf16 v[80:83], v[178:181], v[202:205], v[80:83]
	v_mfma_f32_16x16x32_bf16 v[68:71], v[164:167], v[210:213], v[68:71]
	v_mfma_f32_16x16x32_bf16 v[64:67], v[178:181], v[210:213], v[64:67]
	s_barrier
	s_add_i32 s26, s52, s33
	s_mov_b32 m0, s26
	ds_read_b128 v[182:185], v177 offset:49152
	ds_read_b128 v[186:189], v177 offset:50176
	ds_read_b128 v[190:193], v177 offset:51200
	ds_read_b128 v[194:197], v177 offset:52224
	ds_read_b128 v[198:201], v177 offset:53248
	ds_read_b128 v[202:205], v177 offset:54272
	ds_read_b128 v[206:209], v177 offset:55296
	ds_read_b128 v[210:213], v177 offset:56320
	global_load_lds_dwordx4 v150, s[98:99]
	s_add_i32 m0, s26, 0x2000
	s_add_u32 s26, s30, 0xb0080
	s_addc_u32 s27, s31, 0
	s_add_i32 s30, s53, s33
	global_load_lds_dwordx4 v154, s[98:99]
	s_mov_b32 m0, s30
	s_nop 0
	global_load_lds_dwordx4 v150, s[26:27]
	s_add_i32 m0, s30, 0x2000
	s_nop 0
	global_load_lds_dwordx4 v154, s[26:27]
	s_mov_b32 m0, s48
	s_nop 0
	global_load_lds_dwordx4 v148, s[100:101]
	s_mov_b32 m0, s49
	s_nop 0
	global_load_lds_dwordx4 v152, s[100:101]
	s_waitcnt vmcnt(8)
	s_barrier
	s_waitcnt lgkmcnt(0)
	v_mfma_f32_16x16x32_bf16 v[60:63], v[128:131], v[182:185], v[60:63]
	v_mfma_f32_16x16x32_bf16 v[56:59], v[136:139], v[182:185], v[56:59]
	v_mfma_f32_16x16x32_bf16 v[44:47], v[128:131], v[190:193], v[44:47]
	v_mfma_f32_16x16x32_bf16 v[40:43], v[136:139], v[190:193], v[40:43]
	v_mfma_f32_16x16x32_bf16 v[36:39], v[128:131], v[198:201], v[36:39]
	v_mfma_f32_16x16x32_bf16 v[32:35], v[136:139], v[198:201], v[32:35]
	v_mfma_f32_16x16x32_bf16 v[20:23], v[128:131], v[206:209], v[20:23]
	v_mfma_f32_16x16x32_bf16 v[16:19], v[136:139], v[206:209], v[16:19]
	v_mfma_f32_16x16x32_bf16 v[60:63], v[132:135], v[186:189], v[60:63]
	v_mfma_f32_16x16x32_bf16 v[56:59], v[140:143], v[186:189], v[56:59]
	v_mfma_f32_16x16x32_bf16 v[44:47], v[132:135], v[194:197], v[44:47]
	v_mfma_f32_16x16x32_bf16 v[40:43], v[140:143], v[194:197], v[40:43]
	v_mfma_f32_16x16x32_bf16 v[36:39], v[132:135], v[202:205], v[36:39]
	v_mfma_f32_16x16x32_bf16 v[32:35], v[140:143], v[202:205], v[32:35]
	v_mfma_f32_16x16x32_bf16 v[20:23], v[132:135], v[210:213], v[20:23]
	v_mfma_f32_16x16x32_bf16 v[16:19], v[140:143], v[210:213], v[16:19]
	v_mfma_f32_16x16x32_bf16 v[52:55], v[144:147], v[182:185], v[52:55]
	v_mfma_f32_16x16x32_bf16 v[48:51], v[168:171], v[182:185], v[48:51]
	v_mfma_f32_16x16x32_bf16 v[28:31], v[144:147], v[190:193], v[28:31]
	v_mfma_f32_16x16x32_bf16 v[24:27], v[168:171], v[190:193], v[24:27]
	v_mfma_f32_16x16x32_bf16 v[12:15], v[144:147], v[198:201], v[12:15]
	v_mfma_f32_16x16x32_bf16 v[8:11], v[168:171], v[198:201], v[8:11]
	v_mfma_f32_16x16x32_bf16 v[4:7], v[144:147], v[206:209], v[4:7]
	v_mfma_f32_16x16x32_bf16 v[0:3], v[168:171], v[206:209], v[0:3]
	v_mfma_f32_16x16x32_bf16 v[52:55], v[164:167], v[186:189], v[52:55]
	v_mfma_f32_16x16x32_bf16 v[48:51], v[178:181], v[186:189], v[48:51]
	v_mfma_f32_16x16x32_bf16 v[28:31], v[164:167], v[194:197], v[28:31]
	v_mfma_f32_16x16x32_bf16 v[24:27], v[178:181], v[194:197], v[24:27]
	v_mfma_f32_16x16x32_bf16 v[12:15], v[164:167], v[202:205], v[12:15]
	v_mfma_f32_16x16x32_bf16 v[8:11], v[178:181], v[202:205], v[8:11]
	v_mfma_f32_16x16x32_bf16 v[4:7], v[164:167], v[210:213], v[4:7]
	v_mfma_f32_16x16x32_bf16 v[0:3], v[178:181], v[210:213], v[0:3]
	s_barrier
	s_add_i32 s67, s67, 2
	s_add_u32 s65, s65, 0x100
	s_addc_u32 s66, s66, 0
	s_mov_b64 s[26:27], s[28:29]
; #define PG8_STAGE(bufoff, gbase, voff) do { _Pragma("unroll") for (int _i = 0; _i < 2; ++_i) \
;         __builtin_amdgcn_global_load_lds((const unsigned*)((const char*)(gbase) + (voff)[_i]), (LAS unsigned*)(lds + (bufoff) + ldsw + _i * 8192), 16, 0, 0); } while (0)
; #define PG8_LDA(dst, b, h) do { _Pragma("unroll") for (int m = 0; m < 4; ++m) _Pragma("unroll") for (int k = 0; k < 2; ++k) dst[m][k] = *(const LAS bf16x8*)(lds + PG8_SA(b, h) + aoff + m * 2048 + k * 1024); } while (0)
; #define PG8_LDB(dst, b, h) do { _Pragma("unroll") for (int n = 0; n < 2; ++n) _Pragma("unroll") for (int k = 0; k < 2; ++k) dst[n][k] = *(const LAS bf16x8*)(lds + PG8_SB(b, h) + boff + n * 2048 + k * 1024); } while (0)
; #define PG8_MMA(ai, bj, At, Bt) do { __builtin_amdgcn_s_setprio(1); _Pragma("unroll") for (int m = 0; m < 4; ++m) _Pragma("unroll") for (int n = 0; n < 2; ++n) _Pragma("unroll") for (int k = 0; k < 2; ++k) \
;         acc[ai][bj][m][n] = __builtin_amdgcn_mfma_f32_16x16x32_bf16(Bt[n][k], At[m][k], acc[ai][bj][m][n], 0, 0, 0); __builtin_amdgcn_s_setprio(0); } while (0)
; #define PG8_WAIT_V(n) asm volatile("s_waitcnt vmcnt(" #n ")" ::: "memory")
; #define PG8_WAIT_L(n) asm volatile("s_waitcnt lgkmcnt(" #n ")" ::: "memory")
; #define PG8_BAR __builtin_amdgcn_s_barrier()
; template <class Epi, bool ALIGN_EPI, int K, int LDA, int LDB>
; __device__ __forceinline__ void gemm_phase(LAS unsigned char* lds, const int wid, const Gemm g, const StaticOrder& S, const Epi& E) {
;     ...
;         for (int t = 0; t < nt; t += 2) {
;             const bool last = (t == nt - 2);
;             const char* a1 = cA + (size_t)(t + 1) * kstep;
;             const char* a2 = last ? nA : cA + (size_t)(t + 2) * kstep; const char* b2 = last ? nB : cB + (size_t)(t + 2) * kstep;
;             const char* a3 = a2 + kstep; const char* b3 = b2 + kstep;
;             PG8_LDB(B0, 0, 0); PG8_LDB(B1, 0, 1); PG8_SCHED; PG8_LDA(At, 0, 0); PG8_STAGE(PG8_SA(1, 1), a1 + hA, voffA);
;             PG8_WAIT_V(8); PG8_WAIT_L(0); PG8_BAR; PG8_MMA(0, 0, At, B0); PG8_MMA(0, 1, At, B1); PG8_BAR; PG8_SCHED;
;             PG8_LDA(At, 0, 1); PG8_STAGE(PG8_SB(0, 0), b2, voffB); PG8_STAGE(PG8_SB(0, 1), b2 + hB, voffB); PG8_STAGE(PG8_SA(0, 0), a2, voffA);
;             PG8_WAIT_V(8); PG8_WAIT_L(0); PG8_BAR; PG8_MMA(1, 0, At, B0); PG8_MMA(1, 1, At, B1); PG8_BAR; PG8_SCHED;
.LBB0_1137:
	ds_read_b128 v[128:131], v175
	ds_read_b128 v[132:135], v175 offset:1024
	ds_read_b128 v[136:139], v175 offset:2048
	ds_read_b128 v[140:143], v175 offset:3072
	ds_read_b128 v[144:147], v176
	ds_read_b128 v[164:167], v176 offset:1024
	ds_read_b128 v[168:171], v176 offset:2048
	ds_read_b128 v[178:181], v176 offset:3072
	s_add_u32 s28, s26, 0x100
	s_addc_u32 s29, s27, 0
	s_cmp_eq_u32 s67, 40
	s_cselect_b32 s35, s7, s29
	s_cselect_b32 s34, s6, s28
	s_cselect_b32 s31, s25, s66
	s_cselect_b32 s30, s24, s65
	s_add_i32 m0, s36, 0xc000
	ds_read_b128 v[182:185], v177
	ds_read_b128 v[186:189], v177 offset:1024
	ds_read_b128 v[190:193], v177 offset:2048
	ds_read_b128 v[194:197], v177 offset:3072
	ds_read_b128 v[198:201], v177 offset:4096
	ds_read_b128 v[202:205], v177 offset:5120
	ds_read_b128 v[206:209], v177 offset:6144
	ds_read_b128 v[210:213], v177 offset:7168
	global_load_lds_dwordx4 v156, s[26:27]
	s_add_i32 m0, s36, 0xe000
	s_nop 0
	global_load_lds_dwordx4 v158, s[26:27]
	s_waitcnt vmcnt(8)
	s_barrier
	s_waitcnt lgkmcnt(0)
	v_mfma_f32_16x16x32_bf16 v[124:127], v[128:131], v[182:185], v[124:127]
	v_mfma_f32_16x16x32_bf16 v[116:119], v[136:139], v[182:185], v[116:119]
	v_mfma_f32_16x16x32_bf16 v[120:123], v[128:131], v[190:193], v[120:123]
	v_mfma_f32_16x16x32_bf16 v[112:115], v[136:139], v[190:193], v[112:115]
	v_mfma_f32_16x16x32_bf16 v[92:95], v[128:131], v[198:201], v[92:95]
	v_mfma_f32_16x16x32_bf16 v[88:91], v[136:139], v[198:201], v[88:91]
	v_mfma_f32_16x16x32_bf16 v[76:79], v[128:131], v[206:209], v[76:79]
	v_mfma_f32_16x16x32_bf16 v[72:75], v[136:139], v[206:209], v[72:75]
	v_mfma_f32_16x16x32_bf16 v[124:127], v[132:135], v[186:189], v[124:127]
	v_mfma_f32_16x16x32_bf16 v[116:119], v[140:143], v[186:189], v[116:119]
	v_mfma_f32_16x16x32_bf16 v[120:123], v[132:135], v[194:197], v[120:123]
	v_mfma_f32_16x16x32_bf16 v[112:115], v[140:143], v[194:197], v[112:115]
	v_mfma_f32_16x16x32_bf16 v[92:95], v[132:135], v[202:205], v[92:95]
	v_mfma_f32_16x16x32_bf16 v[88:91], v[140:143], v[202:205], v[88:91]
	v_mfma_f32_16x16x32_bf16 v[76:79], v[132:135], v[210:213], v[76:79]
	v_mfma_f32_16x16x32_bf16 v[72:75], v[140:143], v[210:213], v[72:75]
	v_mfma_f32_16x16x32_bf16 v[108:111], v[144:147], v[182:185], v[108:111]
	v_mfma_f32_16x16x32_bf16 v[104:107], v[168:171], v[182:185], v[104:107]
	v_mfma_f32_16x16x32_bf16 v[100:103], v[144:147], v[190:193], v[100:103]
	v_mfma_f32_16x16x32_bf16 v[96:99], v[168:171], v[190:193], v[96:99]
	v_mfma_f32_16x16x32_bf16 v[84:87], v[144:147], v[198:201], v[84:87]
	v_mfma_f32_16x16x32_bf16 v[80:83], v[168:171], v[198:201], v[80:83]
	v_mfma_f32_16x16x32_bf16 v[68:71], v[144:147], v[206:209], v[68:71]
	v_mfma_f32_16x16x32_bf16 v[64:67], v[168:171], v[206:209], v[64:67]
	v_mfma_f32_16x16x32_bf16 v[108:111], v[164:167], v[186:189], v[108:111]
	v_mfma_f32_16x16x32_bf16 v[104:107], v[178:181], v[186:189], v[104:107]
	v_mfma_f32_16x16x32_bf16 v[100:103], v[164:167], v[194:197], v[100:103]
	v_mfma_f32_16x16x32_bf16 v[96:99], v[178:181], v[194:197], v[96:99]
	v_mfma_f32_16x16x32_bf16 v[84:87], v[164:167], v[202:205], v[84:87]
	v_mfma_f32_16x16x32_bf16 v[80:83], v[178:181], v[202:205], v[80:83]
	v_mfma_f32_16x16x32_bf16 v[68:71], v[164:167], v[210:213], v[68:71]
	v_mfma_f32_16x16x32_bf16 v[64:67], v[178:181], v[210:213], v[64:67]
	s_barrier
	s_add_u32 s98, s30, s12
	s_addc_u32 s99, s31, s13
	s_add_u32 s100, s34, s12
	s_addc_u32 s101, s35, s13
	s_add_i32 s26, s54, s33
	s_mov_b32 m0, s26
	ds_read_b128 v[182:185], v177 offset:16384
	ds_read_b128 v[186:189], v177 offset:17408
	ds_read_b128 v[190:193], v177 offset:18432
	ds_read_b128 v[194:197], v177 offset:19456
	ds_read_b128 v[198:201], v177 offset:20480
	ds_read_b128 v[202:205], v177 offset:21504
	ds_read_b128 v[206:209], v177 offset:22528
	ds_read_b128 v[210:213], v177 offset:23552
	global_load_lds_dwordx4 v150, s[30:31]
	s_add_i32 m0, s26, 0x2000
	s_add_u32 s26, s30, 0xb0000
	s_addc_u32 s27, s31, 0
	s_add_i32 s52, s55, s33
	global_load_lds_dwordx4 v154, s[30:31]
	s_mov_b32 m0, s52
	s_nop 0
	global_load_lds_dwordx4 v150, s[26:27]
	s_add_i32 m0, s52, 0x2000
	s_nop 0
	global_load_lds_dwordx4 v154, s[26:27]
	s_mov_b32 m0, s36
	s_nop 0
	global_load_lds_dwordx4 v148, s[34:35]
	s_mov_b32 m0, s37
	s_nop 0
	global_load_lds_dwordx4 v152, s[34:35]
	s_waitcnt vmcnt(8)
	s_barrier
	s_waitcnt lgkmcnt(0)
	v_mfma_f32_16x16x32_bf16 v[60:63], v[128:131], v[182:185], v[60:63]
	v_mfma_f32_16x16x32_bf16 v[56:59], v[136:139], v[182:185], v[56:59]
	v_mfma_f32_16x16x32_bf16 v[44:47], v[128:131], v[190:193], v[44:47]
	v_mfma_f32_16x16x32_bf16 v[40:43], v[136:139], v[190:193], v[40:43]
	v_mfma_f32_16x16x32_bf16 v[36:39], v[128:131], v[198:201], v[36:39]
	v_mfma_f32_16x16x32_bf16 v[32:35], v[136:139], v[198:201], v[32:35]
	v_mfma_f32_16x16x32_bf16 v[20:23], v[128:131], v[206:209], v[20:23]
	v_mfma_f32_16x16x32_bf16 v[16:19], v[136:139], v[206:209], v[16:19]
	v_mfma_f32_16x16x32_bf16 v[60:63], v[132:135], v[186:189], v[60:63]
	v_mfma_f32_16x16x32_bf16 v[56:59], v[140:143], v[186:189], v[56:59]
	v_mfma_f32_16x16x32_bf16 v[44:47], v[132:135], v[194:197], v[44:47]
	v_mfma_f32_16x16x32_bf16 v[40:43], v[140:143], v[194:197], v[40:43]
	v_mfma_f32_16x16x32_bf16 v[36:39], v[132:135], v[202:205], v[36:39]
	v_mfma_f32_16x16x32_bf16 v[32:35], v[140:143], v[202:205], v[32:35]
	v_mfma_f32_16x16x32_bf16 v[20:23], v[132:135], v[210:213], v[20:23]
	v_mfma_f32_16x16x32_bf16 v[16:19], v[140:143], v[210:213], v[16:19]
	v_mfma_f32_16x16x32_bf16 v[52:55], v[144:147], v[182:185], v[52:55]
	v_mfma_f32_16x16x32_bf16 v[48:51], v[168:171], v[182:185], v[48:51]
	v_mfma_f32_16x16x32_bf16 v[28:31], v[144:147], v[190:193], v[28:31]
	v_mfma_f32_16x16x32_bf16 v[24:27], v[168:171], v[190:193], v[24:27]
	v_mfma_f32_16x16x32_bf16 v[12:15], v[144:147], v[198:201], v[12:15]
	v_mfma_f32_16x16x32_bf16 v[8:11], v[168:171], v[198:201], v[8:11]
	v_mfma_f32_16x16x32_bf16 v[4:7], v[144:147], v[206:209], v[4:7]
	v_mfma_f32_16x16x32_bf16 v[0:3], v[168:171], v[206:209], v[0:3]
	v_mfma_f32_16x16x32_bf16 v[52:55], v[164:167], v[186:189], v[52:55]
	v_mfma_f32_16x16x32_bf16 v[48:51], v[178:181], v[186:189], v[48:51]
	v_mfma_f32_16x16x32_bf16 v[28:31], v[164:167], v[194:197], v[28:31]
	v_mfma_f32_16x16x32_bf16 v[24:27], v[178:181], v[194:197], v[24:27]
	v_mfma_f32_16x16x32_bf16 v[12:15], v[164:167], v[202:205], v[12:15]
	v_mfma_f32_16x16x32_bf16 v[8:11], v[178:181], v[202:205], v[8:11]
	v_mfma_f32_16x16x32_bf16 v[4:7], v[164:167], v[210:213], v[4:7]
	v_mfma_f32_16x16x32_bf16 v[0:3], v[178:181], v[210:213], v[0:3]
	s_barrier
; #define PG8_STAGE(bufoff, gbase, voff) do { _Pragma("unroll") for (int _i = 0; _i < 2; ++_i) \
;         __builtin_amdgcn_global_load_lds((const unsigned*)((const char*)(gbase) + (voff)[_i]), (LAS unsigned*)(lds + (bufoff) + ldsw + _i * 8192), 16, 0, 0); } while (0)
; #define PG8_LDA(dst, b, h) do { _Pragma("unroll") for (int m = 0; m < 4; ++m) _Pragma("unroll") for (int k = 0; k < 2; ++k) dst[m][k] = *(const LAS bf16x8*)(lds + PG8_SA(b, h) + aoff + m * 2048 + k * 1024); } while (0)
; #define PG8_LDB(dst, b, h) do { _Pragma("unroll") for (int n = 0; n < 2; ++n) _Pragma("unroll") for (int k = 0; k < 2; ++k) dst[n][k] = *(const LAS bf16x8*)(lds + PG8_SB(b, h) + boff + n * 2048 + k * 1024); } while (0)
; #define PG8_MMA(ai, bj, At, Bt) do { __builtin_amdgcn_s_setprio(1); _Pragma("unroll") for (int m = 0; m < 4; ++m) _Pragma("unroll") for (int n = 0; n < 2; ++n) _Pragma("unroll") for (int k = 0; k < 2; ++k) \
;         acc[ai][bj][m][n] = __builtin_amdgcn_mfma_f32_16x16x32_bf16(Bt[n][k], At[m][k], acc[ai][bj][m][n], 0, 0, 0); __builtin_amdgcn_s_setprio(0); } while (0)
; #define PG8_WAIT_V(n) asm volatile("s_waitcnt vmcnt(" #n ")" ::: "memory")
; #define PG8_WAIT_L(n) asm volatile("s_waitcnt lgkmcnt(" #n ")" ::: "memory")
; #define PG8_BAR __builtin_amdgcn_s_barrier()
; #define PG8_SCHED __builtin_amdgcn_sched_barrier(0)
; template <class Epi, bool ALIGN_EPI, int K, int LDA, int LDB>
; __device__ __forceinline__ void gemm_phase(LAS unsigned char* lds, const int wid, const Gemm g, const StaticOrder& S, const Epi& E) {
;     ...
;             PG8_LDB(B0, 1, 0); PG8_LDB(B1, 1, 1); PG8_SCHED; PG8_LDA(At, 1, 0); PG8_STAGE(PG8_SA(0, 1), a2 + hA, voffA);
;             PG8_WAIT_V(8); PG8_WAIT_L(0); PG8_BAR; PG8_MMA(0, 0, At, B0); PG8_MMA(0, 1, At, B1); PG8_BAR; PG8_SCHED;
;             PG8_LDA(At, 1, 1); PG8_STAGE(PG8_SB(1, 0), b3, voffB); PG8_STAGE(PG8_SB(1, 1), b3 + hB, voffB); PG8_STAGE(PG8_SA(1, 0), a3, voffA);
;             PG8_WAIT_V(8); PG8_WAIT_L(0); PG8_BAR; PG8_MMA(1, 0, At, B0); PG8_MMA(1, 1, At, B1); PG8_BAR; PG8_SCHED;
;         }
	s_add_i32 s52, 0, 0x18000
	s_add_i32 s53, 0, 0x1c000
	v_add_u32_e32 v140, s52, v174
	v_add_u32_e32 v178, s53, v174
	ds_read_b128 v[128:131], v140
	ds_read_b128 v[132:135], v140 offset:1024
	ds_read_b128 v[136:139], v140 offset:2048
	ds_read_b128 v[140:143], v140 offset:3072
	ds_read_b128 v[144:147], v178
	ds_read_b128 v[164:167], v178 offset:1024
	ds_read_b128 v[168:171], v178 offset:2048
	ds_read_b128 v[178:181], v178 offset:3072
	s_add_u32 s26, s34, 0xb0000
	s_addc_u32 s27, s35, 0
	s_mov_b32 m0, s38
	ds_read_b128 v[182:185], v177 offset:32768
	ds_read_b128 v[186:189], v177 offset:33792
	ds_read_b128 v[190:193], v177 offset:34816
	ds_read_b128 v[194:197], v177 offset:35840
	ds_read_b128 v[198:201], v177 offset:36864
	ds_read_b128 v[202:205], v177 offset:37888
	ds_read_b128 v[206:209], v177 offset:38912
	ds_read_b128 v[210:213], v177 offset:39936
	global_load_lds_dwordx4 v148, s[26:27]
	s_mov_b32 m0, s39
	s_nop 0
	global_load_lds_dwordx4 v152, s[26:27]
	s_waitcnt vmcnt(8)
	s_barrier
	s_waitcnt lgkmcnt(0)
	v_mfma_f32_16x16x32_bf16 v[124:127], v[128:131], v[182:185], v[124:127]
	v_mfma_f32_16x16x32_bf16 v[116:119], v[136:139], v[182:185], v[116:119]
	v_mfma_f32_16x16x32_bf16 v[120:123], v[128:131], v[190:193], v[120:123]
	v_mfma_f32_16x16x32_bf16 v[112:115], v[136:139], v[190:193], v[112:115]
	v_mfma_f32_16x16x32_bf16 v[92:95], v[128:131], v[198:201], v[92:95]
	v_mfma_f32_16x16x32_bf16 v[88:91], v[136:139], v[198:201], v[88:91]
	v_mfma_f32_16x16x32_bf16 v[76:79], v[128:131], v[206:209], v[76:79]
	v_mfma_f32_16x16x32_bf16 v[72:75], v[136:139], v[206:209], v[72:75]
	v_mfma_f32_16x16x32_bf16 v[124:127], v[132:135], v[186:189], v[124:127]
	v_mfma_f32_16x16x32_bf16 v[116:119], v[140:143], v[186:189], v[116:119]
	v_mfma_f32_16x16x32_bf16 v[120:123], v[132:135], v[194:197], v[120:123]
	v_mfma_f32_16x16x32_bf16 v[112:115], v[140:143], v[194:197], v[112:115]
	v_mfma_f32_16x16x32_bf16 v[92:95], v[132:135], v[202:205], v[92:95]
	v_mfma_f32_16x16x32_bf16 v[88:91], v[140:143], v[202:205], v[88:91]
	v_mfma_f32_16x16x32_bf16 v[76:79], v[132:135], v[210:213], v[76:79]
	v_mfma_f32_16x16x32_bf16 v[72:75], v[140:143], v[210:213], v[72:75]
	v_mfma_f32_16x16x32_bf16 v[108:111], v[144:147], v[182:185], v[108:111]
	v_mfma_f32_16x16x32_bf16 v[104:107], v[168:171], v[182:185], v[104:107]
	v_mfma_f32_16x16x32_bf16 v[100:103], v[144:147], v[190:193], v[100:103]
	v_mfma_f32_16x16x32_bf16 v[96:99], v[168:171], v[190:193], v[96:99]
	v_mfma_f32_16x16x32_bf16 v[84:87], v[144:147], v[198:201], v[84:87]
	v_mfma_f32_16x16x32_bf16 v[80:83], v[168:171], v[198:201], v[80:83]
	v_mfma_f32_16x16x32_bf16 v[68:71], v[144:147], v[206:209], v[68:71]
	v_mfma_f32_16x16x32_bf16 v[64:67], v[168:171], v[206:209], v[64:67]
	v_mfma_f32_16x16x32_bf16 v[108:111], v[164:167], v[186:189], v[108:111]
	v_mfma_f32_16x16x32_bf16 v[104:107], v[178:181], v[186:189], v[104:107]
	v_mfma_f32_16x16x32_bf16 v[100:103], v[164:167], v[194:197], v[100:103]
	v_mfma_f32_16x16x32_bf16 v[96:99], v[178:181], v[194:197], v[96:99]
	v_mfma_f32_16x16x32_bf16 v[84:87], v[164:167], v[202:205], v[84:87]
	v_mfma_f32_16x16x32_bf16 v[80:83], v[178:181], v[202:205], v[80:83]
	v_mfma_f32_16x16x32_bf16 v[68:71], v[164:167], v[210:213], v[68:71]
	v_mfma_f32_16x16x32_bf16 v[64:67], v[178:181], v[210:213], v[64:67]
	s_barrier
	s_add_i32 s26, s52, s33
	s_mov_b32 m0, s26
	ds_read_b128 v[182:185], v177 offset:49152
	ds_read_b128 v[186:189], v177 offset:50176
	ds_read_b128 v[190:193], v177 offset:51200
	ds_read_b128 v[194:197], v177 offset:52224
	ds_read_b128 v[198:201], v177 offset:53248
	ds_read_b128 v[202:205], v177 offset:54272
	ds_read_b128 v[206:209], v177 offset:55296
	ds_read_b128 v[210:213], v177 offset:56320
	global_load_lds_dwordx4 v150, s[98:99]
	s_add_i32 m0, s26, 0x2000
	s_add_u32 s26, s30, 0xb0080
	s_addc_u32 s27, s31, 0
	s_add_i32 s30, s53, s33
	global_load_lds_dwordx4 v154, s[98:99]
	s_mov_b32 m0, s30
	s_nop 0
	global_load_lds_dwordx4 v150, s[26:27]
	s_add_i32 m0, s30, 0x2000
	s_nop 0
	global_load_lds_dwordx4 v154, s[26:27]
	s_mov_b32 m0, s48
	s_nop 0
	global_load_lds_dwordx4 v148, s[100:101]
	s_mov_b32 m0, s49
	s_nop 0
	global_load_lds_dwordx4 v152, s[100:101]
	s_waitcnt vmcnt(8)
	s_barrier
	s_waitcnt lgkmcnt(0)
	v_mfma_f32_16x16x32_bf16 v[60:63], v[128:131], v[182:185], v[60:63]
	v_mfma_f32_16x16x32_bf16 v[56:59], v[136:139], v[182:185], v[56:59]
	v_mfma_f32_16x16x32_bf16 v[44:47], v[128:131], v[190:193], v[44:47]
	v_mfma_f32_16x16x32_bf16 v[40:43], v[136:139], v[190:193], v[40:43]
	v_mfma_f32_16x16x32_bf16 v[36:39], v[128:131], v[198:201], v[36:39]
	v_mfma_f32_16x16x32_bf16 v[32:35], v[136:139], v[198:201], v[32:35]
	v_mfma_f32_16x16x32_bf16 v[20:23], v[128:131], v[206:209], v[20:23]
	v_mfma_f32_16x16x32_bf16 v[16:19], v[136:139], v[206:209], v[16:19]
	v_mfma_f32_16x16x32_bf16 v[60:63], v[132:135], v[186:189], v[60:63]
	v_mfma_f32_16x16x32_bf16 v[56:59], v[140:143], v[186:189], v[56:59]
	v_mfma_f32_16x16x32_bf16 v[44:47], v[132:135], v[194:197], v[44:47]
	v_mfma_f32_16x16x32_bf16 v[40:43], v[140:143], v[194:197], v[40:43]
	v_mfma_f32_16x16x32_bf16 v[36:39], v[132:135], v[202:205], v[36:39]
	v_mfma_f32_16x16x32_bf16 v[32:35], v[140:143], v[202:205], v[32:35]
	v_mfma_f32_16x16x32_bf16 v[20:23], v[132:135], v[210:213], v[20:23]
	v_mfma_f32_16x16x32_bf16 v[16:19], v[140:143], v[210:213], v[16:19]
	v_mfma_f32_16x16x32_bf16 v[52:55], v[144:147], v[182:185], v[52:55]
	v_mfma_f32_16x16x32_bf16 v[48:51], v[168:171], v[182:185], v[48:51]
	v_mfma_f32_16x16x32_bf16 v[28:31], v[144:147], v[190:193], v[28:31]
	v_mfma_f32_16x16x32_bf16 v[24:27], v[168:171], v[190:193], v[24:27]
	v_mfma_f32_16x16x32_bf16 v[12:15], v[144:147], v[198:201], v[12:15]
	v_mfma_f32_16x16x32_bf16 v[8:11], v[168:171], v[198:201], v[8:11]
	v_mfma_f32_16x16x32_bf16 v[4:7], v[144:147], v[206:209], v[4:7]
	v_mfma_f32_16x16x32_bf16 v[0:3], v[168:171], v[206:209], v[0:3]
	v_mfma_f32_16x16x32_bf16 v[52:55], v[164:167], v[186:189], v[52:55]
	v_mfma_f32_16x16x32_bf16 v[48:51], v[178:181], v[186:189], v[48:51]
	v_mfma_f32_16x16x32_bf16 v[28:31], v[164:167], v[194:197], v[28:31]
	v_mfma_f32_16x16x32_bf16 v[24:27], v[178:181], v[194:197], v[24:27]
	v_mfma_f32_16x16x32_bf16 v[12:15], v[164:167], v[202:205], v[12:15]
	v_mfma_f32_16x16x32_bf16 v[8:11], v[178:181], v[202:205], v[8:11]
	v_mfma_f32_16x16x32_bf16 v[4:7], v[164:167], v[210:213], v[4:7]
	v_mfma_f32_16x16x32_bf16 v[0:3], v[178:181], v[210:213], v[0:3]
	s_barrier
	s_add_i32 s67, s67, 2
	s_add_u32 s65, s65, 0x100
	s_addc_u32 s66, s66, 0
	s_cmp_gt_u32 s67, 41
	s_mov_b64 s[26:27], s[28:29]
	s_cbranch_scc0 .LBB0_1137
	s_and_b64 vcc, exec, s[14:15]
	s_cbranch_vccz .LBB0_1140
	s_barrier

; #define PG8_STAGE(bufoff, gbase, voff) do { _Pragma("unroll") for (int _i = 0; _i < 2; ++_i) \
;         __builtin_amdgcn_global_load_lds((const unsigned*)((const char*)(gbase) + (voff)[_i]), (LAS unsigned*)(lds + (bufoff) + ldsw + _i * 8192), 16, 0, 0); } while (0)
; #define PG8_LDA(dst, b, h) do { _Pragma("unroll") for (int m = 0; m < 4; ++m) _Pragma("unroll") for (int k = 0; k < 2; ++k) dst[m][k] = *(const LAS bf16x8*)(lds + PG8_SA(b, h) + aoff + m * 2048 + k * 1024); } while (0)
; #define PG8_LDB(dst, b, h) do { _Pragma("unroll") for (int n = 0; n < 2; ++n) _Pragma("unroll") for (int k = 0; k < 2; ++k) dst[n][k] = *(const LAS bf16x8*)(lds + PG8_SB(b, h) + boff + n * 2048 + k * 1024); } while (0)
; #define PG8_MMA(ai, bj, At, Bt) do { __builtin_amdgcn_s_setprio(1); _Pragma("unroll") for (int m = 0; m < 4; ++m) _Pragma("unroll") for (int n = 0; n < 2; ++n) _Pragma("unroll") for (int k = 0; k < 2; ++k) \
;         acc[ai][bj][m][n] = __builtin_amdgcn_mfma_f32_16x16x32_bf16(Bt[n][k], At[m][k], acc[ai][bj][m][n], 0, 0, 0); __builtin_amdgcn_s_setprio(0); } while (0)
; template <class Epi, bool ALIGN_EPI, int K, int LDA, int LDB>
; __device__ __forceinline__ void gemm_phase(LAS unsigned char* lds, const int wid, const Gemm g, const StaticOrder& S, const Epi& E) {
;     ...
;         const bool has_next = S.next(ui + 1, nxt);
;         const char* nA = has_next ? (const char*)g.A + (size_t)nxt.pm * tA : cA; const char* nB = has_next ? (const char*)g.Bt + (size_t)nxt.pn * tB : cB;
;         for (int t = 0; t < nt; t += 2) {
;             const bool last = (t == nt - 2);
;             const char* a1 = cA + (size_t)(t + 1) * kstep;
;             const char* a2 = last ? nA : cA + (size_t)(t + 2) * kstep; const char* b2 = last ? nB : cB + (size_t)(t + 2) * kstep;
;             const char* a3 = a2 + kstep; const char* b3 = b2 + kstep;
;             PG8_LDB(B0, 0, 0); PG8_LDB(B1, 0, 1); PG8_SCHED; PG8_LDA(At, 0, 0); PG8_STAGE(PG8_SA(1, 1), a1 + hA, voffA);
;             PG8_WAIT_V(8); PG8_WAIT_L(0); PG8_BAR; PG8_MMA(0, 0, At, B0); PG8_MMA(0, 1, At, B1); PG8_BAR; PG8_SCHED;
;             PG8_LDA(At, 0, 1); PG8_STAGE(PG8_SB(0, 0), b2, voffB); PG8_STAGE(PG8_SB(0, 1), b2 + hB, voffB); PG8_STAGE(PG8_SA(0, 0), a2, voffA);
;             PG8_WAIT_V(8); PG8_WAIT_L(0); PG8_BAR; PG8_MMA(1, 0, At, B0); PG8_MMA(1, 1, At, B1); PG8_BAR; PG8_SCHED;
.LBB0_1278:
	s_ashr_i32 s25, s24, 31
	s_lshl_b64 s[26:27], s[24:25], 19
	v_readlane_b32 s7, v254, 0
	s_add_u32 s26, s7, s26
	v_readlane_b32 s7, v254, 1
	s_addc_u32 s27, s7, s27
	s_and_b64 s[28:29], s[4:5], exec
	s_cselect_b32 s7, s27, s35
	s_cselect_b32 s25, s26, s34
	s_ashr_i32 s23, s22, 31
	s_lshl_b64 s[28:29], s[22:23], 19
	s_add_u32 s28, s0, s28
	s_addc_u32 s29, s1, s29
	s_and_b64 s[38:39], s[4:5], exec
	s_cselect_b32 s23, s29, s37
	s_cselect_b32 s42, s28, s36
	s_add_u32 s34, s34, 0x40080
	s_addc_u32 s35, s35, 0
	s_add_u32 s59, s36, 0x100
	s_addc_u32 s60, s37, 0
	s_mov_b32 s61, -2
	s_add_u32 s36, s34, 0xfffc0080
	s_addc_u32 s37, s35, -1
	s_cmp_eq_u32 s61, 12
	s_cselect_b32 s39, s7, s37
	s_cselect_b32 s38, s25, s36
	s_cselect_b32 s37, s23, s60
	s_cselect_b32 s36, s42, s59
	s_add_i32 m0, s31, 0xc000
	global_load_lds_dwordx4 v136, s[34:35]
	s_add_i32 m0, s31, 0xe000
	s_nop 0
	global_load_lds_dwordx4 v138, s[34:35]
	s_waitcnt vmcnt(8)
	s_barrier
	s_waitcnt lgkmcnt(0)
	v_mfma_f32_16x16x32_bf16 v[124:127], v[144:147], v[182:185], 0
	v_mfma_f32_16x16x32_bf16 v[120:123], v[158:161], v[182:185], 0
	v_mfma_f32_16x16x32_bf16 v[108:111], v[144:147], v[190:193], 0
	v_mfma_f32_16x16x32_bf16 v[104:107], v[158:161], v[190:193], 0
	v_mfma_f32_16x16x32_bf16 v[92:95], v[144:147], v[198:201], 0
	v_mfma_f32_16x16x32_bf16 v[88:91], v[158:161], v[198:201], 0
	v_mfma_f32_16x16x32_bf16 v[76:79], v[144:147], v[206:209], 0
	v_mfma_f32_16x16x32_bf16 v[72:75], v[158:161], v[206:209], 0
	v_mfma_f32_16x16x32_bf16 v[124:127], v[154:157], v[186:189], v[124:127]
	v_mfma_f32_16x16x32_bf16 v[120:123], v[162:165], v[186:189], v[120:123]
	v_mfma_f32_16x16x32_bf16 v[108:111], v[154:157], v[194:197], v[108:111]
	v_mfma_f32_16x16x32_bf16 v[104:107], v[162:165], v[194:197], v[104:107]
	v_mfma_f32_16x16x32_bf16 v[92:95], v[154:157], v[202:205], v[92:95]
	v_mfma_f32_16x16x32_bf16 v[88:91], v[162:165], v[202:205], v[88:91]
	v_mfma_f32_16x16x32_bf16 v[76:79], v[154:157], v[210:213], v[76:79]
	v_mfma_f32_16x16x32_bf16 v[72:75], v[162:165], v[210:213], v[72:75]
	v_mfma_f32_16x16x32_bf16 v[116:119], v[166:169], v[182:185], 0
	v_mfma_f32_16x16x32_bf16 v[112:115], v[174:177], v[182:185], 0
	v_mfma_f32_16x16x32_bf16 v[100:103], v[166:169], v[190:193], 0
	v_mfma_f32_16x16x32_bf16 v[96:99], v[174:177], v[190:193], 0
	v_mfma_f32_16x16x32_bf16 v[84:87], v[166:169], v[198:201], 0
	v_mfma_f32_16x16x32_bf16 v[80:83], v[174:177], v[198:201], 0
	v_mfma_f32_16x16x32_bf16 v[68:71], v[166:169], v[206:209], 0
	v_mfma_f32_16x16x32_bf16 v[64:67], v[174:177], v[206:209], 0
	v_mfma_f32_16x16x32_bf16 v[116:119], v[170:173], v[186:189], v[116:119]
	v_mfma_f32_16x16x32_bf16 v[112:115], v[178:181], v[186:189], v[112:115]
	v_mfma_f32_16x16x32_bf16 v[100:103], v[170:173], v[194:197], v[100:103]
	v_mfma_f32_16x16x32_bf16 v[96:99], v[178:181], v[194:197], v[96:99]
	v_mfma_f32_16x16x32_bf16 v[84:87], v[170:173], v[202:205], v[84:87]
	v_mfma_f32_16x16x32_bf16 v[80:83], v[178:181], v[202:205], v[80:83]
	v_mfma_f32_16x16x32_bf16 v[68:71], v[170:173], v[210:213], v[68:71]
	v_mfma_f32_16x16x32_bf16 v[64:67], v[178:181], v[210:213], v[64:67]
	s_barrier
	s_add_u32 s98, s36, s12
	s_addc_u32 s99, s37, s13
	s_add_u32 s100, s38, s12
	s_addc_u32 s101, s39, s13
	s_add_i32 s52, s57, s3
	s_mov_b32 m0, s52
	ds_read_b128 v[182:185], v153 offset:16384
	ds_read_b128 v[186:189], v153 offset:17408
	ds_read_b128 v[190:193], v153 offset:18432
	ds_read_b128 v[194:197], v153 offset:19456
	ds_read_b128 v[198:201], v153 offset:20480
	ds_read_b128 v[202:205], v153 offset:21504
	ds_read_b128 v[206:209], v153 offset:22528
	ds_read_b128 v[210:213], v153 offset:23552
	global_load_lds_dwordx4 v130, s[36:37]
	s_add_i32 m0, s52, 0x2000
	s_add_u32 s62, s36, 0x40000
	s_addc_u32 s63, s37, 0
	s_add_i32 s52, s58, s3
	global_load_lds_dwordx4 v134, s[36:37]
	s_mov_b32 m0, s52
	s_nop 0
	global_load_lds_dwordx4 v130, s[62:63]
	s_add_i32 m0, s52, 0x2000
	s_nop 0
	global_load_lds_dwordx4 v134, s[62:63]
	s_mov_b32 m0, s31
	s_nop 0
	global_load_lds_dwordx4 v128, s[38:39]
	s_mov_b32 m0, s33
	s_nop 0
	global_load_lds_dwordx4 v132, s[38:39]
	s_waitcnt vmcnt(8)
	s_barrier
	s_waitcnt lgkmcnt(0)
	v_mfma_f32_16x16x32_bf16 v[60:63], v[144:147], v[182:185], 0
	v_mfma_f32_16x16x32_bf16 v[56:59], v[158:161], v[182:185], 0
	v_mfma_f32_16x16x32_bf16 v[44:47], v[144:147], v[190:193], 0
	v_mfma_f32_16x16x32_bf16 v[40:43], v[158:161], v[190:193], 0
	v_mfma_f32_16x16x32_bf16 v[28:31], v[144:147], v[198:201], 0
	v_mfma_f32_16x16x32_bf16 v[24:27], v[158:161], v[198:201], 0
	v_mfma_f32_16x16x32_bf16 v[12:15], v[144:147], v[206:209], 0
	v_mfma_f32_16x16x32_bf16 v[8:11], v[158:161], v[206:209], 0
	v_mfma_f32_16x16x32_bf16 v[60:63], v[154:157], v[186:189], v[60:63]
	v_mfma_f32_16x16x32_bf16 v[56:59], v[162:165], v[186:189], v[56:59]
	v_mfma_f32_16x16x32_bf16 v[44:47], v[154:157], v[194:197], v[44:47]
	v_mfma_f32_16x16x32_bf16 v[40:43], v[162:165], v[194:197], v[40:43]
	v_mfma_f32_16x16x32_bf16 v[28:31], v[154:157], v[202:205], v[28:31]
	v_mfma_f32_16x16x32_bf16 v[24:27], v[162:165], v[202:205], v[24:27]
	v_mfma_f32_16x16x32_bf16 v[12:15], v[154:157], v[210:213], v[12:15]
	v_mfma_f32_16x16x32_bf16 v[8:11], v[162:165], v[210:213], v[8:11]
	v_mfma_f32_16x16x32_bf16 v[52:55], v[166:169], v[182:185], 0
	v_mfma_f32_16x16x32_bf16 v[48:51], v[174:177], v[182:185], 0
	v_mfma_f32_16x16x32_bf16 v[36:39], v[166:169], v[190:193], 0
	v_mfma_f32_16x16x32_bf16 v[32:35], v[174:177], v[190:193], 0
	v_mfma_f32_16x16x32_bf16 v[20:23], v[166:169], v[198:201], 0
	v_mfma_f32_16x16x32_bf16 v[16:19], v[174:177], v[198:201], 0
	v_mfma_f32_16x16x32_bf16 v[4:7], v[166:169], v[206:209], 0
	v_mfma_f32_16x16x32_bf16 v[0:3], v[174:177], v[206:209], 0
	v_mfma_f32_16x16x32_bf16 v[52:55], v[170:173], v[186:189], v[52:55]
	v_mfma_f32_16x16x32_bf16 v[48:51], v[178:181], v[186:189], v[48:51]
	v_mfma_f32_16x16x32_bf16 v[36:39], v[170:173], v[194:197], v[36:39]
	v_mfma_f32_16x16x32_bf16 v[32:35], v[178:181], v[194:197], v[32:35]
	v_mfma_f32_16x16x32_bf16 v[20:23], v[170:173], v[202:205], v[20:23]
	v_mfma_f32_16x16x32_bf16 v[16:19], v[178:181], v[202:205], v[16:19]
	v_mfma_f32_16x16x32_bf16 v[4:7], v[170:173], v[210:213], v[4:7]
	v_mfma_f32_16x16x32_bf16 v[0:3], v[178:181], v[210:213], v[0:3]
	s_barrier
; #define PG8_STAGE(bufoff, gbase, voff) do { _Pragma("unroll") for (int _i = 0; _i < 2; ++_i) \
;         __builtin_amdgcn_global_load_lds((const unsigned*)((const char*)(gbase) + (voff)[_i]), (LAS unsigned*)(lds + (bufoff) + ldsw + _i * 8192), 16, 0, 0); } while (0)
; #define PG8_LDA(dst, b, h) do { _Pragma("unroll") for (int m = 0; m < 4; ++m) _Pragma("unroll") for (int k = 0; k < 2; ++k) dst[m][k] = *(const LAS bf16x8*)(lds + PG8_SA(b, h) + aoff + m * 2048 + k * 1024); } while (0)
; #define PG8_LDB(dst, b, h) do { _Pragma("unroll") for (int n = 0; n < 2; ++n) _Pragma("unroll") for (int k = 0; k < 2; ++k) dst[n][k] = *(const LAS bf16x8*)(lds + PG8_SB(b, h) + boff + n * 2048 + k * 1024); } while (0)
; #define PG8_MMA(ai, bj, At, Bt) do { __builtin_amdgcn_s_setprio(1); _Pragma("unroll") for (int m = 0; m < 4; ++m) _Pragma("unroll") for (int n = 0; n < 2; ++n) _Pragma("unroll") for (int k = 0; k < 2; ++k) \
;         acc[ai][bj][m][n] = __builtin_amdgcn_mfma_f32_16x16x32_bf16(Bt[n][k], At[m][k], acc[ai][bj][m][n], 0, 0, 0); __builtin_amdgcn_s_setprio(0); } while (0)
; #define PG8_WAIT_V(n) asm volatile("s_waitcnt vmcnt(" #n ")" ::: "memory")
; #define PG8_WAIT_L(n) asm volatile("s_waitcnt lgkmcnt(" #n ")" ::: "memory")
; #define PG8_BAR __builtin_amdgcn_s_barrier()
; #define PG8_SCHED __builtin_amdgcn_sched_barrier(0)
; template <class Epi, bool ALIGN_EPI, int K, int LDA, int LDB>
; __device__ __forceinline__ void gemm_phase(LAS unsigned char* lds, const int wid, const Gemm g, const StaticOrder& S, const Epi& E) {
;     ...
;             PG8_LDB(B0, 1, 0); PG8_LDB(B1, 1, 1); PG8_SCHED; PG8_LDA(At, 1, 0); PG8_STAGE(PG8_SA(0, 1), a2 + hA, voffA);
;             PG8_WAIT_V(8); PG8_WAIT_L(0); PG8_BAR; PG8_MMA(0, 0, At, B0); PG8_MMA(0, 1, At, B1); PG8_BAR; PG8_SCHED;
;             PG8_LDA(At, 1, 1); PG8_STAGE(PG8_SB(1, 0), b3, voffB); PG8_STAGE(PG8_SB(1, 1), b3 + hB, voffB); PG8_STAGE(PG8_SA(1, 0), a3, voffA);
;             PG8_WAIT_V(8); PG8_WAIT_L(0); PG8_BAR; PG8_MMA(1, 0, At, B0); PG8_MMA(1, 1, At, B1); PG8_BAR; PG8_SCHED;
	s_add_i32 s52, 0, 0x18000
	s_add_i32 s53, 0, 0x1c000
	v_add_u32_e32 v162, s52, v150
	v_add_u32_e32 v178, s53, v150
	ds_read_b128 v[144:147], v162
	ds_read_b128 v[154:157], v162 offset:1024
	ds_read_b128 v[158:161], v162 offset:2048
	ds_read_b128 v[162:165], v162 offset:3072
	ds_read_b128 v[166:169], v178
	ds_read_b128 v[170:173], v178 offset:1024
	ds_read_b128 v[174:177], v178 offset:2048
	ds_read_b128 v[178:181], v178 offset:3072
	s_add_u32 s38, s38, 0x40000
	s_addc_u32 s39, s39, 0
	s_mov_b32 m0, s40
	ds_read_b128 v[182:185], v153 offset:32768
	ds_read_b128 v[186:189], v153 offset:33792
	ds_read_b128 v[190:193], v153 offset:34816
	ds_read_b128 v[194:197], v153 offset:35840
	ds_read_b128 v[198:201], v153 offset:36864
	ds_read_b128 v[202:205], v153 offset:37888
	ds_read_b128 v[206:209], v153 offset:38912
	ds_read_b128 v[210:213], v153 offset:39936
	global_load_lds_dwordx4 v128, s[38:39]
	s_mov_b32 m0, s41
	s_nop 0
	global_load_lds_dwordx4 v132, s[38:39]
	s_waitcnt vmcnt(8)
	s_barrier
	s_waitcnt lgkmcnt(0)
	v_mfma_f32_16x16x32_bf16 v[124:127], v[144:147], v[182:185], v[124:127]
	v_mfma_f32_16x16x32_bf16 v[120:123], v[158:161], v[182:185], v[120:123]
	v_mfma_f32_16x16x32_bf16 v[108:111], v[144:147], v[190:193], v[108:111]
	v_mfma_f32_16x16x32_bf16 v[104:107], v[158:161], v[190:193], v[104:107]
	v_mfma_f32_16x16x32_bf16 v[92:95], v[144:147], v[198:201], v[92:95]
	v_mfma_f32_16x16x32_bf16 v[88:91], v[158:161], v[198:201], v[88:91]
	v_mfma_f32_16x16x32_bf16 v[76:79], v[144:147], v[206:209], v[76:79]
	v_mfma_f32_16x16x32_bf16 v[72:75], v[158:161], v[206:209], v[72:75]
	v_mfma_f32_16x16x32_bf16 v[124:127], v[154:157], v[186:189], v[124:127]
	v_mfma_f32_16x16x32_bf16 v[120:123], v[162:165], v[186:189], v[120:123]
	v_mfma_f32_16x16x32_bf16 v[108:111], v[154:157], v[194:197], v[108:111]
	v_mfma_f32_16x16x32_bf16 v[104:107], v[162:165], v[194:197], v[104:107]
	v_mfma_f32_16x16x32_bf16 v[92:95], v[154:157], v[202:205], v[92:95]
	v_mfma_f32_16x16x32_bf16 v[88:91], v[162:165], v[202:205], v[88:91]
	v_mfma_f32_16x16x32_bf16 v[76:79], v[154:157], v[210:213], v[76:79]
	v_mfma_f32_16x16x32_bf16 v[72:75], v[162:165], v[210:213], v[72:75]
	v_mfma_f32_16x16x32_bf16 v[116:119], v[166:169], v[182:185], v[116:119]
	v_mfma_f32_16x16x32_bf16 v[112:115], v[174:177], v[182:185], v[112:115]
	v_mfma_f32_16x16x32_bf16 v[100:103], v[166:169], v[190:193], v[100:103]
	v_mfma_f32_16x16x32_bf16 v[96:99], v[174:177], v[190:193], v[96:99]
	v_mfma_f32_16x16x32_bf16 v[84:87], v[166:169], v[198:201], v[84:87]
	v_mfma_f32_16x16x32_bf16 v[80:83], v[174:177], v[198:201], v[80:83]
	v_mfma_f32_16x16x32_bf16 v[68:71], v[166:169], v[206:209], v[68:71]
	v_mfma_f32_16x16x32_bf16 v[64:67], v[174:177], v[206:209], v[64:67]
	v_mfma_f32_16x16x32_bf16 v[116:119], v[170:173], v[186:189], v[116:119]
	v_mfma_f32_16x16x32_bf16 v[112:115], v[178:181], v[186:189], v[112:115]
	v_mfma_f32_16x16x32_bf16 v[100:103], v[170:173], v[194:197], v[100:103]
	v_mfma_f32_16x16x32_bf16 v[96:99], v[178:181], v[194:197], v[96:99]
	v_mfma_f32_16x16x32_bf16 v[84:87], v[170:173], v[202:205], v[84:87]
	v_mfma_f32_16x16x32_bf16 v[80:83], v[178:181], v[202:205], v[80:83]
	v_mfma_f32_16x16x32_bf16 v[68:71], v[170:173], v[210:213], v[68:71]
	v_mfma_f32_16x16x32_bf16 v[64:67], v[178:181], v[210:213], v[64:67]
	s_barrier
	s_add_i32 s38, s52, s3
	s_mov_b32 m0, s38
	ds_read_b128 v[182:185], v153 offset:49152
	ds_read_b128 v[186:189], v153 offset:50176
	ds_read_b128 v[190:193], v153 offset:51200
	ds_read_b128 v[194:197], v153 offset:52224
	ds_read_b128 v[198:201], v153 offset:53248
	ds_read_b128 v[202:205], v153 offset:54272
	ds_read_b128 v[206:209], v153 offset:55296
	ds_read_b128 v[210:213], v153 offset:56320
	global_load_lds_dwordx4 v130, s[98:99]
	s_add_i32 m0, s38, 0x2000
	s_add_u32 s36, s36, 0x40080
	s_addc_u32 s37, s37, 0
	s_add_i32 s38, s53, s3
	global_load_lds_dwordx4 v134, s[98:99]
	s_mov_b32 m0, s38
	s_nop 0
	global_load_lds_dwordx4 v130, s[36:37]
	s_add_i32 m0, s38, 0x2000
	s_nop 0
	global_load_lds_dwordx4 v134, s[36:37]
	s_mov_b32 m0, s55
	s_nop 0
	global_load_lds_dwordx4 v128, s[100:101]
	s_mov_b32 m0, s56
	s_nop 0
	global_load_lds_dwordx4 v132, s[100:101]
	s_waitcnt vmcnt(8)
	s_barrier
	s_waitcnt lgkmcnt(0)
	v_mfma_f32_16x16x32_bf16 v[60:63], v[144:147], v[182:185], v[60:63]
	v_mfma_f32_16x16x32_bf16 v[56:59], v[158:161], v[182:185], v[56:59]
	v_mfma_f32_16x16x32_bf16 v[44:47], v[144:147], v[190:193], v[44:47]
	v_mfma_f32_16x16x32_bf16 v[40:43], v[158:161], v[190:193], v[40:43]
	v_mfma_f32_16x16x32_bf16 v[28:31], v[144:147], v[198:201], v[28:31]
	v_mfma_f32_16x16x32_bf16 v[24:27], v[158:161], v[198:201], v[24:27]
	v_mfma_f32_16x16x32_bf16 v[12:15], v[144:147], v[206:209], v[12:15]
	v_mfma_f32_16x16x32_bf16 v[8:11], v[158:161], v[206:209], v[8:11]
	v_mfma_f32_16x16x32_bf16 v[60:63], v[154:157], v[186:189], v[60:63]
	v_mfma_f32_16x16x32_bf16 v[56:59], v[162:165], v[186:189], v[56:59]
	v_mfma_f32_16x16x32_bf16 v[44:47], v[154:157], v[194:197], v[44:47]
	v_mfma_f32_16x16x32_bf16 v[40:43], v[162:165], v[194:197], v[40:43]
	v_mfma_f32_16x16x32_bf16 v[28:31], v[154:157], v[202:205], v[28:31]
	v_mfma_f32_16x16x32_bf16 v[24:27], v[162:165], v[202:205], v[24:27]
	v_mfma_f32_16x16x32_bf16 v[12:15], v[154:157], v[210:213], v[12:15]
	v_mfma_f32_16x16x32_bf16 v[8:11], v[162:165], v[210:213], v[8:11]
	v_mfma_f32_16x16x32_bf16 v[52:55], v[166:169], v[182:185], v[52:55]
	v_mfma_f32_16x16x32_bf16 v[48:51], v[174:177], v[182:185], v[48:51]
	v_mfma_f32_16x16x32_bf16 v[36:39], v[166:169], v[190:193], v[36:39]
	v_mfma_f32_16x16x32_bf16 v[32:35], v[174:177], v[190:193], v[32:35]
	v_mfma_f32_16x16x32_bf16 v[20:23], v[166:169], v[198:201], v[20:23]
	v_mfma_f32_16x16x32_bf16 v[16:19], v[174:177], v[198:201], v[16:19]
	v_mfma_f32_16x16x32_bf16 v[4:7], v[166:169], v[206:209], v[4:7]
	v_mfma_f32_16x16x32_bf16 v[0:3], v[174:177], v[206:209], v[0:3]
	v_mfma_f32_16x16x32_bf16 v[52:55], v[170:173], v[186:189], v[52:55]
	v_mfma_f32_16x16x32_bf16 v[48:51], v[178:181], v[186:189], v[48:51]
	v_mfma_f32_16x16x32_bf16 v[36:39], v[170:173], v[194:197], v[36:39]
	v_mfma_f32_16x16x32_bf16 v[32:35], v[178:181], v[194:197], v[32:35]
	v_mfma_f32_16x16x32_bf16 v[20:23], v[170:173], v[202:205], v[20:23]
	v_mfma_f32_16x16x32_bf16 v[16:19], v[178:181], v[202:205], v[16:19]
	v_mfma_f32_16x16x32_bf16 v[4:7], v[170:173], v[210:213], v[4:7]
	v_mfma_f32_16x16x32_bf16 v[0:3], v[178:181], v[210:213], v[0:3]
	s_barrier
	s_add_i32 s61, s61, 2
	s_add_u32 s34, s34, 0x100
	s_addc_u32 s35, s35, 0
	s_add_u32 s59, s59, 0x100
	s_addc_u32 s60, s60, 0
; #define PG8_STAGE(bufoff, gbase, voff) do { _Pragma("unroll") for (int _i = 0; _i < 2; ++_i) \
;         __builtin_amdgcn_global_load_lds((const unsigned*)((const char*)(gbase) + (voff)[_i]), (LAS unsigned*)(lds + (bufoff) + ldsw + _i * 8192), 16, 0, 0); } while (0)
; #define PG8_LDA(dst, b, h) do { _Pragma("unroll") for (int m = 0; m < 4; ++m) _Pragma("unroll") for (int k = 0; k < 2; ++k) dst[m][k] = *(const LAS bf16x8*)(lds + PG8_SA(b, h) + aoff + m * 2048 + k * 1024); } while (0)
; #define PG8_LDB(dst, b, h) do { _Pragma("unroll") for (int n = 0; n < 2; ++n) _Pragma("unroll") for (int k = 0; k < 2; ++k) dst[n][k] = *(const LAS bf16x8*)(lds + PG8_SB(b, h) + boff + n * 2048 + k * 1024); } while (0)
; #define PG8_MMA(ai, bj, At, Bt) do { __builtin_amdgcn_s_setprio(1); _Pragma("unroll") for (int m = 0; m < 4; ++m) _Pragma("unroll") for (int n = 0; n < 2; ++n) _Pragma("unroll") for (int k = 0; k < 2; ++k) \
;         acc[ai][bj][m][n] = __builtin_amdgcn_mfma_f32_16x16x32_bf16(Bt[n][k], At[m][k], acc[ai][bj][m][n], 0, 0, 0); __builtin_amdgcn_s_setprio(0); } while (0)
; #define PG8_WAIT_V(n) asm volatile("s_waitcnt vmcnt(" #n ")" ::: "memory")
; #define PG8_WAIT_L(n) asm volatile("s_waitcnt lgkmcnt(" #n ")" ::: "memory")
; #define PG8_BAR __builtin_amdgcn_s_barrier()
; template <class Epi, bool ALIGN_EPI, int K, int LDA, int LDB>
; __device__ __forceinline__ void gemm_phase(LAS unsigned char* lds, const int wid, const Gemm g, const StaticOrder& S, const Epi& E) {
;     ...
;         for (int t = 0; t < nt; t += 2) {
;             const bool last = (t == nt - 2);
;             const char* a1 = cA + (size_t)(t + 1) * kstep;
;             const char* a2 = last ? nA : cA + (size_t)(t + 2) * kstep; const char* b2 = last ? nB : cB + (size_t)(t + 2) * kstep;
;             const char* a3 = a2 + kstep; const char* b3 = b2 + kstep;
;             PG8_LDB(B0, 0, 0); PG8_LDB(B1, 0, 1); PG8_SCHED; PG8_LDA(At, 0, 0); PG8_STAGE(PG8_SA(1, 1), a1 + hA, voffA);
;             PG8_WAIT_V(8); PG8_WAIT_L(0); PG8_BAR; PG8_MMA(0, 0, At, B0); PG8_MMA(0, 1, At, B1); PG8_BAR; PG8_SCHED;
;             PG8_LDA(At, 0, 1); PG8_STAGE(PG8_SB(0, 0), b2, voffB); PG8_STAGE(PG8_SB(0, 1), b2 + hB, voffB); PG8_STAGE(PG8_SA(0, 0), a2, voffA);
;             PG8_WAIT_V(8); PG8_WAIT_L(0); PG8_BAR; PG8_MMA(1, 0, At, B0); PG8_MMA(1, 1, At, B1); PG8_BAR; PG8_SCHED;
.LBB0_1279:
	ds_read_b128 v[144:147], v151
	ds_read_b128 v[154:157], v151 offset:1024
	ds_read_b128 v[158:161], v151 offset:2048
	ds_read_b128 v[162:165], v151 offset:3072
	ds_read_b128 v[166:169], v152
	ds_read_b128 v[170:173], v152 offset:1024
	ds_read_b128 v[174:177], v152 offset:2048
	ds_read_b128 v[178:181], v152 offset:3072
	s_add_u32 s36, s34, 0xfffc0080
	s_addc_u32 s37, s35, -1
	s_cmp_eq_u32 s61, 12
	s_cselect_b32 s39, s7, s37
	s_cselect_b32 s38, s25, s36
	s_cselect_b32 s37, s23, s60
	s_cselect_b32 s36, s42, s59
	s_add_i32 m0, s31, 0xc000
	ds_read_b128 v[182:185], v153
	ds_read_b128 v[186:189], v153 offset:1024
	ds_read_b128 v[190:193], v153 offset:2048
	ds_read_b128 v[194:197], v153 offset:3072
	ds_read_b128 v[198:201], v153 offset:4096
	ds_read_b128 v[202:205], v153 offset:5120
	ds_read_b128 v[206:209], v153 offset:6144
	ds_read_b128 v[210:213], v153 offset:7168
	global_load_lds_dwordx4 v136, s[34:35]
	s_add_i32 m0, s31, 0xe000
	s_nop 0
	global_load_lds_dwordx4 v138, s[34:35]
	s_waitcnt vmcnt(8)
	s_barrier
	s_waitcnt lgkmcnt(0)
	v_mfma_f32_16x16x32_bf16 v[124:127], v[144:147], v[182:185], v[124:127]
	v_mfma_f32_16x16x32_bf16 v[120:123], v[158:161], v[182:185], v[120:123]
	v_mfma_f32_16x16x32_bf16 v[108:111], v[144:147], v[190:193], v[108:111]
	v_mfma_f32_16x16x32_bf16 v[104:107], v[158:161], v[190:193], v[104:107]
	v_mfma_f32_16x16x32_bf16 v[92:95], v[144:147], v[198:201], v[92:95]
	v_mfma_f32_16x16x32_bf16 v[88:91], v[158:161], v[198:201], v[88:91]
	v_mfma_f32_16x16x32_bf16 v[76:79], v[144:147], v[206:209], v[76:79]
	v_mfma_f32_16x16x32_bf16 v[72:75], v[158:161], v[206:209], v[72:75]
	v_mfma_f32_16x16x32_bf16 v[124:127], v[154:157], v[186:189], v[124:127]
	v_mfma_f32_16x16x32_bf16 v[120:123], v[162:165], v[186:189], v[120:123]
	v_mfma_f32_16x16x32_bf16 v[108:111], v[154:157], v[194:197], v[108:111]
	v_mfma_f32_16x16x32_bf16 v[104:107], v[162:165], v[194:197], v[104:107]
	v_mfma_f32_16x16x32_bf16 v[92:95], v[154:157], v[202:205], v[92:95]
	v_mfma_f32_16x16x32_bf16 v[88:91], v[162:165], v[202:205], v[88:91]
	v_mfma_f32_16x16x32_bf16 v[76:79], v[154:157], v[210:213], v[76:79]
	v_mfma_f32_16x16x32_bf16 v[72:75], v[162:165], v[210:213], v[72:75]
	v_mfma_f32_16x16x32_bf16 v[116:119], v[166:169], v[182:185], v[116:119]
	v_mfma_f32_16x16x32_bf16 v[112:115], v[174:177], v[182:185], v[112:115]
	v_mfma_f32_16x16x32_bf16 v[100:103], v[166:169], v[190:193], v[100:103]
	v_mfma_f32_16x16x32_bf16 v[96:99], v[174:177], v[190:193], v[96:99]
	v_mfma_f32_16x16x32_bf16 v[84:87], v[166:169], v[198:201], v[84:87]
	v_mfma_f32_16x16x32_bf16 v[80:83], v[174:177], v[198:201], v[80:83]
	v_mfma_f32_16x16x32_bf16 v[68:71], v[166:169], v[206:209], v[68:71]
	v_mfma_f32_16x16x32_bf16 v[64:67], v[174:177], v[206:209], v[64:67]
	v_mfma_f32_16x16x32_bf16 v[116:119], v[170:173], v[186:189], v[116:119]
	v_mfma_f32_16x16x32_bf16 v[112:115], v[178:181], v[186:189], v[112:115]
	v_mfma_f32_16x16x32_bf16 v[100:103], v[170:173], v[194:197], v[100:103]
	v_mfma_f32_16x16x32_bf16 v[96:99], v[178:181], v[194:197], v[96:99]
	v_mfma_f32_16x16x32_bf16 v[84:87], v[170:173], v[202:205], v[84:87]
	v_mfma_f32_16x16x32_bf16 v[80:83], v[178:181], v[202:205], v[80:83]
	v_mfma_f32_16x16x32_bf16 v[68:71], v[170:173], v[210:213], v[68:71]
	v_mfma_f32_16x16x32_bf16 v[64:67], v[178:181], v[210:213], v[64:67]
	s_barrier
	s_add_u32 s98, s36, s12
	s_addc_u32 s99, s37, s13
	s_add_u32 s100, s38, s12
	s_addc_u32 s101, s39, s13
	s_add_i32 s52, s57, s3
	s_mov_b32 m0, s52
	ds_read_b128 v[182:185], v153 offset:16384
	ds_read_b128 v[186:189], v153 offset:17408
	ds_read_b128 v[190:193], v153 offset:18432
	ds_read_b128 v[194:197], v153 offset:19456
	ds_read_b128 v[198:201], v153 offset:20480
	ds_read_b128 v[202:205], v153 offset:21504
	ds_read_b128 v[206:209], v153 offset:22528
	ds_read_b128 v[210:213], v153 offset:23552
	global_load_lds_dwordx4 v130, s[36:37]
	s_add_i32 m0, s52, 0x2000
	s_add_u32 s62, s36, 0x40000
	s_addc_u32 s63, s37, 0
	s_add_i32 s52, s58, s3
	global_load_lds_dwordx4 v134, s[36:37]
	s_mov_b32 m0, s52
	s_nop 0
	global_load_lds_dwordx4 v130, s[62:63]
	s_add_i32 m0, s52, 0x2000
	s_nop 0
	global_load_lds_dwordx4 v134, s[62:63]
	s_mov_b32 m0, s31
	s_nop 0
	global_load_lds_dwordx4 v128, s[38:39]
	s_mov_b32 m0, s33
	s_nop 0
	global_load_lds_dwordx4 v132, s[38:39]
	s_waitcnt vmcnt(8)
	s_barrier
	s_waitcnt lgkmcnt(0)
	v_mfma_f32_16x16x32_bf16 v[60:63], v[144:147], v[182:185], v[60:63]
	v_mfma_f32_16x16x32_bf16 v[56:59], v[158:161], v[182:185], v[56:59]
	v_mfma_f32_16x16x32_bf16 v[44:47], v[144:147], v[190:193], v[44:47]
	v_mfma_f32_16x16x32_bf16 v[40:43], v[158:161], v[190:193], v[40:43]
	v_mfma_f32_16x16x32_bf16 v[28:31], v[144:147], v[198:201], v[28:31]
	v_mfma_f32_16x16x32_bf16 v[24:27], v[158:161], v[198:201], v[24:27]
	v_mfma_f32_16x16x32_bf16 v[12:15], v[144:147], v[206:209], v[12:15]
	v_mfma_f32_16x16x32_bf16 v[8:11], v[158:161], v[206:209], v[8:11]
	v_mfma_f32_16x16x32_bf16 v[60:63], v[154:157], v[186:189], v[60:63]
	v_mfma_f32_16x16x32_bf16 v[56:59], v[162:165], v[186:189], v[56:59]
	v_mfma_f32_16x16x32_bf16 v[44:47], v[154:157], v[194:197], v[44:47]
	v_mfma_f32_16x16x32_bf16 v[40:43], v[162:165], v[194:197], v[40:43]
	v_mfma_f32_16x16x32_bf16 v[28:31], v[154:157], v[202:205], v[28:31]
	v_mfma_f32_16x16x32_bf16 v[24:27], v[162:165], v[202:205], v[24:27]
	v_mfma_f32_16x16x32_bf16 v[12:15], v[154:157], v[210:213], v[12:15]
	v_mfma_f32_16x16x32_bf16 v[8:11], v[162:165], v[210:213], v[8:11]
	v_mfma_f32_16x16x32_bf16 v[52:55], v[166:169], v[182:185], v[52:55]
	v_mfma_f32_16x16x32_bf16 v[48:51], v[174:177], v[182:185], v[48:51]
	v_mfma_f32_16x16x32_bf16 v[36:39], v[166:169], v[190:193], v[36:39]
	v_mfma_f32_16x16x32_bf16 v[32:35], v[174:177], v[190:193], v[32:35]
	v_mfma_f32_16x16x32_bf16 v[20:23], v[166:169], v[198:201], v[20:23]
	v_mfma_f32_16x16x32_bf16 v[16:19], v[174:177], v[198:201], v[16:19]
	v_mfma_f32_16x16x32_bf16 v[4:7], v[166:169], v[206:209], v[4:7]
	v_mfma_f32_16x16x32_bf16 v[0:3], v[174:177], v[206:209], v[0:3]
	v_mfma_f32_16x16x32_bf16 v[52:55], v[170:173], v[186:189], v[52:55]
	v_mfma_f32_16x16x32_bf16 v[48:51], v[178:181], v[186:189], v[48:51]
	v_mfma_f32_16x16x32_bf16 v[36:39], v[170:173], v[194:197], v[36:39]
	v_mfma_f32_16x16x32_bf16 v[32:35], v[178:181], v[194:197], v[32:35]
	v_mfma_f32_16x16x32_bf16 v[20:23], v[170:173], v[202:205], v[20:23]
	v_mfma_f32_16x16x32_bf16 v[16:19], v[178:181], v[202:205], v[16:19]
	v_mfma_f32_16x16x32_bf16 v[4:7], v[170:173], v[210:213], v[4:7]
	v_mfma_f32_16x16x32_bf16 v[0:3], v[178:181], v[210:213], v[0:3]
	s_barrier
; #define PG8_STAGE(bufoff, gbase, voff) do { _Pragma("unroll") for (int _i = 0; _i < 2; ++_i) \
;         __builtin_amdgcn_global_load_lds((const unsigned*)((const char*)(gbase) + (voff)[_i]), (LAS unsigned*)(lds + (bufoff) + ldsw + _i * 8192), 16, 0, 0); } while (0)
; #define PG8_LDA(dst, b, h) do { _Pragma("unroll") for (int m = 0; m < 4; ++m) _Pragma("unroll") for (int k = 0; k < 2; ++k) dst[m][k] = *(const LAS bf16x8*)(lds + PG8_SA(b, h) + aoff + m * 2048 + k * 1024); } while (0)
; #define PG8_LDB(dst, b, h) do { _Pragma("unroll") for (int n = 0; n < 2; ++n) _Pragma("unroll") for (int k = 0; k < 2; ++k) dst[n][k] = *(const LAS bf16x8*)(lds + PG8_SB(b, h) + boff + n * 2048 + k * 1024); } while (0)
; #define PG8_MMA(ai, bj, At, Bt) do { __builtin_amdgcn_s_setprio(1); _Pragma("unroll") for (int m = 0; m < 4; ++m) _Pragma("unroll") for (int n = 0; n < 2; ++n) _Pragma("unroll") for (int k = 0; k < 2; ++k) \
;         acc[ai][bj][m][n] = __builtin_amdgcn_mfma_f32_16x16x32_bf16(Bt[n][k], At[m][k], acc[ai][bj][m][n], 0, 0, 0); __builtin_amdgcn_s_setprio(0); } while (0)
; #define PG8_WAIT_V(n) asm volatile("s_waitcnt vmcnt(" #n ")" ::: "memory")
; #define PG8_WAIT_L(n) asm volatile("s_waitcnt lgkmcnt(" #n ")" ::: "memory")
; #define PG8_BAR __builtin_amdgcn_s_barrier()
; #define PG8_SCHED __builtin_amdgcn_sched_barrier(0)
; template <class Epi, bool ALIGN_EPI, int K, int LDA, int LDB>
; __device__ __forceinline__ void gemm_phase(LAS unsigned char* lds, const int wid, const Gemm g, const StaticOrder& S, const Epi& E) {
;     ...
;             PG8_LDB(B0, 1, 0); PG8_LDB(B1, 1, 1); PG8_SCHED; PG8_LDA(At, 1, 0); PG8_STAGE(PG8_SA(0, 1), a2 + hA, voffA);
;             PG8_WAIT_V(8); PG8_WAIT_L(0); PG8_BAR; PG8_MMA(0, 0, At, B0); PG8_MMA(0, 1, At, B1); PG8_BAR; PG8_SCHED;
;             PG8_LDA(At, 1, 1); PG8_STAGE(PG8_SB(1, 0), b3, voffB); PG8_STAGE(PG8_SB(1, 1), b3 + hB, voffB); PG8_STAGE(PG8_SA(1, 0), a3, voffA);
;             PG8_WAIT_V(8); PG8_WAIT_L(0); PG8_BAR; PG8_MMA(1, 0, At, B0); PG8_MMA(1, 1, At, B1); PG8_BAR; PG8_SCHED;
;         }
	s_add_i32 s52, 0, 0x18000
	s_add_i32 s53, 0, 0x1c000
	v_add_u32_e32 v162, s52, v150
	v_add_u32_e32 v178, s53, v150
	ds_read_b128 v[144:147], v162
	ds_read_b128 v[154:157], v162 offset:1024
	ds_read_b128 v[158:161], v162 offset:2048
	ds_read_b128 v[162:165], v162 offset:3072
	ds_read_b128 v[166:169], v178
	ds_read_b128 v[170:173], v178 offset:1024
	ds_read_b128 v[174:177], v178 offset:2048
	ds_read_b128 v[178:181], v178 offset:3072
	s_add_u32 s38, s38, 0x40000
	s_addc_u32 s39, s39, 0
	s_mov_b32 m0, s40
	ds_read_b128 v[182:185], v153 offset:32768
	ds_read_b128 v[186:189], v153 offset:33792
	ds_read_b128 v[190:193], v153 offset:34816
	ds_read_b128 v[194:197], v153 offset:35840
	ds_read_b128 v[198:201], v153 offset:36864
	ds_read_b128 v[202:205], v153 offset:37888
	ds_read_b128 v[206:209], v153 offset:38912
	ds_read_b128 v[210:213], v153 offset:39936
	global_load_lds_dwordx4 v128, s[38:39]
	s_mov_b32 m0, s41
	s_nop 0
	global_load_lds_dwordx4 v132, s[38:39]
	s_waitcnt vmcnt(8)
	s_barrier
	s_waitcnt lgkmcnt(0)
	v_mfma_f32_16x16x32_bf16 v[124:127], v[144:147], v[182:185], v[124:127]
	v_mfma_f32_16x16x32_bf16 v[120:123], v[158:161], v[182:185], v[120:123]
	v_mfma_f32_16x16x32_bf16 v[108:111], v[144:147], v[190:193], v[108:111]
	v_mfma_f32_16x16x32_bf16 v[104:107], v[158:161], v[190:193], v[104:107]
	v_mfma_f32_16x16x32_bf16 v[92:95], v[144:147], v[198:201], v[92:95]
	v_mfma_f32_16x16x32_bf16 v[88:91], v[158:161], v[198:201], v[88:91]
	v_mfma_f32_16x16x32_bf16 v[76:79], v[144:147], v[206:209], v[76:79]
	v_mfma_f32_16x16x32_bf16 v[72:75], v[158:161], v[206:209], v[72:75]
	v_mfma_f32_16x16x32_bf16 v[124:127], v[154:157], v[186:189], v[124:127]
	v_mfma_f32_16x16x32_bf16 v[120:123], v[162:165], v[186:189], v[120:123]
	v_mfma_f32_16x16x32_bf16 v[108:111], v[154:157], v[194:197], v[108:111]
	v_mfma_f32_16x16x32_bf16 v[104:107], v[162:165], v[194:197], v[104:107]
	v_mfma_f32_16x16x32_bf16 v[92:95], v[154:157], v[202:205], v[92:95]
	v_mfma_f32_16x16x32_bf16 v[88:91], v[162:165], v[202:205], v[88:91]
	v_mfma_f32_16x16x32_bf16 v[76:79], v[154:157], v[210:213], v[76:79]
	v_mfma_f32_16x16x32_bf16 v[72:75], v[162:165], v[210:213], v[72:75]
	v_mfma_f32_16x16x32_bf16 v[116:119], v[166:169], v[182:185], v[116:119]
	v_mfma_f32_16x16x32_bf16 v[112:115], v[174:177], v[182:185], v[112:115]
	v_mfma_f32_16x16x32_bf16 v[100:103], v[166:169], v[190:193], v[100:103]
	v_mfma_f32_16x16x32_bf16 v[96:99], v[174:177], v[190:193], v[96:99]
	v_mfma_f32_16x16x32_bf16 v[84:87], v[166:169], v[198:201], v[84:87]
	v_mfma_f32_16x16x32_bf16 v[80:83], v[174:177], v[198:201], v[80:83]
	v_mfma_f32_16x16x32_bf16 v[68:71], v[166:169], v[206:209], v[68:71]
	v_mfma_f32_16x16x32_bf16 v[64:67], v[174:177], v[206:209], v[64:67]
	v_mfma_f32_16x16x32_bf16 v[116:119], v[170:173], v[186:189], v[116:119]
	v_mfma_f32_16x16x32_bf16 v[112:115], v[178:181], v[186:189], v[112:115]
	v_mfma_f32_16x16x32_bf16 v[100:103], v[170:173], v[194:197], v[100:103]
	v_mfma_f32_16x16x32_bf16 v[96:99], v[178:181], v[194:197], v[96:99]
	v_mfma_f32_16x16x32_bf16 v[84:87], v[170:173], v[202:205], v[84:87]
	v_mfma_f32_16x16x32_bf16 v[80:83], v[178:181], v[202:205], v[80:83]
	v_mfma_f32_16x16x32_bf16 v[68:71], v[170:173], v[210:213], v[68:71]
	v_mfma_f32_16x16x32_bf16 v[64:67], v[178:181], v[210:213], v[64:67]
	s_barrier
	s_add_i32 s38, s52, s3
	s_mov_b32 m0, s38
	ds_read_b128 v[182:185], v153 offset:49152
	ds_read_b128 v[186:189], v153 offset:50176
	ds_read_b128 v[190:193], v153 offset:51200
	ds_read_b128 v[194:197], v153 offset:52224
	ds_read_b128 v[198:201], v153 offset:53248
	ds_read_b128 v[202:205], v153 offset:54272
	ds_read_b128 v[206:209], v153 offset:55296
	ds_read_b128 v[210:213], v153 offset:56320
	global_load_lds_dwordx4 v130, s[98:99]
	s_add_i32 m0, s38, 0x2000
	s_add_u32 s36, s36, 0x40080
	s_addc_u32 s37, s37, 0
	s_add_i32 s38, s53, s3
	global_load_lds_dwordx4 v134, s[98:99]
	s_mov_b32 m0, s38
	s_nop 0
	global_load_lds_dwordx4 v130, s[36:37]
	s_add_i32 m0, s38, 0x2000
	s_nop 0
	global_load_lds_dwordx4 v134, s[36:37]
	s_mov_b32 m0, s55
	s_nop 0
	global_load_lds_dwordx4 v128, s[100:101]
	s_mov_b32 m0, s56
	s_nop 0
	global_load_lds_dwordx4 v132, s[100:101]
	s_waitcnt vmcnt(8)
	s_barrier
	s_waitcnt lgkmcnt(0)
	v_mfma_f32_16x16x32_bf16 v[60:63], v[144:147], v[182:185], v[60:63]
	v_mfma_f32_16x16x32_bf16 v[56:59], v[158:161], v[182:185], v[56:59]
	v_mfma_f32_16x16x32_bf16 v[44:47], v[144:147], v[190:193], v[44:47]
	v_mfma_f32_16x16x32_bf16 v[40:43], v[158:161], v[190:193], v[40:43]
	v_mfma_f32_16x16x32_bf16 v[28:31], v[144:147], v[198:201], v[28:31]
	v_mfma_f32_16x16x32_bf16 v[24:27], v[158:161], v[198:201], v[24:27]
	v_mfma_f32_16x16x32_bf16 v[12:15], v[144:147], v[206:209], v[12:15]
	v_mfma_f32_16x16x32_bf16 v[8:11], v[158:161], v[206:209], v[8:11]
	v_mfma_f32_16x16x32_bf16 v[60:63], v[154:157], v[186:189], v[60:63]
	v_mfma_f32_16x16x32_bf16 v[56:59], v[162:165], v[186:189], v[56:59]
	v_mfma_f32_16x16x32_bf16 v[44:47], v[154:157], v[194:197], v[44:47]
	v_mfma_f32_16x16x32_bf16 v[40:43], v[162:165], v[194:197], v[40:43]
	v_mfma_f32_16x16x32_bf16 v[28:31], v[154:157], v[202:205], v[28:31]
	v_mfma_f32_16x16x32_bf16 v[24:27], v[162:165], v[202:205], v[24:27]
	v_mfma_f32_16x16x32_bf16 v[12:15], v[154:157], v[210:213], v[12:15]
	v_mfma_f32_16x16x32_bf16 v[8:11], v[162:165], v[210:213], v[8:11]
	v_mfma_f32_16x16x32_bf16 v[52:55], v[166:169], v[182:185], v[52:55]
	v_mfma_f32_16x16x32_bf16 v[48:51], v[174:177], v[182:185], v[48:51]
	v_mfma_f32_16x16x32_bf16 v[36:39], v[166:169], v[190:193], v[36:39]
	v_mfma_f32_16x16x32_bf16 v[32:35], v[174:177], v[190:193], v[32:35]
	v_mfma_f32_16x16x32_bf16 v[20:23], v[166:169], v[198:201], v[20:23]
	v_mfma_f32_16x16x32_bf16 v[16:19], v[174:177], v[198:201], v[16:19]
	v_mfma_f32_16x16x32_bf16 v[4:7], v[166:169], v[206:209], v[4:7]
	v_mfma_f32_16x16x32_bf16 v[0:3], v[174:177], v[206:209], v[0:3]
	v_mfma_f32_16x16x32_bf16 v[52:55], v[170:173], v[186:189], v[52:55]
	v_mfma_f32_16x16x32_bf16 v[48:51], v[178:181], v[186:189], v[48:51]
	v_mfma_f32_16x16x32_bf16 v[36:39], v[170:173], v[194:197], v[36:39]
	v_mfma_f32_16x16x32_bf16 v[32:35], v[178:181], v[194:197], v[32:35]
	v_mfma_f32_16x16x32_bf16 v[20:23], v[170:173], v[202:205], v[20:23]
	v_mfma_f32_16x16x32_bf16 v[16:19], v[178:181], v[202:205], v[16:19]
	v_mfma_f32_16x16x32_bf16 v[4:7], v[170:173], v[210:213], v[4:7]
	v_mfma_f32_16x16x32_bf16 v[0:3], v[178:181], v[210:213], v[0:3]
	s_barrier
	s_add_i32 s61, s61, 2
	s_add_u32 s34, s34, 0x100
	s_addc_u32 s35, s35, 0
	s_add_u32 s59, s59, 0x100
	s_addc_u32 s60, s60, 0
	s_cmp_gt_u32 s61, 13
	s_cbranch_scc0 .LBB0_1279
	s_and_b64 vcc, exec, s[10:11]
	s_cbranch_vccz .LBB0_1282
	s_barrier

; #define PG8_STAGE(bufoff, gbase, voff) do { _Pragma("unroll") for (int _i = 0; _i < 2; ++_i) \
;         __builtin_amdgcn_global_load_lds((const unsigned*)((const char*)(gbase) + (voff)[_i]), (LAS unsigned*)(lds + (bufoff) + ldsw + _i * 8192), 16, 0, 0); } while (0)
; #define PG8_LDA(dst, b, h) do { _Pragma("unroll") for (int m = 0; m < 4; ++m) _Pragma("unroll") for (int k = 0; k < 2; ++k) dst[m][k] = *(const LAS bf16x8*)(lds + PG8_SA(b, h) + aoff + m * 2048 + k * 1024); } while (0)
; #define PG8_LDB(dst, b, h) do { _Pragma("unroll") for (int n = 0; n < 2; ++n) _Pragma("unroll") for (int k = 0; k < 2; ++k) dst[n][k] = *(const LAS bf16x8*)(lds + PG8_SB(b, h) + boff + n * 2048 + k * 1024); } while (0)
; #define PG8_MMA(ai, bj, At, Bt) do { __builtin_amdgcn_s_setprio(1); _Pragma("unroll") for (int m = 0; m < 4; ++m) _Pragma("unroll") for (int n = 0; n < 2; ++n) _Pragma("unroll") for (int k = 0; k < 2; ++k) \
;         acc[ai][bj][m][n] = __builtin_amdgcn_mfma_f32_16x16x32_bf16(Bt[n][k], At[m][k], acc[ai][bj][m][n], 0, 0, 0); __builtin_amdgcn_s_setprio(0); } while (0)
; template <class Epi, bool ALIGN_EPI, int K, int LDA, int LDB>
; __device__ __forceinline__ void gemm_phase(LAS unsigned char* lds, const int wid, const Gemm g, const StaticOrder& S, const Epi& E) {
;     ...
;         const bool has_next = S.next(ui + 1, nxt);
;         const char* nA = has_next ? (const char*)g.A + (size_t)nxt.pm * tA : cA; const char* nB = has_next ? (const char*)g.Bt + (size_t)nxt.pn * tB : cB;
;         for (int t = 0; t < nt; t += 2) {
;             const bool last = (t == nt - 2);
;             const char* a1 = cA + (size_t)(t + 1) * kstep;
;             const char* a2 = last ? nA : cA + (size_t)(t + 2) * kstep; const char* b2 = last ? nB : cB + (size_t)(t + 2) * kstep;
;             const char* a3 = a2 + kstep; const char* b3 = b2 + kstep;
;             PG8_LDB(B0, 0, 0); PG8_LDB(B1, 0, 1); PG8_SCHED; PG8_LDA(At, 0, 0); PG8_STAGE(PG8_SA(1, 1), a1 + hA, voffA);
;             PG8_WAIT_V(8); PG8_WAIT_L(0); PG8_BAR; PG8_MMA(0, 0, At, B0); PG8_MMA(0, 1, At, B1); PG8_BAR; PG8_SCHED;
;             PG8_LDA(At, 0, 1); PG8_STAGE(PG8_SB(0, 0), b2, voffB); PG8_STAGE(PG8_SB(0, 1), b2 + hB, voffB); PG8_STAGE(PG8_SA(0, 0), a2, voffA);
;             PG8_WAIT_V(8); PG8_WAIT_L(0); PG8_BAR; PG8_MMA(1, 0, At, B0); PG8_MMA(1, 1, At, B1); PG8_BAR; PG8_SCHED;
.LBB0_1476:
	s_ashr_i32 s25, s24, 31
	s_lshl_b64 s[26:27], s[24:25], 19
	v_readlane_b32 s23, v254, 0
	s_add_u32 s26, s23, s26
	v_readlane_b32 s23, v254, 1
	s_addc_u32 s27, s23, s27
	s_and_b64 s[28:29], s[4:5], exec
	s_cselect_b32 s25, s27, s35
	s_cselect_b32 s42, s26, s34
	s_ashr_i32 s23, s22, 31
	s_lshl_b64 s[28:29], s[22:23], 19
	s_add_u32 s28, s1, s28
	s_addc_u32 s29, s3, s29
	s_and_b64 s[38:39], s[4:5], exec
	s_cselect_b32 s23, s29, s37
	s_cselect_b32 s66, s28, s36
	s_add_u32 s34, s34, 0x40080
	s_addc_u32 s35, s35, 0
	s_add_u32 s67, s36, 0x100
	s_addc_u32 s68, s37, 0
	s_mov_b32 s69, -2
	s_add_u32 s36, s34, 0xfffc0080
	s_addc_u32 s37, s35, -1
	s_cmp_eq_u32 s69, 12
	s_cselect_b32 s39, s25, s37
	s_cselect_b32 s38, s42, s36
	s_cselect_b32 s37, s23, s68
	s_cselect_b32 s36, s66, s67
	s_add_i32 m0, s40, 0xc000
	global_load_lds_dwordx4 v156, s[34:35]
	s_add_i32 m0, s40, 0xe000
	s_nop 0
	global_load_lds_dwordx4 v158, s[34:35]
	s_waitcnt vmcnt(8)
	s_barrier
	s_waitcnt lgkmcnt(0)
	v_mfma_f32_16x16x32_bf16 v[124:127], v[128:131], v[182:185], 0
	v_mfma_f32_16x16x32_bf16 v[116:119], v[136:139], v[182:185], 0
	v_mfma_f32_16x16x32_bf16 v[120:123], v[128:131], v[190:193], 0
	v_mfma_f32_16x16x32_bf16 v[112:115], v[136:139], v[190:193], 0
	v_mfma_f32_16x16x32_bf16 v[92:95], v[128:131], v[198:201], 0
	v_mfma_f32_16x16x32_bf16 v[88:91], v[136:139], v[198:201], 0
	v_mfma_f32_16x16x32_bf16 v[76:79], v[128:131], v[206:209], 0
	v_mfma_f32_16x16x32_bf16 v[72:75], v[136:139], v[206:209], 0
	v_mfma_f32_16x16x32_bf16 v[124:127], v[132:135], v[186:189], v[124:127]
	v_mfma_f32_16x16x32_bf16 v[116:119], v[140:143], v[186:189], v[116:119]
	v_mfma_f32_16x16x32_bf16 v[120:123], v[132:135], v[194:197], v[120:123]
	v_mfma_f32_16x16x32_bf16 v[112:115], v[140:143], v[194:197], v[112:115]
	v_mfma_f32_16x16x32_bf16 v[92:95], v[132:135], v[202:205], v[92:95]
	v_mfma_f32_16x16x32_bf16 v[88:91], v[140:143], v[202:205], v[88:91]
	v_mfma_f32_16x16x32_bf16 v[76:79], v[132:135], v[210:213], v[76:79]
	v_mfma_f32_16x16x32_bf16 v[72:75], v[140:143], v[210:213], v[72:75]
	v_mfma_f32_16x16x32_bf16 v[108:111], v[144:147], v[182:185], 0
	v_mfma_f32_16x16x32_bf16 v[104:107], v[168:171], v[182:185], 0
	v_mfma_f32_16x16x32_bf16 v[100:103], v[144:147], v[190:193], 0
	v_mfma_f32_16x16x32_bf16 v[96:99], v[168:171], v[190:193], 0
	v_mfma_f32_16x16x32_bf16 v[84:87], v[144:147], v[198:201], 0
	v_mfma_f32_16x16x32_bf16 v[80:83], v[168:171], v[198:201], 0
	v_mfma_f32_16x16x32_bf16 v[68:71], v[144:147], v[206:209], 0
	v_mfma_f32_16x16x32_bf16 v[64:67], v[168:171], v[206:209], 0
	v_mfma_f32_16x16x32_bf16 v[108:111], v[164:167], v[186:189], v[108:111]
	v_mfma_f32_16x16x32_bf16 v[104:107], v[178:181], v[186:189], v[104:107]
	v_mfma_f32_16x16x32_bf16 v[100:103], v[164:167], v[194:197], v[100:103]
	v_mfma_f32_16x16x32_bf16 v[96:99], v[178:181], v[194:197], v[96:99]
	v_mfma_f32_16x16x32_bf16 v[84:87], v[164:167], v[202:205], v[84:87]
	v_mfma_f32_16x16x32_bf16 v[80:83], v[178:181], v[202:205], v[80:83]
	v_mfma_f32_16x16x32_bf16 v[68:71], v[164:167], v[210:213], v[68:71]
	v_mfma_f32_16x16x32_bf16 v[64:67], v[178:181], v[210:213], v[64:67]
	s_barrier
	s_add_u32 s98, s36, s12
	s_addc_u32 s99, s37, s13
	s_add_u32 s100, s38, s12
	s_addc_u32 s101, s39, s13
	s_add_i32 s52, s58, s33
	s_mov_b32 m0, s52
	ds_read_b128 v[182:185], v177 offset:16384
	ds_read_b128 v[186:189], v177 offset:17408
	ds_read_b128 v[190:193], v177 offset:18432
	ds_read_b128 v[194:197], v177 offset:19456
	ds_read_b128 v[198:201], v177 offset:20480
	ds_read_b128 v[202:205], v177 offset:21504
	ds_read_b128 v[206:209], v177 offset:22528
	ds_read_b128 v[210:213], v177 offset:23552
	global_load_lds_dwordx4 v150, s[36:37]
	s_add_i32 m0, s52, 0x2000
	s_add_u32 s70, s36, 0x40000
	s_addc_u32 s71, s37, 0
	s_add_i32 s52, s59, s33
	global_load_lds_dwordx4 v154, s[36:37]
	s_mov_b32 m0, s52
	s_nop 0
	global_load_lds_dwordx4 v150, s[70:71]
	s_add_i32 m0, s52, 0x2000
	s_nop 0
	global_load_lds_dwordx4 v154, s[70:71]
	s_mov_b32 m0, s40
	s_nop 0
	global_load_lds_dwordx4 v148, s[38:39]
	s_mov_b32 m0, s41
	s_nop 0
	global_load_lds_dwordx4 v152, s[38:39]
	s_waitcnt vmcnt(8)
	s_barrier
	s_waitcnt lgkmcnt(0)
	v_mfma_f32_16x16x32_bf16 v[60:63], v[128:131], v[182:185], 0
	v_mfma_f32_16x16x32_bf16 v[56:59], v[136:139], v[182:185], 0
	v_mfma_f32_16x16x32_bf16 v[44:47], v[128:131], v[190:193], 0
	v_mfma_f32_16x16x32_bf16 v[40:43], v[136:139], v[190:193], 0
	v_mfma_f32_16x16x32_bf16 v[36:39], v[128:131], v[198:201], 0
	v_mfma_f32_16x16x32_bf16 v[32:35], v[136:139], v[198:201], 0
	v_mfma_f32_16x16x32_bf16 v[20:23], v[128:131], v[206:209], 0
	v_mfma_f32_16x16x32_bf16 v[16:19], v[136:139], v[206:209], 0
	v_mfma_f32_16x16x32_bf16 v[60:63], v[132:135], v[186:189], v[60:63]
	v_mfma_f32_16x16x32_bf16 v[56:59], v[140:143], v[186:189], v[56:59]
	v_mfma_f32_16x16x32_bf16 v[44:47], v[132:135], v[194:197], v[44:47]
	v_mfma_f32_16x16x32_bf16 v[40:43], v[140:143], v[194:197], v[40:43]
	v_mfma_f32_16x16x32_bf16 v[36:39], v[132:135], v[202:205], v[36:39]
	v_mfma_f32_16x16x32_bf16 v[32:35], v[140:143], v[202:205], v[32:35]
	v_mfma_f32_16x16x32_bf16 v[20:23], v[132:135], v[210:213], v[20:23]
	v_mfma_f32_16x16x32_bf16 v[16:19], v[140:143], v[210:213], v[16:19]
	v_mfma_f32_16x16x32_bf16 v[52:55], v[144:147], v[182:185], 0
	v_mfma_f32_16x16x32_bf16 v[48:51], v[168:171], v[182:185], 0
	v_mfma_f32_16x16x32_bf16 v[28:31], v[144:147], v[190:193], 0
	v_mfma_f32_16x16x32_bf16 v[24:27], v[168:171], v[190:193], 0
	v_mfma_f32_16x16x32_bf16 v[12:15], v[144:147], v[198:201], 0
	v_mfma_f32_16x16x32_bf16 v[8:11], v[168:171], v[198:201], 0
	v_mfma_f32_16x16x32_bf16 v[4:7], v[144:147], v[206:209], 0
	v_mfma_f32_16x16x32_bf16 v[0:3], v[168:171], v[206:209], 0
	v_mfma_f32_16x16x32_bf16 v[52:55], v[164:167], v[186:189], v[52:55]
	v_mfma_f32_16x16x32_bf16 v[48:51], v[178:181], v[186:189], v[48:51]
	v_mfma_f32_16x16x32_bf16 v[28:31], v[164:167], v[194:197], v[28:31]
	v_mfma_f32_16x16x32_bf16 v[24:27], v[178:181], v[194:197], v[24:27]
	v_mfma_f32_16x16x32_bf16 v[12:15], v[164:167], v[202:205], v[12:15]
	v_mfma_f32_16x16x32_bf16 v[8:11], v[178:181], v[202:205], v[8:11]
	v_mfma_f32_16x16x32_bf16 v[4:7], v[164:167], v[210:213], v[4:7]
	v_mfma_f32_16x16x32_bf16 v[0:3], v[178:181], v[210:213], v[0:3]
	s_barrier
; #define PG8_STAGE(bufoff, gbase, voff) do { _Pragma("unroll") for (int _i = 0; _i < 2; ++_i) \
;         __builtin_amdgcn_global_load_lds((const unsigned*)((const char*)(gbase) + (voff)[_i]), (LAS unsigned*)(lds + (bufoff) + ldsw + _i * 8192), 16, 0, 0); } while (0)
; #define PG8_LDA(dst, b, h) do { _Pragma("unroll") for (int m = 0; m < 4; ++m) _Pragma("unroll") for (int k = 0; k < 2; ++k) dst[m][k] = *(const LAS bf16x8*)(lds + PG8_SA(b, h) + aoff + m * 2048 + k * 1024); } while (0)
; #define PG8_LDB(dst, b, h) do { _Pragma("unroll") for (int n = 0; n < 2; ++n) _Pragma("unroll") for (int k = 0; k < 2; ++k) dst[n][k] = *(const LAS bf16x8*)(lds + PG8_SB(b, h) + boff + n * 2048 + k * 1024); } while (0)
; #define PG8_MMA(ai, bj, At, Bt) do { __builtin_amdgcn_s_setprio(1); _Pragma("unroll") for (int m = 0; m < 4; ++m) _Pragma("unroll") for (int n = 0; n < 2; ++n) _Pragma("unroll") for (int k = 0; k < 2; ++k) \
;         acc[ai][bj][m][n] = __builtin_amdgcn_mfma_f32_16x16x32_bf16(Bt[n][k], At[m][k], acc[ai][bj][m][n], 0, 0, 0); __builtin_amdgcn_s_setprio(0); } while (0)
; #define PG8_WAIT_V(n) asm volatile("s_waitcnt vmcnt(" #n ")" ::: "memory")
; #define PG8_WAIT_L(n) asm volatile("s_waitcnt lgkmcnt(" #n ")" ::: "memory")
; #define PG8_BAR __builtin_amdgcn_s_barrier()
; #define PG8_SCHED __builtin_amdgcn_sched_barrier(0)
; template <class Epi, bool ALIGN_EPI, int K, int LDA, int LDB>
; __device__ __forceinline__ void gemm_phase(LAS unsigned char* lds, const int wid, const Gemm g, const StaticOrder& S, const Epi& E) {
;     ...
;             PG8_LDB(B0, 1, 0); PG8_LDB(B1, 1, 1); PG8_SCHED; PG8_LDA(At, 1, 0); PG8_STAGE(PG8_SA(0, 1), a2 + hA, voffA);
;             PG8_WAIT_V(8); PG8_WAIT_L(0); PG8_BAR; PG8_MMA(0, 0, At, B0); PG8_MMA(0, 1, At, B1); PG8_BAR; PG8_SCHED;
;             PG8_LDA(At, 1, 1); PG8_STAGE(PG8_SB(1, 0), b3, voffB); PG8_STAGE(PG8_SB(1, 1), b3 + hB, voffB); PG8_STAGE(PG8_SA(1, 0), a3, voffA);
;             PG8_WAIT_V(8); PG8_WAIT_L(0); PG8_BAR; PG8_MMA(1, 0, At, B0); PG8_MMA(1, 1, At, B1); PG8_BAR; PG8_SCHED;
	s_add_i32 s52, 0, 0x18000
	s_add_i32 s53, 0, 0x1c000
	v_add_u32_e32 v140, s52, v174
	v_add_u32_e32 v178, s53, v174
	ds_read_b128 v[128:131], v140
	ds_read_b128 v[132:135], v140 offset:1024
	ds_read_b128 v[136:139], v140 offset:2048
	ds_read_b128 v[140:143], v140 offset:3072
	ds_read_b128 v[144:147], v178
	ds_read_b128 v[164:167], v178 offset:1024
	ds_read_b128 v[168:171], v178 offset:2048
	ds_read_b128 v[178:181], v178 offset:3072
	s_add_u32 s38, s38, 0x40000
	s_addc_u32 s39, s39, 0
	s_mov_b32 m0, s43
	ds_read_b128 v[182:185], v177 offset:32768
	ds_read_b128 v[186:189], v177 offset:33792
	ds_read_b128 v[190:193], v177 offset:34816
	ds_read_b128 v[194:197], v177 offset:35840
	ds_read_b128 v[198:201], v177 offset:36864
	ds_read_b128 v[202:205], v177 offset:37888
	ds_read_b128 v[206:209], v177 offset:38912
	ds_read_b128 v[210:213], v177 offset:39936
	global_load_lds_dwordx4 v148, s[38:39]
	s_mov_b32 m0, s48
	s_nop 0
	global_load_lds_dwordx4 v152, s[38:39]
	s_waitcnt vmcnt(8)
	s_barrier
	s_waitcnt lgkmcnt(0)
	v_mfma_f32_16x16x32_bf16 v[124:127], v[128:131], v[182:185], v[124:127]
	v_mfma_f32_16x16x32_bf16 v[116:119], v[136:139], v[182:185], v[116:119]
	v_mfma_f32_16x16x32_bf16 v[120:123], v[128:131], v[190:193], v[120:123]
	v_mfma_f32_16x16x32_bf16 v[112:115], v[136:139], v[190:193], v[112:115]
	v_mfma_f32_16x16x32_bf16 v[92:95], v[128:131], v[198:201], v[92:95]
	v_mfma_f32_16x16x32_bf16 v[88:91], v[136:139], v[198:201], v[88:91]
	v_mfma_f32_16x16x32_bf16 v[76:79], v[128:131], v[206:209], v[76:79]
	v_mfma_f32_16x16x32_bf16 v[72:75], v[136:139], v[206:209], v[72:75]
	v_mfma_f32_16x16x32_bf16 v[124:127], v[132:135], v[186:189], v[124:127]
	v_mfma_f32_16x16x32_bf16 v[116:119], v[140:143], v[186:189], v[116:119]
	v_mfma_f32_16x16x32_bf16 v[120:123], v[132:135], v[194:197], v[120:123]
	v_mfma_f32_16x16x32_bf16 v[112:115], v[140:143], v[194:197], v[112:115]
	v_mfma_f32_16x16x32_bf16 v[92:95], v[132:135], v[202:205], v[92:95]
	v_mfma_f32_16x16x32_bf16 v[88:91], v[140:143], v[202:205], v[88:91]
	v_mfma_f32_16x16x32_bf16 v[76:79], v[132:135], v[210:213], v[76:79]
	v_mfma_f32_16x16x32_bf16 v[72:75], v[140:143], v[210:213], v[72:75]
	v_mfma_f32_16x16x32_bf16 v[108:111], v[144:147], v[182:185], v[108:111]
	v_mfma_f32_16x16x32_bf16 v[104:107], v[168:171], v[182:185], v[104:107]
	v_mfma_f32_16x16x32_bf16 v[100:103], v[144:147], v[190:193], v[100:103]
	v_mfma_f32_16x16x32_bf16 v[96:99], v[168:171], v[190:193], v[96:99]
	v_mfma_f32_16x16x32_bf16 v[84:87], v[144:147], v[198:201], v[84:87]
	v_mfma_f32_16x16x32_bf16 v[80:83], v[168:171], v[198:201], v[80:83]
	v_mfma_f32_16x16x32_bf16 v[68:71], v[144:147], v[206:209], v[68:71]
	v_mfma_f32_16x16x32_bf16 v[64:67], v[168:171], v[206:209], v[64:67]
	v_mfma_f32_16x16x32_bf16 v[108:111], v[164:167], v[186:189], v[108:111]
	v_mfma_f32_16x16x32_bf16 v[104:107], v[178:181], v[186:189], v[104:107]
	v_mfma_f32_16x16x32_bf16 v[100:103], v[164:167], v[194:197], v[100:103]
	v_mfma_f32_16x16x32_bf16 v[96:99], v[178:181], v[194:197], v[96:99]
	v_mfma_f32_16x16x32_bf16 v[84:87], v[164:167], v[202:205], v[84:87]
	v_mfma_f32_16x16x32_bf16 v[80:83], v[178:181], v[202:205], v[80:83]
	v_mfma_f32_16x16x32_bf16 v[68:71], v[164:167], v[210:213], v[68:71]
	v_mfma_f32_16x16x32_bf16 v[64:67], v[178:181], v[210:213], v[64:67]
	s_barrier
	s_add_i32 s38, s52, s33
	s_mov_b32 m0, s38
	ds_read_b128 v[182:185], v177 offset:49152
	ds_read_b128 v[186:189], v177 offset:50176
	ds_read_b128 v[190:193], v177 offset:51200
	ds_read_b128 v[194:197], v177 offset:52224
	ds_read_b128 v[198:201], v177 offset:53248
	ds_read_b128 v[202:205], v177 offset:54272
	ds_read_b128 v[206:209], v177 offset:55296
	ds_read_b128 v[210:213], v177 offset:56320
	global_load_lds_dwordx4 v150, s[98:99]
	s_add_i32 m0, s38, 0x2000
	s_add_u32 s36, s36, 0x40080
	s_addc_u32 s37, s37, 0
	s_add_i32 s38, s53, s33
	global_load_lds_dwordx4 v154, s[98:99]
	s_mov_b32 m0, s38
	s_nop 0
	global_load_lds_dwordx4 v150, s[36:37]
	s_add_i32 m0, s38, 0x2000
	s_nop 0
	global_load_lds_dwordx4 v154, s[36:37]
	s_mov_b32 m0, s55
	s_nop 0
	global_load_lds_dwordx4 v148, s[100:101]
	s_mov_b32 m0, s56
	s_nop 0
	global_load_lds_dwordx4 v152, s[100:101]
	s_waitcnt vmcnt(8)
	s_barrier
	s_waitcnt lgkmcnt(0)
	v_mfma_f32_16x16x32_bf16 v[60:63], v[128:131], v[182:185], v[60:63]
	v_mfma_f32_16x16x32_bf16 v[56:59], v[136:139], v[182:185], v[56:59]
	v_mfma_f32_16x16x32_bf16 v[44:47], v[128:131], v[190:193], v[44:47]
	v_mfma_f32_16x16x32_bf16 v[40:43], v[136:139], v[190:193], v[40:43]
	v_mfma_f32_16x16x32_bf16 v[36:39], v[128:131], v[198:201], v[36:39]
	v_mfma_f32_16x16x32_bf16 v[32:35], v[136:139], v[198:201], v[32:35]
	v_mfma_f32_16x16x32_bf16 v[20:23], v[128:131], v[206:209], v[20:23]
	v_mfma_f32_16x16x32_bf16 v[16:19], v[136:139], v[206:209], v[16:19]
	v_mfma_f32_16x16x32_bf16 v[60:63], v[132:135], v[186:189], v[60:63]
	v_mfma_f32_16x16x32_bf16 v[56:59], v[140:143], v[186:189], v[56:59]
	v_mfma_f32_16x16x32_bf16 v[44:47], v[132:135], v[194:197], v[44:47]
	v_mfma_f32_16x16x32_bf16 v[40:43], v[140:143], v[194:197], v[40:43]
	v_mfma_f32_16x16x32_bf16 v[36:39], v[132:135], v[202:205], v[36:39]
	v_mfma_f32_16x16x32_bf16 v[32:35], v[140:143], v[202:205], v[32:35]
	v_mfma_f32_16x16x32_bf16 v[20:23], v[132:135], v[210:213], v[20:23]
	v_mfma_f32_16x16x32_bf16 v[16:19], v[140:143], v[210:213], v[16:19]
	v_mfma_f32_16x16x32_bf16 v[52:55], v[144:147], v[182:185], v[52:55]
	v_mfma_f32_16x16x32_bf16 v[48:51], v[168:171], v[182:185], v[48:51]
	v_mfma_f32_16x16x32_bf16 v[28:31], v[144:147], v[190:193], v[28:31]
	v_mfma_f32_16x16x32_bf16 v[24:27], v[168:171], v[190:193], v[24:27]
	v_mfma_f32_16x16x32_bf16 v[12:15], v[144:147], v[198:201], v[12:15]
	v_mfma_f32_16x16x32_bf16 v[8:11], v[168:171], v[198:201], v[8:11]
	v_mfma_f32_16x16x32_bf16 v[4:7], v[144:147], v[206:209], v[4:7]
	v_mfma_f32_16x16x32_bf16 v[0:3], v[168:171], v[206:209], v[0:3]
	v_mfma_f32_16x16x32_bf16 v[52:55], v[164:167], v[186:189], v[52:55]
	v_mfma_f32_16x16x32_bf16 v[48:51], v[178:181], v[186:189], v[48:51]
	v_mfma_f32_16x16x32_bf16 v[28:31], v[164:167], v[194:197], v[28:31]
	v_mfma_f32_16x16x32_bf16 v[24:27], v[178:181], v[194:197], v[24:27]
	v_mfma_f32_16x16x32_bf16 v[12:15], v[164:167], v[202:205], v[12:15]
	v_mfma_f32_16x16x32_bf16 v[8:11], v[178:181], v[202:205], v[8:11]
	v_mfma_f32_16x16x32_bf16 v[4:7], v[164:167], v[210:213], v[4:7]
	v_mfma_f32_16x16x32_bf16 v[0:3], v[178:181], v[210:213], v[0:3]
	s_barrier
	s_add_i32 s69, s69, 2
	s_add_u32 s34, s34, 0x100
	s_addc_u32 s35, s35, 0
	s_add_u32 s67, s67, 0x100
	s_addc_u32 s68, s68, 0
; #define PG8_STAGE(bufoff, gbase, voff) do { _Pragma("unroll") for (int _i = 0; _i < 2; ++_i) \
;         __builtin_amdgcn_global_load_lds((const unsigned*)((const char*)(gbase) + (voff)[_i]), (LAS unsigned*)(lds + (bufoff) + ldsw + _i * 8192), 16, 0, 0); } while (0)
; #define PG8_LDA(dst, b, h) do { _Pragma("unroll") for (int m = 0; m < 4; ++m) _Pragma("unroll") for (int k = 0; k < 2; ++k) dst[m][k] = *(const LAS bf16x8*)(lds + PG8_SA(b, h) + aoff + m * 2048 + k * 1024); } while (0)
; #define PG8_LDB(dst, b, h) do { _Pragma("unroll") for (int n = 0; n < 2; ++n) _Pragma("unroll") for (int k = 0; k < 2; ++k) dst[n][k] = *(const LAS bf16x8*)(lds + PG8_SB(b, h) + boff + n * 2048 + k * 1024); } while (0)
; #define PG8_MMA(ai, bj, At, Bt) do { __builtin_amdgcn_s_setprio(1); _Pragma("unroll") for (int m = 0; m < 4; ++m) _Pragma("unroll") for (int n = 0; n < 2; ++n) _Pragma("unroll") for (int k = 0; k < 2; ++k) \
;         acc[ai][bj][m][n] = __builtin_amdgcn_mfma_f32_16x16x32_bf16(Bt[n][k], At[m][k], acc[ai][bj][m][n], 0, 0, 0); __builtin_amdgcn_s_setprio(0); } while (0)
; #define PG8_WAIT_V(n) asm volatile("s_waitcnt vmcnt(" #n ")" ::: "memory")
; #define PG8_WAIT_L(n) asm volatile("s_waitcnt lgkmcnt(" #n ")" ::: "memory")
; #define PG8_BAR __builtin_amdgcn_s_barrier()
; template <class Epi, bool ALIGN_EPI, int K, int LDA, int LDB>
; __device__ __forceinline__ void gemm_phase(LAS unsigned char* lds, const int wid, const Gemm g, const StaticOrder& S, const Epi& E) {
;     ...
;         for (int t = 0; t < nt; t += 2) {
;             const bool last = (t == nt - 2);
;             const char* a1 = cA + (size_t)(t + 1) * kstep;
;             const char* a2 = last ? nA : cA + (size_t)(t + 2) * kstep; const char* b2 = last ? nB : cB + (size_t)(t + 2) * kstep;
;             const char* a3 = a2 + kstep; const char* b3 = b2 + kstep;
;             PG8_LDB(B0, 0, 0); PG8_LDB(B1, 0, 1); PG8_SCHED; PG8_LDA(At, 0, 0); PG8_STAGE(PG8_SA(1, 1), a1 + hA, voffA);
;             PG8_WAIT_V(8); PG8_WAIT_L(0); PG8_BAR; PG8_MMA(0, 0, At, B0); PG8_MMA(0, 1, At, B1); PG8_BAR; PG8_SCHED;
;             PG8_LDA(At, 0, 1); PG8_STAGE(PG8_SB(0, 0), b2, voffB); PG8_STAGE(PG8_SB(0, 1), b2 + hB, voffB); PG8_STAGE(PG8_SA(0, 0), a2, voffA);
;             PG8_WAIT_V(8); PG8_WAIT_L(0); PG8_BAR; PG8_MMA(1, 0, At, B0); PG8_MMA(1, 1, At, B1); PG8_BAR; PG8_SCHED;
.LBB0_1477:
	ds_read_b128 v[128:131], v175
	ds_read_b128 v[132:135], v175 offset:1024
	ds_read_b128 v[136:139], v175 offset:2048
	ds_read_b128 v[140:143], v175 offset:3072
	ds_read_b128 v[144:147], v176
	ds_read_b128 v[164:167], v176 offset:1024
	ds_read_b128 v[168:171], v176 offset:2048
	ds_read_b128 v[178:181], v176 offset:3072
	s_add_u32 s36, s34, 0xfffc0080
	s_addc_u32 s37, s35, -1
	s_cmp_eq_u32 s69, 12
	s_cselect_b32 s39, s25, s37
	s_cselect_b32 s38, s42, s36
	s_cselect_b32 s37, s23, s68
	s_cselect_b32 s36, s66, s67
	s_add_i32 m0, s40, 0xc000
	ds_read_b128 v[182:185], v177
	ds_read_b128 v[186:189], v177 offset:1024
	ds_read_b128 v[190:193], v177 offset:2048
	ds_read_b128 v[194:197], v177 offset:3072
	ds_read_b128 v[198:201], v177 offset:4096
	ds_read_b128 v[202:205], v177 offset:5120
	ds_read_b128 v[206:209], v177 offset:6144
	ds_read_b128 v[210:213], v177 offset:7168
	global_load_lds_dwordx4 v156, s[34:35]
	s_add_i32 m0, s40, 0xe000
	s_nop 0
	global_load_lds_dwordx4 v158, s[34:35]
	s_waitcnt vmcnt(8)
	s_barrier
	s_waitcnt lgkmcnt(0)
	v_mfma_f32_16x16x32_bf16 v[124:127], v[128:131], v[182:185], v[124:127]
	v_mfma_f32_16x16x32_bf16 v[116:119], v[136:139], v[182:185], v[116:119]
	v_mfma_f32_16x16x32_bf16 v[120:123], v[128:131], v[190:193], v[120:123]
	v_mfma_f32_16x16x32_bf16 v[112:115], v[136:139], v[190:193], v[112:115]
	v_mfma_f32_16x16x32_bf16 v[92:95], v[128:131], v[198:201], v[92:95]
	v_mfma_f32_16x16x32_bf16 v[88:91], v[136:139], v[198:201], v[88:91]
	v_mfma_f32_16x16x32_bf16 v[76:79], v[128:131], v[206:209], v[76:79]
	v_mfma_f32_16x16x32_bf16 v[72:75], v[136:139], v[206:209], v[72:75]
	v_mfma_f32_16x16x32_bf16 v[124:127], v[132:135], v[186:189], v[124:127]
	v_mfma_f32_16x16x32_bf16 v[116:119], v[140:143], v[186:189], v[116:119]
	v_mfma_f32_16x16x32_bf16 v[120:123], v[132:135], v[194:197], v[120:123]
	v_mfma_f32_16x16x32_bf16 v[112:115], v[140:143], v[194:197], v[112:115]
	v_mfma_f32_16x16x32_bf16 v[92:95], v[132:135], v[202:205], v[92:95]
	v_mfma_f32_16x16x32_bf16 v[88:91], v[140:143], v[202:205], v[88:91]
	v_mfma_f32_16x16x32_bf16 v[76:79], v[132:135], v[210:213], v[76:79]
	v_mfma_f32_16x16x32_bf16 v[72:75], v[140:143], v[210:213], v[72:75]
	v_mfma_f32_16x16x32_bf16 v[108:111], v[144:147], v[182:185], v[108:111]
	v_mfma_f32_16x16x32_bf16 v[104:107], v[168:171], v[182:185], v[104:107]
	v_mfma_f32_16x16x32_bf16 v[100:103], v[144:147], v[190:193], v[100:103]
	v_mfma_f32_16x16x32_bf16 v[96:99], v[168:171], v[190:193], v[96:99]
	v_mfma_f32_16x16x32_bf16 v[84:87], v[144:147], v[198:201], v[84:87]
	v_mfma_f32_16x16x32_bf16 v[80:83], v[168:171], v[198:201], v[80:83]
	v_mfma_f32_16x16x32_bf16 v[68:71], v[144:147], v[206:209], v[68:71]
	v_mfma_f32_16x16x32_bf16 v[64:67], v[168:171], v[206:209], v[64:67]
	v_mfma_f32_16x16x32_bf16 v[108:111], v[164:167], v[186:189], v[108:111]
	v_mfma_f32_16x16x32_bf16 v[104:107], v[178:181], v[186:189], v[104:107]
	v_mfma_f32_16x16x32_bf16 v[100:103], v[164:167], v[194:197], v[100:103]
	v_mfma_f32_16x16x32_bf16 v[96:99], v[178:181], v[194:197], v[96:99]
	v_mfma_f32_16x16x32_bf16 v[84:87], v[164:167], v[202:205], v[84:87]
	v_mfma_f32_16x16x32_bf16 v[80:83], v[178:181], v[202:205], v[80:83]
	v_mfma_f32_16x16x32_bf16 v[68:71], v[164:167], v[210:213], v[68:71]
	v_mfma_f32_16x16x32_bf16 v[64:67], v[178:181], v[210:213], v[64:67]
	s_barrier
	s_add_u32 s98, s36, s12
	s_addc_u32 s99, s37, s13
	s_add_u32 s100, s38, s12
	s_addc_u32 s101, s39, s13
	s_add_i32 s52, s58, s33
	s_mov_b32 m0, s52
	ds_read_b128 v[182:185], v177 offset:16384
	ds_read_b128 v[186:189], v177 offset:17408
	ds_read_b128 v[190:193], v177 offset:18432
	ds_read_b128 v[194:197], v177 offset:19456
	ds_read_b128 v[198:201], v177 offset:20480
	ds_read_b128 v[202:205], v177 offset:21504
	ds_read_b128 v[206:209], v177 offset:22528
	ds_read_b128 v[210:213], v177 offset:23552
	global_load_lds_dwordx4 v150, s[36:37]
	s_add_i32 m0, s52, 0x2000
	s_add_u32 s70, s36, 0x40000
	s_addc_u32 s71, s37, 0
	s_add_i32 s52, s59, s33
	global_load_lds_dwordx4 v154, s[36:37]
	s_mov_b32 m0, s52
	s_nop 0
	global_load_lds_dwordx4 v150, s[70:71]
	s_add_i32 m0, s52, 0x2000
	s_nop 0
	global_load_lds_dwordx4 v154, s[70:71]
	s_mov_b32 m0, s40
	s_nop 0
	global_load_lds_dwordx4 v148, s[38:39]
	s_mov_b32 m0, s41
	s_nop 0
	global_load_lds_dwordx4 v152, s[38:39]
	s_waitcnt vmcnt(8)
	s_barrier
	s_waitcnt lgkmcnt(0)
	v_mfma_f32_16x16x32_bf16 v[60:63], v[128:131], v[182:185], v[60:63]
	v_mfma_f32_16x16x32_bf16 v[56:59], v[136:139], v[182:185], v[56:59]
	v_mfma_f32_16x16x32_bf16 v[44:47], v[128:131], v[190:193], v[44:47]
	v_mfma_f32_16x16x32_bf16 v[40:43], v[136:139], v[190:193], v[40:43]
	v_mfma_f32_16x16x32_bf16 v[36:39], v[128:131], v[198:201], v[36:39]
	v_mfma_f32_16x16x32_bf16 v[32:35], v[136:139], v[198:201], v[32:35]
	v_mfma_f32_16x16x32_bf16 v[20:23], v[128:131], v[206:209], v[20:23]
	v_mfma_f32_16x16x32_bf16 v[16:19], v[136:139], v[206:209], v[16:19]
	v_mfma_f32_16x16x32_bf16 v[60:63], v[132:135], v[186:189], v[60:63]
	v_mfma_f32_16x16x32_bf16 v[56:59], v[140:143], v[186:189], v[56:59]
	v_mfma_f32_16x16x32_bf16 v[44:47], v[132:135], v[194:197], v[44:47]
	v_mfma_f32_16x16x32_bf16 v[40:43], v[140:143], v[194:197], v[40:43]
	v_mfma_f32_16x16x32_bf16 v[36:39], v[132:135], v[202:205], v[36:39]
	v_mfma_f32_16x16x32_bf16 v[32:35], v[140:143], v[202:205], v[32:35]
	v_mfma_f32_16x16x32_bf16 v[20:23], v[132:135], v[210:213], v[20:23]
	v_mfma_f32_16x16x32_bf16 v[16:19], v[140:143], v[210:213], v[16:19]
	v_mfma_f32_16x16x32_bf16 v[52:55], v[144:147], v[182:185], v[52:55]
	v_mfma_f32_16x16x32_bf16 v[48:51], v[168:171], v[182:185], v[48:51]
	v_mfma_f32_16x16x32_bf16 v[28:31], v[144:147], v[190:193], v[28:31]
	v_mfma_f32_16x16x32_bf16 v[24:27], v[168:171], v[190:193], v[24:27]
	v_mfma_f32_16x16x32_bf16 v[12:15], v[144:147], v[198:201], v[12:15]
	v_mfma_f32_16x16x32_bf16 v[8:11], v[168:171], v[198:201], v[8:11]
	v_mfma_f32_16x16x32_bf16 v[4:7], v[144:147], v[206:209], v[4:7]
	v_mfma_f32_16x16x32_bf16 v[0:3], v[168:171], v[206:209], v[0:3]
	v_mfma_f32_16x16x32_bf16 v[52:55], v[164:167], v[186:189], v[52:55]
	v_mfma_f32_16x16x32_bf16 v[48:51], v[178:181], v[186:189], v[48:51]
	v_mfma_f32_16x16x32_bf16 v[28:31], v[164:167], v[194:197], v[28:31]
	v_mfma_f32_16x16x32_bf16 v[24:27], v[178:181], v[194:197], v[24:27]
	v_mfma_f32_16x16x32_bf16 v[12:15], v[164:167], v[202:205], v[12:15]
	v_mfma_f32_16x16x32_bf16 v[8:11], v[178:181], v[202:205], v[8:11]
	v_mfma_f32_16x16x32_bf16 v[4:7], v[164:167], v[210:213], v[4:7]
	v_mfma_f32_16x16x32_bf16 v[0:3], v[178:181], v[210:213], v[0:3]
	s_barrier
; #define PG8_STAGE(bufoff, gbase, voff) do { _Pragma("unroll") for (int _i = 0; _i < 2; ++_i) \
;         __builtin_amdgcn_global_load_lds((const unsigned*)((const char*)(gbase) + (voff)[_i]), (LAS unsigned*)(lds + (bufoff) + ldsw + _i * 8192), 16, 0, 0); } while (0)
; #define PG8_LDA(dst, b, h) do { _Pragma("unroll") for (int m = 0; m < 4; ++m) _Pragma("unroll") for (int k = 0; k < 2; ++k) dst[m][k] = *(const LAS bf16x8*)(lds + PG8_SA(b, h) + aoff + m * 2048 + k * 1024); } while (0)
; #define PG8_LDB(dst, b, h) do { _Pragma("unroll") for (int n = 0; n < 2; ++n) _Pragma("unroll") for (int k = 0; k < 2; ++k) dst[n][k] = *(const LAS bf16x8*)(lds + PG8_SB(b, h) + boff + n * 2048 + k * 1024); } while (0)
; #define PG8_MMA(ai, bj, At, Bt) do { __builtin_amdgcn_s_setprio(1); _Pragma("unroll") for (int m = 0; m < 4; ++m) _Pragma("unroll") for (int n = 0; n < 2; ++n) _Pragma("unroll") for (int k = 0; k < 2; ++k) \
;         acc[ai][bj][m][n] = __builtin_amdgcn_mfma_f32_16x16x32_bf16(Bt[n][k], At[m][k], acc[ai][bj][m][n], 0, 0, 0); __builtin_amdgcn_s_setprio(0); } while (0)
; #define PG8_WAIT_V(n) asm volatile("s_waitcnt vmcnt(" #n ")" ::: "memory")
; #define PG8_WAIT_L(n) asm volatile("s_waitcnt lgkmcnt(" #n ")" ::: "memory")
; #define PG8_BAR __builtin_amdgcn_s_barrier()
; #define PG8_SCHED __builtin_amdgcn_sched_barrier(0)
; template <class Epi, bool ALIGN_EPI, int K, int LDA, int LDB>
; __device__ __forceinline__ void gemm_phase(LAS unsigned char* lds, const int wid, const Gemm g, const StaticOrder& S, const Epi& E) {
;     ...
;             PG8_LDB(B0, 1, 0); PG8_LDB(B1, 1, 1); PG8_SCHED; PG8_LDA(At, 1, 0); PG8_STAGE(PG8_SA(0, 1), a2 + hA, voffA);
;             PG8_WAIT_V(8); PG8_WAIT_L(0); PG8_BAR; PG8_MMA(0, 0, At, B0); PG8_MMA(0, 1, At, B1); PG8_BAR; PG8_SCHED;
;             PG8_LDA(At, 1, 1); PG8_STAGE(PG8_SB(1, 0), b3, voffB); PG8_STAGE(PG8_SB(1, 1), b3 + hB, voffB); PG8_STAGE(PG8_SA(1, 0), a3, voffA);
;             PG8_WAIT_V(8); PG8_WAIT_L(0); PG8_BAR; PG8_MMA(1, 0, At, B0); PG8_MMA(1, 1, At, B1); PG8_BAR; PG8_SCHED;
;         }
	s_add_i32 s52, 0, 0x18000
	s_add_i32 s53, 0, 0x1c000
	v_add_u32_e32 v140, s52, v174
	v_add_u32_e32 v178, s53, v174
	ds_read_b128 v[128:131], v140
	ds_read_b128 v[132:135], v140 offset:1024
	ds_read_b128 v[136:139], v140 offset:2048
	ds_read_b128 v[140:143], v140 offset:3072
	ds_read_b128 v[144:147], v178
	ds_read_b128 v[164:167], v178 offset:1024
	ds_read_b128 v[168:171], v178 offset:2048
	ds_read_b128 v[178:181], v178 offset:3072
	s_add_u32 s38, s38, 0x40000
	s_addc_u32 s39, s39, 0
	s_mov_b32 m0, s43
	ds_read_b128 v[182:185], v177 offset:32768
	ds_read_b128 v[186:189], v177 offset:33792
	ds_read_b128 v[190:193], v177 offset:34816
	ds_read_b128 v[194:197], v177 offset:35840
	ds_read_b128 v[198:201], v177 offset:36864
	ds_read_b128 v[202:205], v177 offset:37888
	ds_read_b128 v[206:209], v177 offset:38912
	ds_read_b128 v[210:213], v177 offset:39936
	global_load_lds_dwordx4 v148, s[38:39]
	s_mov_b32 m0, s48
	s_nop 0
	global_load_lds_dwordx4 v152, s[38:39]
	s_waitcnt vmcnt(8)
	s_barrier
	s_waitcnt lgkmcnt(0)
	v_mfma_f32_16x16x32_bf16 v[124:127], v[128:131], v[182:185], v[124:127]
	v_mfma_f32_16x16x32_bf16 v[116:119], v[136:139], v[182:185], v[116:119]
	v_mfma_f32_16x16x32_bf16 v[120:123], v[128:131], v[190:193], v[120:123]
	v_mfma_f32_16x16x32_bf16 v[112:115], v[136:139], v[190:193], v[112:115]
	v_mfma_f32_16x16x32_bf16 v[92:95], v[128:131], v[198:201], v[92:95]
	v_mfma_f32_16x16x32_bf16 v[88:91], v[136:139], v[198:201], v[88:91]
	v_mfma_f32_16x16x32_bf16 v[76:79], v[128:131], v[206:209], v[76:79]
	v_mfma_f32_16x16x32_bf16 v[72:75], v[136:139], v[206:209], v[72:75]
	v_mfma_f32_16x16x32_bf16 v[124:127], v[132:135], v[186:189], v[124:127]
	v_mfma_f32_16x16x32_bf16 v[116:119], v[140:143], v[186:189], v[116:119]
	v_mfma_f32_16x16x32_bf16 v[120:123], v[132:135], v[194:197], v[120:123]
	v_mfma_f32_16x16x32_bf16 v[112:115], v[140:143], v[194:197], v[112:115]
	v_mfma_f32_16x16x32_bf16 v[92:95], v[132:135], v[202:205], v[92:95]
	v_mfma_f32_16x16x32_bf16 v[88:91], v[140:143], v[202:205], v[88:91]
	v_mfma_f32_16x16x32_bf16 v[76:79], v[132:135], v[210:213], v[76:79]
	v_mfma_f32_16x16x32_bf16 v[72:75], v[140:143], v[210:213], v[72:75]
	v_mfma_f32_16x16x32_bf16 v[108:111], v[144:147], v[182:185], v[108:111]
	v_mfma_f32_16x16x32_bf16 v[104:107], v[168:171], v[182:185], v[104:107]
	v_mfma_f32_16x16x32_bf16 v[100:103], v[144:147], v[190:193], v[100:103]
	v_mfma_f32_16x16x32_bf16 v[96:99], v[168:171], v[190:193], v[96:99]
	v_mfma_f32_16x16x32_bf16 v[84:87], v[144:147], v[198:201], v[84:87]
	v_mfma_f32_16x16x32_bf16 v[80:83], v[168:171], v[198:201], v[80:83]
	v_mfma_f32_16x16x32_bf16 v[68:71], v[144:147], v[206:209], v[68:71]
	v_mfma_f32_16x16x32_bf16 v[64:67], v[168:171], v[206:209], v[64:67]
	v_mfma_f32_16x16x32_bf16 v[108:111], v[164:167], v[186:189], v[108:111]
	v_mfma_f32_16x16x32_bf16 v[104:107], v[178:181], v[186:189], v[104:107]
	v_mfma_f32_16x16x32_bf16 v[100:103], v[164:167], v[194:197], v[100:103]
	v_mfma_f32_16x16x32_bf16 v[96:99], v[178:181], v[194:197], v[96:99]
	v_mfma_f32_16x16x32_bf16 v[84:87], v[164:167], v[202:205], v[84:87]
	v_mfma_f32_16x16x32_bf16 v[80:83], v[178:181], v[202:205], v[80:83]
	v_mfma_f32_16x16x32_bf16 v[68:71], v[164:167], v[210:213], v[68:71]
	v_mfma_f32_16x16x32_bf16 v[64:67], v[178:181], v[210:213], v[64:67]
	s_barrier
	s_add_i32 s38, s52, s33
	s_mov_b32 m0, s38
	ds_read_b128 v[182:185], v177 offset:49152
	ds_read_b128 v[186:189], v177 offset:50176
	ds_read_b128 v[190:193], v177 offset:51200
	ds_read_b128 v[194:197], v177 offset:52224
	ds_read_b128 v[198:201], v177 offset:53248
	ds_read_b128 v[202:205], v177 offset:54272
	ds_read_b128 v[206:209], v177 offset:55296
	ds_read_b128 v[210:213], v177 offset:56320
	global_load_lds_dwordx4 v150, s[98:99]
	s_add_i32 m0, s38, 0x2000
	s_add_u32 s36, s36, 0x40080
	s_addc_u32 s37, s37, 0
	s_add_i32 s38, s53, s33
	global_load_lds_dwordx4 v154, s[98:99]
	s_mov_b32 m0, s38
	s_nop 0
	global_load_lds_dwordx4 v150, s[36:37]
	s_add_i32 m0, s38, 0x2000
	s_nop 0
	global_load_lds_dwordx4 v154, s[36:37]
	s_mov_b32 m0, s55
	s_nop 0
	global_load_lds_dwordx4 v148, s[100:101]
	s_mov_b32 m0, s56
	s_nop 0
	global_load_lds_dwordx4 v152, s[100:101]
	s_waitcnt vmcnt(8)
	s_barrier
	s_waitcnt lgkmcnt(0)
	v_mfma_f32_16x16x32_bf16 v[60:63], v[128:131], v[182:185], v[60:63]
	v_mfma_f32_16x16x32_bf16 v[56:59], v[136:139], v[182:185], v[56:59]
	v_mfma_f32_16x16x32_bf16 v[44:47], v[128:131], v[190:193], v[44:47]
	v_mfma_f32_16x16x32_bf16 v[40:43], v[136:139], v[190:193], v[40:43]
	v_mfma_f32_16x16x32_bf16 v[36:39], v[128:131], v[198:201], v[36:39]
	v_mfma_f32_16x16x32_bf16 v[32:35], v[136:139], v[198:201], v[32:35]
	v_mfma_f32_16x16x32_bf16 v[20:23], v[128:131], v[206:209], v[20:23]
	v_mfma_f32_16x16x32_bf16 v[16:19], v[136:139], v[206:209], v[16:19]
	v_mfma_f32_16x16x32_bf16 v[60:63], v[132:135], v[186:189], v[60:63]
	v_mfma_f32_16x16x32_bf16 v[56:59], v[140:143], v[186:189], v[56:59]
	v_mfma_f32_16x16x32_bf16 v[44:47], v[132:135], v[194:197], v[44:47]
	v_mfma_f32_16x16x32_bf16 v[40:43], v[140:143], v[194:197], v[40:43]
	v_mfma_f32_16x16x32_bf16 v[36:39], v[132:135], v[202:205], v[36:39]
	v_mfma_f32_16x16x32_bf16 v[32:35], v[140:143], v[202:205], v[32:35]
	v_mfma_f32_16x16x32_bf16 v[20:23], v[132:135], v[210:213], v[20:23]
	v_mfma_f32_16x16x32_bf16 v[16:19], v[140:143], v[210:213], v[16:19]
	v_mfma_f32_16x16x32_bf16 v[52:55], v[144:147], v[182:185], v[52:55]
	v_mfma_f32_16x16x32_bf16 v[48:51], v[168:171], v[182:185], v[48:51]
	v_mfma_f32_16x16x32_bf16 v[28:31], v[144:147], v[190:193], v[28:31]
	v_mfma_f32_16x16x32_bf16 v[24:27], v[168:171], v[190:193], v[24:27]
	v_mfma_f32_16x16x32_bf16 v[12:15], v[144:147], v[198:201], v[12:15]
	v_mfma_f32_16x16x32_bf16 v[8:11], v[168:171], v[198:201], v[8:11]
	v_mfma_f32_16x16x32_bf16 v[4:7], v[144:147], v[206:209], v[4:7]
	v_mfma_f32_16x16x32_bf16 v[0:3], v[168:171], v[206:209], v[0:3]
	v_mfma_f32_16x16x32_bf16 v[52:55], v[164:167], v[186:189], v[52:55]
	v_mfma_f32_16x16x32_bf16 v[48:51], v[178:181], v[186:189], v[48:51]
	v_mfma_f32_16x16x32_bf16 v[28:31], v[164:167], v[194:197], v[28:31]
	v_mfma_f32_16x16x32_bf16 v[24:27], v[178:181], v[194:197], v[24:27]
	v_mfma_f32_16x16x32_bf16 v[12:15], v[164:167], v[202:205], v[12:15]
	v_mfma_f32_16x16x32_bf16 v[8:11], v[178:181], v[202:205], v[8:11]
	v_mfma_f32_16x16x32_bf16 v[4:7], v[164:167], v[210:213], v[4:7]
	v_mfma_f32_16x16x32_bf16 v[0:3], v[178:181], v[210:213], v[0:3]
	s_barrier
	s_add_i32 s69, s69, 2
	s_add_u32 s34, s34, 0x100
	s_addc_u32 s35, s35, 0
	s_add_u32 s67, s67, 0x100
	s_addc_u32 s68, s68, 0
	s_cmp_gt_u32 s69, 13
	s_cbranch_scc0 .LBB0_1477
	s_and_b64 vcc, exec, s[14:15]
	s_cbranch_vccz .LBB0_1480
	s_barrier

; #define PG8_STAGE(bufoff, gbase, voff) do { _Pragma("unroll") for (int _i = 0; _i < 2; ++_i) \
;         __builtin_amdgcn_global_load_lds((const unsigned*)((const char*)(gbase) + (voff)[_i]), (LAS unsigned*)(lds + (bufoff) + ldsw + _i * 8192), 16, 0, 0); } while (0)
; #define PG8_LDA(dst, b, h) do { _Pragma("unroll") for (int m = 0; m < 4; ++m) _Pragma("unroll") for (int k = 0; k < 2; ++k) dst[m][k] = *(const LAS bf16x8*)(lds + PG8_SA(b, h) + aoff + m * 2048 + k * 1024); } while (0)
; #define PG8_LDB(dst, b, h) do { _Pragma("unroll") for (int n = 0; n < 2; ++n) _Pragma("unroll") for (int k = 0; k < 2; ++k) dst[n][k] = *(const LAS bf16x8*)(lds + PG8_SB(b, h) + boff + n * 2048 + k * 1024); } while (0)
; #define PG8_MMA(ai, bj, At, Bt) do { __builtin_amdgcn_s_setprio(1); _Pragma("unroll") for (int m = 0; m < 4; ++m) _Pragma("unroll") for (int n = 0; n < 2; ++n) _Pragma("unroll") for (int k = 0; k < 2; ++k) \
;         acc[ai][bj][m][n] = __builtin_amdgcn_mfma_f32_16x16x32_bf16(Bt[n][k], At[m][k], acc[ai][bj][m][n], 0, 0, 0); __builtin_amdgcn_s_setprio(0); } while (0)
; template <class Epi, bool ALIGN_EPI, int K, int LDA, int LDB>
; __device__ __forceinline__ void gemm_phase(LAS unsigned char* lds, const int wid, const Gemm g, const StaticOrder& S, const Epi& E) {
;     ...
;         const bool has_next = S.next(ui + 1, nxt);
;         const char* nA = has_next ? (const char*)g.A + (size_t)nxt.pm * tA : cA; const char* nB = has_next ? (const char*)g.Bt + (size_t)nxt.pn * tB : cB;
;         for (int t = 0; t < nt; t += 2) {
;             const bool last = (t == nt - 2);
;             const char* a1 = cA + (size_t)(t + 1) * kstep;
;             const char* a2 = last ? nA : cA + (size_t)(t + 2) * kstep; const char* b2 = last ? nB : cB + (size_t)(t + 2) * kstep;
;             const char* a3 = a2 + kstep; const char* b3 = b2 + kstep;
;             PG8_LDB(B0, 0, 0); PG8_LDB(B1, 0, 1); PG8_SCHED; PG8_LDA(At, 0, 0); PG8_STAGE(PG8_SA(1, 1), a1 + hA, voffA);
;             PG8_WAIT_V(8); PG8_WAIT_L(0); PG8_BAR; PG8_MMA(0, 0, At, B0); PG8_MMA(0, 1, At, B1); PG8_BAR; PG8_SCHED;
;             PG8_LDA(At, 0, 1); PG8_STAGE(PG8_SB(0, 0), b2, voffB); PG8_STAGE(PG8_SB(0, 1), b2 + hB, voffB); PG8_STAGE(PG8_SA(0, 0), a2, voffA);
;             PG8_WAIT_V(8); PG8_WAIT_L(0); PG8_BAR; PG8_MMA(1, 0, At, B0); PG8_MMA(1, 1, At, B1); PG8_BAR; PG8_SCHED;
.LBB0_1696:
	s_add_u32 s61, s28, 0x100
	s_addc_u32 s62, s29, 0
	s_mov_b32 s63, -2
	s_add_u32 s28, s26, 0x100
	s_addc_u32 s29, s27, 0
	s_cmp_eq_u32 s63, 40
	s_cselect_b32 s35, s7, s29
	s_cselect_b32 s34, s6, s28
	s_cselect_b32 s31, s25, s62
	s_cselect_b32 s30, s24, s61
	s_add_i32 m0, s36, 0xc000
	global_load_lds_dwordx4 v152, s[26:27]
	s_add_i32 m0, s36, 0xe000
	s_nop 0
	global_load_lds_dwordx4 v154, s[26:27]
	s_waitcnt vmcnt(8)
	s_barrier
	s_waitcnt lgkmcnt(0)
	v_mfma_f32_16x16x32_bf16 v[140:143], v[120:123], v[182:185], 0
	v_mfma_f32_16x16x32_bf16 v[136:139], v[128:131], v[182:185], 0
	v_mfma_f32_16x16x32_bf16 v[108:111], v[120:123], v[190:193], 0
	v_mfma_f32_16x16x32_bf16 v[104:107], v[128:131], v[190:193], 0
	v_mfma_f32_16x16x32_bf16 v[92:95], v[120:123], v[198:201], 0
	v_mfma_f32_16x16x32_bf16 v[88:91], v[128:131], v[198:201], 0
	v_mfma_f32_16x16x32_bf16 v[76:79], v[120:123], v[206:209], 0
	v_mfma_f32_16x16x32_bf16 v[72:75], v[128:131], v[206:209], 0
	v_mfma_f32_16x16x32_bf16 v[140:143], v[124:127], v[186:189], v[140:143]
	v_mfma_f32_16x16x32_bf16 v[136:139], v[132:135], v[186:189], v[136:139]
	v_mfma_f32_16x16x32_bf16 v[108:111], v[124:127], v[194:197], v[108:111]
	v_mfma_f32_16x16x32_bf16 v[104:107], v[132:135], v[194:197], v[104:107]
	v_mfma_f32_16x16x32_bf16 v[92:95], v[124:127], v[202:205], v[92:95]
	v_mfma_f32_16x16x32_bf16 v[88:91], v[132:135], v[202:205], v[88:91]
	v_mfma_f32_16x16x32_bf16 v[76:79], v[124:127], v[210:213], v[76:79]
	v_mfma_f32_16x16x32_bf16 v[72:75], v[132:135], v[210:213], v[72:75]
	v_mfma_f32_16x16x32_bf16 v[116:119], v[160:163], v[182:185], 0
	v_mfma_f32_16x16x32_bf16 v[112:115], v[174:177], v[182:185], 0
	v_mfma_f32_16x16x32_bf16 v[100:103], v[160:163], v[190:193], 0
	v_mfma_f32_16x16x32_bf16 v[96:99], v[174:177], v[190:193], 0
	v_mfma_f32_16x16x32_bf16 v[84:87], v[160:163], v[198:201], 0
	v_mfma_f32_16x16x32_bf16 v[80:83], v[174:177], v[198:201], 0
	v_mfma_f32_16x16x32_bf16 v[68:71], v[160:163], v[206:209], 0
	v_mfma_f32_16x16x32_bf16 v[64:67], v[174:177], v[206:209], 0
	v_mfma_f32_16x16x32_bf16 v[116:119], v[170:173], v[186:189], v[116:119]
	v_mfma_f32_16x16x32_bf16 v[112:115], v[178:181], v[186:189], v[112:115]
	v_mfma_f32_16x16x32_bf16 v[100:103], v[170:173], v[194:197], v[100:103]
	v_mfma_f32_16x16x32_bf16 v[96:99], v[178:181], v[194:197], v[96:99]
	v_mfma_f32_16x16x32_bf16 v[84:87], v[170:173], v[202:205], v[84:87]
	v_mfma_f32_16x16x32_bf16 v[80:83], v[178:181], v[202:205], v[80:83]
	v_mfma_f32_16x16x32_bf16 v[68:71], v[170:173], v[210:213], v[68:71]
	v_mfma_f32_16x16x32_bf16 v[64:67], v[178:181], v[210:213], v[64:67]
	s_barrier
	s_add_u32 s98, s30, s12
	s_addc_u32 s99, s31, s13
	s_add_u32 s100, s34, s12
	s_addc_u32 s101, s35, s13
	s_add_i32 s26, s54, s33
	s_mov_b32 m0, s26
	ds_read_b128 v[182:185], v169 offset:16384
	ds_read_b128 v[186:189], v169 offset:17408
	ds_read_b128 v[190:193], v169 offset:18432
	ds_read_b128 v[194:197], v169 offset:19456
	ds_read_b128 v[198:201], v169 offset:20480
	ds_read_b128 v[202:205], v169 offset:21504
	ds_read_b128 v[206:209], v169 offset:22528
	ds_read_b128 v[210:213], v169 offset:23552
	global_load_lds_dwordx4 v146, s[30:31]
	s_add_i32 m0, s26, 0x2000
	s_add_u32 s26, s30, 0xb0000
	s_addc_u32 s27, s31, 0
	s_add_i32 s52, s55, s33
	global_load_lds_dwordx4 v150, s[30:31]
	s_mov_b32 m0, s52
	s_nop 0
	global_load_lds_dwordx4 v146, s[26:27]
	s_add_i32 m0, s52, 0x2000
	s_nop 0
	global_load_lds_dwordx4 v150, s[26:27]
	s_mov_b32 m0, s36
	s_nop 0
	global_load_lds_dwordx4 v144, s[34:35]
	s_mov_b32 m0, s37
	s_nop 0
	global_load_lds_dwordx4 v148, s[34:35]
	s_waitcnt vmcnt(8)
	s_barrier
	s_waitcnt lgkmcnt(0)
	v_mfma_f32_16x16x32_bf16 v[60:63], v[120:123], v[182:185], 0
	v_mfma_f32_16x16x32_bf16 v[56:59], v[128:131], v[182:185], 0
	v_mfma_f32_16x16x32_bf16 v[44:47], v[120:123], v[190:193], 0
	v_mfma_f32_16x16x32_bf16 v[40:43], v[128:131], v[190:193], 0
	v_mfma_f32_16x16x32_bf16 v[28:31], v[120:123], v[198:201], 0
	v_mfma_f32_16x16x32_bf16 v[24:27], v[128:131], v[198:201], 0
	v_mfma_f32_16x16x32_bf16 v[12:15], v[120:123], v[206:209], 0
	v_mfma_f32_16x16x32_bf16 v[8:11], v[128:131], v[206:209], 0
	v_mfma_f32_16x16x32_bf16 v[60:63], v[124:127], v[186:189], v[60:63]
	v_mfma_f32_16x16x32_bf16 v[56:59], v[132:135], v[186:189], v[56:59]
	v_mfma_f32_16x16x32_bf16 v[44:47], v[124:127], v[194:197], v[44:47]
	v_mfma_f32_16x16x32_bf16 v[40:43], v[132:135], v[194:197], v[40:43]
	v_mfma_f32_16x16x32_bf16 v[28:31], v[124:127], v[202:205], v[28:31]
	v_mfma_f32_16x16x32_bf16 v[24:27], v[132:135], v[202:205], v[24:27]
	v_mfma_f32_16x16x32_bf16 v[12:15], v[124:127], v[210:213], v[12:15]
	v_mfma_f32_16x16x32_bf16 v[8:11], v[132:135], v[210:213], v[8:11]
	v_mfma_f32_16x16x32_bf16 v[52:55], v[160:163], v[182:185], 0
	v_mfma_f32_16x16x32_bf16 v[48:51], v[174:177], v[182:185], 0
	v_mfma_f32_16x16x32_bf16 v[36:39], v[160:163], v[190:193], 0
	v_mfma_f32_16x16x32_bf16 v[32:35], v[174:177], v[190:193], 0
	v_mfma_f32_16x16x32_bf16 v[20:23], v[160:163], v[198:201], 0
	v_mfma_f32_16x16x32_bf16 v[16:19], v[174:177], v[198:201], 0
	v_mfma_f32_16x16x32_bf16 v[4:7], v[160:163], v[206:209], 0
	v_mfma_f32_16x16x32_bf16 v[0:3], v[174:177], v[206:209], 0
	v_mfma_f32_16x16x32_bf16 v[52:55], v[170:173], v[186:189], v[52:55]
	v_mfma_f32_16x16x32_bf16 v[48:51], v[178:181], v[186:189], v[48:51]
	v_mfma_f32_16x16x32_bf16 v[36:39], v[170:173], v[194:197], v[36:39]
	v_mfma_f32_16x16x32_bf16 v[32:35], v[178:181], v[194:197], v[32:35]
	v_mfma_f32_16x16x32_bf16 v[20:23], v[170:173], v[202:205], v[20:23]
	v_mfma_f32_16x16x32_bf16 v[16:19], v[178:181], v[202:205], v[16:19]
	v_mfma_f32_16x16x32_bf16 v[4:7], v[170:173], v[210:213], v[4:7]
	v_mfma_f32_16x16x32_bf16 v[0:3], v[178:181], v[210:213], v[0:3]
	s_barrier
; #define PG8_STAGE(bufoff, gbase, voff) do { _Pragma("unroll") for (int _i = 0; _i < 2; ++_i) \
;         __builtin_amdgcn_global_load_lds((const unsigned*)((const char*)(gbase) + (voff)[_i]), (LAS unsigned*)(lds + (bufoff) + ldsw + _i * 8192), 16, 0, 0); } while (0)
; #define PG8_LDA(dst, b, h) do { _Pragma("unroll") for (int m = 0; m < 4; ++m) _Pragma("unroll") for (int k = 0; k < 2; ++k) dst[m][k] = *(const LAS bf16x8*)(lds + PG8_SA(b, h) + aoff + m * 2048 + k * 1024); } while (0)
; #define PG8_LDB(dst, b, h) do { _Pragma("unroll") for (int n = 0; n < 2; ++n) _Pragma("unroll") for (int k = 0; k < 2; ++k) dst[n][k] = *(const LAS bf16x8*)(lds + PG8_SB(b, h) + boff + n * 2048 + k * 1024); } while (0)
; #define PG8_MMA(ai, bj, At, Bt) do { __builtin_amdgcn_s_setprio(1); _Pragma("unroll") for (int m = 0; m < 4; ++m) _Pragma("unroll") for (int n = 0; n < 2; ++n) _Pragma("unroll") for (int k = 0; k < 2; ++k) \
;         acc[ai][bj][m][n] = __builtin_amdgcn_mfma_f32_16x16x32_bf16(Bt[n][k], At[m][k], acc[ai][bj][m][n], 0, 0, 0); __builtin_amdgcn_s_setprio(0); } while (0)
; #define PG8_WAIT_V(n) asm volatile("s_waitcnt vmcnt(" #n ")" ::: "memory")
; #define PG8_WAIT_L(n) asm volatile("s_waitcnt lgkmcnt(" #n ")" ::: "memory")
; #define PG8_BAR __builtin_amdgcn_s_barrier()
; #define PG8_SCHED __builtin_amdgcn_sched_barrier(0)
; template <class Epi, bool ALIGN_EPI, int K, int LDA, int LDB>
; __device__ __forceinline__ void gemm_phase(LAS unsigned char* lds, const int wid, const Gemm g, const StaticOrder& S, const Epi& E) {
;     ...
;             PG8_LDB(B0, 1, 0); PG8_LDB(B1, 1, 1); PG8_SCHED; PG8_LDA(At, 1, 0); PG8_STAGE(PG8_SA(0, 1), a2 + hA, voffA);
;             PG8_WAIT_V(8); PG8_WAIT_L(0); PG8_BAR; PG8_MMA(0, 0, At, B0); PG8_MMA(0, 1, At, B1); PG8_BAR; PG8_SCHED;
;             PG8_LDA(At, 1, 1); PG8_STAGE(PG8_SB(1, 0), b3, voffB); PG8_STAGE(PG8_SB(1, 1), b3 + hB, voffB); PG8_STAGE(PG8_SA(1, 0), a3, voffA);
;             PG8_WAIT_V(8); PG8_WAIT_L(0); PG8_BAR; PG8_MMA(1, 0, At, B0); PG8_MMA(1, 1, At, B1); PG8_BAR; PG8_SCHED;
	s_add_i32 s52, 0, 0x18000
	s_add_i32 s53, 0, 0x1c000
	v_add_u32_e32 v132, s52, v166
	v_add_u32_e32 v178, s53, v166
	ds_read_b128 v[120:123], v132
	ds_read_b128 v[124:127], v132 offset:1024
	ds_read_b128 v[128:131], v132 offset:2048
	ds_read_b128 v[132:135], v132 offset:3072
	ds_read_b128 v[160:163], v178
	ds_read_b128 v[170:173], v178 offset:1024
	ds_read_b128 v[174:177], v178 offset:2048
	ds_read_b128 v[178:181], v178 offset:3072
	s_add_u32 s26, s34, 0xb0000
	s_addc_u32 s27, s35, 0
	s_mov_b32 m0, s38
	ds_read_b128 v[182:185], v169 offset:32768
	ds_read_b128 v[186:189], v169 offset:33792
	ds_read_b128 v[190:193], v169 offset:34816
	ds_read_b128 v[194:197], v169 offset:35840
	ds_read_b128 v[198:201], v169 offset:36864
	ds_read_b128 v[202:205], v169 offset:37888
	ds_read_b128 v[206:209], v169 offset:38912
	ds_read_b128 v[210:213], v169 offset:39936
	global_load_lds_dwordx4 v144, s[26:27]
	s_mov_b32 m0, s39
	s_nop 0
	global_load_lds_dwordx4 v148, s[26:27]
	s_waitcnt vmcnt(8)
	s_barrier
	s_waitcnt lgkmcnt(0)
	v_mfma_f32_16x16x32_bf16 v[140:143], v[120:123], v[182:185], v[140:143]
	v_mfma_f32_16x16x32_bf16 v[136:139], v[128:131], v[182:185], v[136:139]
	v_mfma_f32_16x16x32_bf16 v[108:111], v[120:123], v[190:193], v[108:111]
	v_mfma_f32_16x16x32_bf16 v[104:107], v[128:131], v[190:193], v[104:107]
	v_mfma_f32_16x16x32_bf16 v[92:95], v[120:123], v[198:201], v[92:95]
	v_mfma_f32_16x16x32_bf16 v[88:91], v[128:131], v[198:201], v[88:91]
	v_mfma_f32_16x16x32_bf16 v[76:79], v[120:123], v[206:209], v[76:79]
	v_mfma_f32_16x16x32_bf16 v[72:75], v[128:131], v[206:209], v[72:75]
	v_mfma_f32_16x16x32_bf16 v[140:143], v[124:127], v[186:189], v[140:143]
	v_mfma_f32_16x16x32_bf16 v[136:139], v[132:135], v[186:189], v[136:139]
	v_mfma_f32_16x16x32_bf16 v[108:111], v[124:127], v[194:197], v[108:111]
	v_mfma_f32_16x16x32_bf16 v[104:107], v[132:135], v[194:197], v[104:107]
	v_mfma_f32_16x16x32_bf16 v[92:95], v[124:127], v[202:205], v[92:95]
	v_mfma_f32_16x16x32_bf16 v[88:91], v[132:135], v[202:205], v[88:91]
	v_mfma_f32_16x16x32_bf16 v[76:79], v[124:127], v[210:213], v[76:79]
	v_mfma_f32_16x16x32_bf16 v[72:75], v[132:135], v[210:213], v[72:75]
	v_mfma_f32_16x16x32_bf16 v[116:119], v[160:163], v[182:185], v[116:119]
	v_mfma_f32_16x16x32_bf16 v[112:115], v[174:177], v[182:185], v[112:115]
	v_mfma_f32_16x16x32_bf16 v[100:103], v[160:163], v[190:193], v[100:103]
	v_mfma_f32_16x16x32_bf16 v[96:99], v[174:177], v[190:193], v[96:99]
	v_mfma_f32_16x16x32_bf16 v[84:87], v[160:163], v[198:201], v[84:87]
	v_mfma_f32_16x16x32_bf16 v[80:83], v[174:177], v[198:201], v[80:83]
	v_mfma_f32_16x16x32_bf16 v[68:71], v[160:163], v[206:209], v[68:71]
	v_mfma_f32_16x16x32_bf16 v[64:67], v[174:177], v[206:209], v[64:67]
	v_mfma_f32_16x16x32_bf16 v[116:119], v[170:173], v[186:189], v[116:119]
	v_mfma_f32_16x16x32_bf16 v[112:115], v[178:181], v[186:189], v[112:115]
	v_mfma_f32_16x16x32_bf16 v[100:103], v[170:173], v[194:197], v[100:103]
	v_mfma_f32_16x16x32_bf16 v[96:99], v[178:181], v[194:197], v[96:99]
	v_mfma_f32_16x16x32_bf16 v[84:87], v[170:173], v[202:205], v[84:87]
	v_mfma_f32_16x16x32_bf16 v[80:83], v[178:181], v[202:205], v[80:83]
	v_mfma_f32_16x16x32_bf16 v[68:71], v[170:173], v[210:213], v[68:71]
	v_mfma_f32_16x16x32_bf16 v[64:67], v[178:181], v[210:213], v[64:67]
	s_barrier
	s_add_i32 s26, s52, s33
	s_mov_b32 m0, s26
	ds_read_b128 v[182:185], v169 offset:49152
	ds_read_b128 v[186:189], v169 offset:50176
	ds_read_b128 v[190:193], v169 offset:51200
	ds_read_b128 v[194:197], v169 offset:52224
	ds_read_b128 v[198:201], v169 offset:53248
	ds_read_b128 v[202:205], v169 offset:54272
	ds_read_b128 v[206:209], v169 offset:55296
	ds_read_b128 v[210:213], v169 offset:56320
	global_load_lds_dwordx4 v146, s[98:99]
	s_add_i32 m0, s26, 0x2000
	s_add_u32 s26, s30, 0xb0080
	s_addc_u32 s27, s31, 0
	s_add_i32 s30, s53, s33
	global_load_lds_dwordx4 v150, s[98:99]
	s_mov_b32 m0, s30
	s_nop 0
	global_load_lds_dwordx4 v146, s[26:27]
	s_add_i32 m0, s30, 0x2000
	s_nop 0
	global_load_lds_dwordx4 v150, s[26:27]
	s_mov_b32 m0, s48
	s_nop 0
	global_load_lds_dwordx4 v144, s[100:101]
	s_mov_b32 m0, s49
	s_nop 0
	global_load_lds_dwordx4 v148, s[100:101]
	s_waitcnt vmcnt(8)
	s_barrier
	s_waitcnt lgkmcnt(0)
	v_mfma_f32_16x16x32_bf16 v[60:63], v[120:123], v[182:185], v[60:63]
	v_mfma_f32_16x16x32_bf16 v[56:59], v[128:131], v[182:185], v[56:59]
	v_mfma_f32_16x16x32_bf16 v[44:47], v[120:123], v[190:193], v[44:47]
	v_mfma_f32_16x16x32_bf16 v[40:43], v[128:131], v[190:193], v[40:43]
	v_mfma_f32_16x16x32_bf16 v[28:31], v[120:123], v[198:201], v[28:31]
	v_mfma_f32_16x16x32_bf16 v[24:27], v[128:131], v[198:201], v[24:27]
	v_mfma_f32_16x16x32_bf16 v[12:15], v[120:123], v[206:209], v[12:15]
	v_mfma_f32_16x16x32_bf16 v[8:11], v[128:131], v[206:209], v[8:11]
	v_mfma_f32_16x16x32_bf16 v[60:63], v[124:127], v[186:189], v[60:63]
	v_mfma_f32_16x16x32_bf16 v[56:59], v[132:135], v[186:189], v[56:59]
	v_mfma_f32_16x16x32_bf16 v[44:47], v[124:127], v[194:197], v[44:47]
	v_mfma_f32_16x16x32_bf16 v[40:43], v[132:135], v[194:197], v[40:43]
	v_mfma_f32_16x16x32_bf16 v[28:31], v[124:127], v[202:205], v[28:31]
	v_mfma_f32_16x16x32_bf16 v[24:27], v[132:135], v[202:205], v[24:27]
	v_mfma_f32_16x16x32_bf16 v[12:15], v[124:127], v[210:213], v[12:15]
	v_mfma_f32_16x16x32_bf16 v[8:11], v[132:135], v[210:213], v[8:11]
	v_mfma_f32_16x16x32_bf16 v[52:55], v[160:163], v[182:185], v[52:55]
	v_mfma_f32_16x16x32_bf16 v[48:51], v[174:177], v[182:185], v[48:51]
	v_mfma_f32_16x16x32_bf16 v[36:39], v[160:163], v[190:193], v[36:39]
	v_mfma_f32_16x16x32_bf16 v[32:35], v[174:177], v[190:193], v[32:35]
	v_mfma_f32_16x16x32_bf16 v[20:23], v[160:163], v[198:201], v[20:23]
	v_mfma_f32_16x16x32_bf16 v[16:19], v[174:177], v[198:201], v[16:19]
	v_mfma_f32_16x16x32_bf16 v[4:7], v[160:163], v[206:209], v[4:7]
	v_mfma_f32_16x16x32_bf16 v[0:3], v[174:177], v[206:209], v[0:3]
	v_mfma_f32_16x16x32_bf16 v[52:55], v[170:173], v[186:189], v[52:55]
	v_mfma_f32_16x16x32_bf16 v[48:51], v[178:181], v[186:189], v[48:51]
	v_mfma_f32_16x16x32_bf16 v[36:39], v[170:173], v[194:197], v[36:39]
	v_mfma_f32_16x16x32_bf16 v[32:35], v[178:181], v[194:197], v[32:35]
	v_mfma_f32_16x16x32_bf16 v[20:23], v[170:173], v[202:205], v[20:23]
	v_mfma_f32_16x16x32_bf16 v[16:19], v[178:181], v[202:205], v[16:19]
	v_mfma_f32_16x16x32_bf16 v[4:7], v[170:173], v[210:213], v[4:7]
	v_mfma_f32_16x16x32_bf16 v[0:3], v[178:181], v[210:213], v[0:3]
	s_barrier
	s_add_i32 s63, s63, 2
	s_add_u32 s61, s61, 0x100
	s_addc_u32 s62, s62, 0
	s_mov_b64 s[26:27], s[28:29]
; #define PG8_STAGE(bufoff, gbase, voff) do { _Pragma("unroll") for (int _i = 0; _i < 2; ++_i) \
;         __builtin_amdgcn_global_load_lds((const unsigned*)((const char*)(gbase) + (voff)[_i]), (LAS unsigned*)(lds + (bufoff) + ldsw + _i * 8192), 16, 0, 0); } while (0)
; #define PG8_LDA(dst, b, h) do { _Pragma("unroll") for (int m = 0; m < 4; ++m) _Pragma("unroll") for (int k = 0; k < 2; ++k) dst[m][k] = *(const LAS bf16x8*)(lds + PG8_SA(b, h) + aoff + m * 2048 + k * 1024); } while (0)
; #define PG8_LDB(dst, b, h) do { _Pragma("unroll") for (int n = 0; n < 2; ++n) _Pragma("unroll") for (int k = 0; k < 2; ++k) dst[n][k] = *(const LAS bf16x8*)(lds + PG8_SB(b, h) + boff + n * 2048 + k * 1024); } while (0)
; #define PG8_MMA(ai, bj, At, Bt) do { __builtin_amdgcn_s_setprio(1); _Pragma("unroll") for (int m = 0; m < 4; ++m) _Pragma("unroll") for (int n = 0; n < 2; ++n) _Pragma("unroll") for (int k = 0; k < 2; ++k) \
;         acc[ai][bj][m][n] = __builtin_amdgcn_mfma_f32_16x16x32_bf16(Bt[n][k], At[m][k], acc[ai][bj][m][n], 0, 0, 0); __builtin_amdgcn_s_setprio(0); } while (0)
; #define PG8_WAIT_V(n) asm volatile("s_waitcnt vmcnt(" #n ")" ::: "memory")
; #define PG8_WAIT_L(n) asm volatile("s_waitcnt lgkmcnt(" #n ")" ::: "memory")
; #define PG8_BAR __builtin_amdgcn_s_barrier()
; template <class Epi, bool ALIGN_EPI, int K, int LDA, int LDB>
; __device__ __forceinline__ void gemm_phase(LAS unsigned char* lds, const int wid, const Gemm g, const StaticOrder& S, const Epi& E) {
;     ...
;         for (int t = 0; t < nt; t += 2) {
;             const bool last = (t == nt - 2);
;             const char* a1 = cA + (size_t)(t + 1) * kstep;
;             const char* a2 = last ? nA : cA + (size_t)(t + 2) * kstep; const char* b2 = last ? nB : cB + (size_t)(t + 2) * kstep;
;             const char* a3 = a2 + kstep; const char* b3 = b2 + kstep;
;             PG8_LDB(B0, 0, 0); PG8_LDB(B1, 0, 1); PG8_SCHED; PG8_LDA(At, 0, 0); PG8_STAGE(PG8_SA(1, 1), a1 + hA, voffA);
;             PG8_WAIT_V(8); PG8_WAIT_L(0); PG8_BAR; PG8_MMA(0, 0, At, B0); PG8_MMA(0, 1, At, B1); PG8_BAR; PG8_SCHED;
;             PG8_LDA(At, 0, 1); PG8_STAGE(PG8_SB(0, 0), b2, voffB); PG8_STAGE(PG8_SB(0, 1), b2 + hB, voffB); PG8_STAGE(PG8_SA(0, 0), a2, voffA);
;             PG8_WAIT_V(8); PG8_WAIT_L(0); PG8_BAR; PG8_MMA(1, 0, At, B0); PG8_MMA(1, 1, At, B1); PG8_BAR; PG8_SCHED;
.LBB0_1697:
	ds_read_b128 v[120:123], v167
	ds_read_b128 v[124:127], v167 offset:1024
	ds_read_b128 v[128:131], v167 offset:2048
	ds_read_b128 v[132:135], v167 offset:3072
	ds_read_b128 v[160:163], v168
	ds_read_b128 v[170:173], v168 offset:1024
	ds_read_b128 v[174:177], v168 offset:2048
	ds_read_b128 v[178:181], v168 offset:3072
	s_add_u32 s28, s26, 0x100
	s_addc_u32 s29, s27, 0
	s_cmp_eq_u32 s63, 40
	s_cselect_b32 s35, s7, s29
	s_cselect_b32 s34, s6, s28
	s_cselect_b32 s31, s25, s62
	s_cselect_b32 s30, s24, s61
	s_add_i32 m0, s36, 0xc000
	ds_read_b128 v[182:185], v169
	ds_read_b128 v[186:189], v169 offset:1024
	ds_read_b128 v[190:193], v169 offset:2048
	ds_read_b128 v[194:197], v169 offset:3072
	ds_read_b128 v[198:201], v169 offset:4096
	ds_read_b128 v[202:205], v169 offset:5120
	ds_read_b128 v[206:209], v169 offset:6144
	ds_read_b128 v[210:213], v169 offset:7168
	global_load_lds_dwordx4 v152, s[26:27]
	s_add_i32 m0, s36, 0xe000
	s_nop 0
	global_load_lds_dwordx4 v154, s[26:27]
	s_waitcnt vmcnt(8)
	s_barrier
	s_waitcnt lgkmcnt(0)
	v_mfma_f32_16x16x32_bf16 v[140:143], v[120:123], v[182:185], v[140:143]
	v_mfma_f32_16x16x32_bf16 v[136:139], v[128:131], v[182:185], v[136:139]
	v_mfma_f32_16x16x32_bf16 v[108:111], v[120:123], v[190:193], v[108:111]
	v_mfma_f32_16x16x32_bf16 v[104:107], v[128:131], v[190:193], v[104:107]
	v_mfma_f32_16x16x32_bf16 v[92:95], v[120:123], v[198:201], v[92:95]
	v_mfma_f32_16x16x32_bf16 v[88:91], v[128:131], v[198:201], v[88:91]
	v_mfma_f32_16x16x32_bf16 v[76:79], v[120:123], v[206:209], v[76:79]
	v_mfma_f32_16x16x32_bf16 v[72:75], v[128:131], v[206:209], v[72:75]
	v_mfma_f32_16x16x32_bf16 v[140:143], v[124:127], v[186:189], v[140:143]
	v_mfma_f32_16x16x32_bf16 v[136:139], v[132:135], v[186:189], v[136:139]
	v_mfma_f32_16x16x32_bf16 v[108:111], v[124:127], v[194:197], v[108:111]
	v_mfma_f32_16x16x32_bf16 v[104:107], v[132:135], v[194:197], v[104:107]
	v_mfma_f32_16x16x32_bf16 v[92:95], v[124:127], v[202:205], v[92:95]
	v_mfma_f32_16x16x32_bf16 v[88:91], v[132:135], v[202:205], v[88:91]
	v_mfma_f32_16x16x32_bf16 v[76:79], v[124:127], v[210:213], v[76:79]
	v_mfma_f32_16x16x32_bf16 v[72:75], v[132:135], v[210:213], v[72:75]
	v_mfma_f32_16x16x32_bf16 v[116:119], v[160:163], v[182:185], v[116:119]
	v_mfma_f32_16x16x32_bf16 v[112:115], v[174:177], v[182:185], v[112:115]
	v_mfma_f32_16x16x32_bf16 v[100:103], v[160:163], v[190:193], v[100:103]
	v_mfma_f32_16x16x32_bf16 v[96:99], v[174:177], v[190:193], v[96:99]
	v_mfma_f32_16x16x32_bf16 v[84:87], v[160:163], v[198:201], v[84:87]
	v_mfma_f32_16x16x32_bf16 v[80:83], v[174:177], v[198:201], v[80:83]
	v_mfma_f32_16x16x32_bf16 v[68:71], v[160:163], v[206:209], v[68:71]
	v_mfma_f32_16x16x32_bf16 v[64:67], v[174:177], v[206:209], v[64:67]
	v_mfma_f32_16x16x32_bf16 v[116:119], v[170:173], v[186:189], v[116:119]
	v_mfma_f32_16x16x32_bf16 v[112:115], v[178:181], v[186:189], v[112:115]
	v_mfma_f32_16x16x32_bf16 v[100:103], v[170:173], v[194:197], v[100:103]
	v_mfma_f32_16x16x32_bf16 v[96:99], v[178:181], v[194:197], v[96:99]
	v_mfma_f32_16x16x32_bf16 v[84:87], v[170:173], v[202:205], v[84:87]
	v_mfma_f32_16x16x32_bf16 v[80:83], v[178:181], v[202:205], v[80:83]
	v_mfma_f32_16x16x32_bf16 v[68:71], v[170:173], v[210:213], v[68:71]
	v_mfma_f32_16x16x32_bf16 v[64:67], v[178:181], v[210:213], v[64:67]
	s_barrier
	s_add_u32 s98, s30, s12
	s_addc_u32 s99, s31, s13
	s_add_u32 s100, s34, s12
	s_addc_u32 s101, s35, s13
	s_add_i32 s26, s54, s33
	s_mov_b32 m0, s26
	ds_read_b128 v[182:185], v169 offset:16384
	ds_read_b128 v[186:189], v169 offset:17408
	ds_read_b128 v[190:193], v169 offset:18432
	ds_read_b128 v[194:197], v169 offset:19456
	ds_read_b128 v[198:201], v169 offset:20480
	ds_read_b128 v[202:205], v169 offset:21504
	ds_read_b128 v[206:209], v169 offset:22528
	ds_read_b128 v[210:213], v169 offset:23552
	global_load_lds_dwordx4 v146, s[30:31]
	s_add_i32 m0, s26, 0x2000
	s_add_u32 s26, s30, 0xb0000
	s_addc_u32 s27, s31, 0
	s_add_i32 s52, s55, s33
	global_load_lds_dwordx4 v150, s[30:31]
	s_mov_b32 m0, s52
	s_nop 0
	global_load_lds_dwordx4 v146, s[26:27]
	s_add_i32 m0, s52, 0x2000
	s_nop 0
	global_load_lds_dwordx4 v150, s[26:27]
	s_mov_b32 m0, s36
	s_nop 0
	global_load_lds_dwordx4 v144, s[34:35]
	s_mov_b32 m0, s37
	s_nop 0
	global_load_lds_dwordx4 v148, s[34:35]
	s_waitcnt vmcnt(8)
	s_barrier
	s_waitcnt lgkmcnt(0)
	v_mfma_f32_16x16x32_bf16 v[60:63], v[120:123], v[182:185], v[60:63]
	v_mfma_f32_16x16x32_bf16 v[56:59], v[128:131], v[182:185], v[56:59]
	v_mfma_f32_16x16x32_bf16 v[44:47], v[120:123], v[190:193], v[44:47]
	v_mfma_f32_16x16x32_bf16 v[40:43], v[128:131], v[190:193], v[40:43]
	v_mfma_f32_16x16x32_bf16 v[28:31], v[120:123], v[198:201], v[28:31]
	v_mfma_f32_16x16x32_bf16 v[24:27], v[128:131], v[198:201], v[24:27]
	v_mfma_f32_16x16x32_bf16 v[12:15], v[120:123], v[206:209], v[12:15]
	v_mfma_f32_16x16x32_bf16 v[8:11], v[128:131], v[206:209], v[8:11]
	v_mfma_f32_16x16x32_bf16 v[60:63], v[124:127], v[186:189], v[60:63]
	v_mfma_f32_16x16x32_bf16 v[56:59], v[132:135], v[186:189], v[56:59]
	v_mfma_f32_16x16x32_bf16 v[44:47], v[124:127], v[194:197], v[44:47]
	v_mfma_f32_16x16x32_bf16 v[40:43], v[132:135], v[194:197], v[40:43]
	v_mfma_f32_16x16x32_bf16 v[28:31], v[124:127], v[202:205], v[28:31]
	v_mfma_f32_16x16x32_bf16 v[24:27], v[132:135], v[202:205], v[24:27]
	v_mfma_f32_16x16x32_bf16 v[12:15], v[124:127], v[210:213], v[12:15]
	v_mfma_f32_16x16x32_bf16 v[8:11], v[132:135], v[210:213], v[8:11]
	v_mfma_f32_16x16x32_bf16 v[52:55], v[160:163], v[182:185], v[52:55]
	v_mfma_f32_16x16x32_bf16 v[48:51], v[174:177], v[182:185], v[48:51]
	v_mfma_f32_16x16x32_bf16 v[36:39], v[160:163], v[190:193], v[36:39]
	v_mfma_f32_16x16x32_bf16 v[32:35], v[174:177], v[190:193], v[32:35]
	v_mfma_f32_16x16x32_bf16 v[20:23], v[160:163], v[198:201], v[20:23]
	v_mfma_f32_16x16x32_bf16 v[16:19], v[174:177], v[198:201], v[16:19]
	v_mfma_f32_16x16x32_bf16 v[4:7], v[160:163], v[206:209], v[4:7]
	v_mfma_f32_16x16x32_bf16 v[0:3], v[174:177], v[206:209], v[0:3]
	v_mfma_f32_16x16x32_bf16 v[52:55], v[170:173], v[186:189], v[52:55]
	v_mfma_f32_16x16x32_bf16 v[48:51], v[178:181], v[186:189], v[48:51]
	v_mfma_f32_16x16x32_bf16 v[36:39], v[170:173], v[194:197], v[36:39]
	v_mfma_f32_16x16x32_bf16 v[32:35], v[178:181], v[194:197], v[32:35]
	v_mfma_f32_16x16x32_bf16 v[20:23], v[170:173], v[202:205], v[20:23]
	v_mfma_f32_16x16x32_bf16 v[16:19], v[178:181], v[202:205], v[16:19]
	v_mfma_f32_16x16x32_bf16 v[4:7], v[170:173], v[210:213], v[4:7]
	v_mfma_f32_16x16x32_bf16 v[0:3], v[178:181], v[210:213], v[0:3]
	s_barrier
; #define PG8_STAGE(bufoff, gbase, voff) do { _Pragma("unroll") for (int _i = 0; _i < 2; ++_i) \
;         __builtin_amdgcn_global_load_lds((const unsigned*)((const char*)(gbase) + (voff)[_i]), (LAS unsigned*)(lds + (bufoff) + ldsw + _i * 8192), 16, 0, 0); } while (0)
; #define PG8_LDA(dst, b, h) do { _Pragma("unroll") for (int m = 0; m < 4; ++m) _Pragma("unroll") for (int k = 0; k < 2; ++k) dst[m][k] = *(const LAS bf16x8*)(lds + PG8_SA(b, h) + aoff + m * 2048 + k * 1024); } while (0)
; #define PG8_LDB(dst, b, h) do { _Pragma("unroll") for (int n = 0; n < 2; ++n) _Pragma("unroll") for (int k = 0; k < 2; ++k) dst[n][k] = *(const LAS bf16x8*)(lds + PG8_SB(b, h) + boff + n * 2048 + k * 1024); } while (0)
; #define PG8_MMA(ai, bj, At, Bt) do { __builtin_amdgcn_s_setprio(1); _Pragma("unroll") for (int m = 0; m < 4; ++m) _Pragma("unroll") for (int n = 0; n < 2; ++n) _Pragma("unroll") for (int k = 0; k < 2; ++k) \
;         acc[ai][bj][m][n] = __builtin_amdgcn_mfma_f32_16x16x32_bf16(Bt[n][k], At[m][k], acc[ai][bj][m][n], 0, 0, 0); __builtin_amdgcn_s_setprio(0); } while (0)
; #define PG8_WAIT_V(n) asm volatile("s_waitcnt vmcnt(" #n ")" ::: "memory")
; #define PG8_WAIT_L(n) asm volatile("s_waitcnt lgkmcnt(" #n ")" ::: "memory")
; #define PG8_BAR __builtin_amdgcn_s_barrier()
; #define PG8_SCHED __builtin_amdgcn_sched_barrier(0)
; template <class Epi, bool ALIGN_EPI, int K, int LDA, int LDB>
; __device__ __forceinline__ void gemm_phase(LAS unsigned char* lds, const int wid, const Gemm g, const StaticOrder& S, const Epi& E) {
;     ...
;             PG8_LDB(B0, 1, 0); PG8_LDB(B1, 1, 1); PG8_SCHED; PG8_LDA(At, 1, 0); PG8_STAGE(PG8_SA(0, 1), a2 + hA, voffA);
;             PG8_WAIT_V(8); PG8_WAIT_L(0); PG8_BAR; PG8_MMA(0, 0, At, B0); PG8_MMA(0, 1, At, B1); PG8_BAR; PG8_SCHED;
;             PG8_LDA(At, 1, 1); PG8_STAGE(PG8_SB(1, 0), b3, voffB); PG8_STAGE(PG8_SB(1, 1), b3 + hB, voffB); PG8_STAGE(PG8_SA(1, 0), a3, voffA);
;             PG8_WAIT_V(8); PG8_WAIT_L(0); PG8_BAR; PG8_MMA(1, 0, At, B0); PG8_MMA(1, 1, At, B1); PG8_BAR; PG8_SCHED;
;         }
	s_add_i32 s52, 0, 0x18000
	s_add_i32 s53, 0, 0x1c000
	v_add_u32_e32 v132, s52, v166
	v_add_u32_e32 v178, s53, v166
	ds_read_b128 v[120:123], v132
	ds_read_b128 v[124:127], v132 offset:1024
	ds_read_b128 v[128:131], v132 offset:2048
	ds_read_b128 v[132:135], v132 offset:3072
	ds_read_b128 v[160:163], v178
	ds_read_b128 v[170:173], v178 offset:1024
	ds_read_b128 v[174:177], v178 offset:2048
	ds_read_b128 v[178:181], v178 offset:3072
	s_add_u32 s26, s34, 0xb0000
	s_addc_u32 s27, s35, 0
	s_mov_b32 m0, s38
	ds_read_b128 v[182:185], v169 offset:32768
	ds_read_b128 v[186:189], v169 offset:33792
	ds_read_b128 v[190:193], v169 offset:34816
	ds_read_b128 v[194:197], v169 offset:35840
	ds_read_b128 v[198:201], v169 offset:36864
	ds_read_b128 v[202:205], v169 offset:37888
	ds_read_b128 v[206:209], v169 offset:38912
	ds_read_b128 v[210:213], v169 offset:39936
	global_load_lds_dwordx4 v144, s[26:27]
	s_mov_b32 m0, s39
	s_nop 0
	global_load_lds_dwordx4 v148, s[26:27]
	s_waitcnt vmcnt(8)
	s_barrier
	s_waitcnt lgkmcnt(0)
	v_mfma_f32_16x16x32_bf16 v[140:143], v[120:123], v[182:185], v[140:143]
	v_mfma_f32_16x16x32_bf16 v[136:139], v[128:131], v[182:185], v[136:139]
	v_mfma_f32_16x16x32_bf16 v[108:111], v[120:123], v[190:193], v[108:111]
	v_mfma_f32_16x16x32_bf16 v[104:107], v[128:131], v[190:193], v[104:107]
	v_mfma_f32_16x16x32_bf16 v[92:95], v[120:123], v[198:201], v[92:95]
	v_mfma_f32_16x16x32_bf16 v[88:91], v[128:131], v[198:201], v[88:91]
	v_mfma_f32_16x16x32_bf16 v[76:79], v[120:123], v[206:209], v[76:79]
	v_mfma_f32_16x16x32_bf16 v[72:75], v[128:131], v[206:209], v[72:75]
	v_mfma_f32_16x16x32_bf16 v[140:143], v[124:127], v[186:189], v[140:143]
	v_mfma_f32_16x16x32_bf16 v[136:139], v[132:135], v[186:189], v[136:139]
	v_mfma_f32_16x16x32_bf16 v[108:111], v[124:127], v[194:197], v[108:111]
	v_mfma_f32_16x16x32_bf16 v[104:107], v[132:135], v[194:197], v[104:107]
	v_mfma_f32_16x16x32_bf16 v[92:95], v[124:127], v[202:205], v[92:95]
	v_mfma_f32_16x16x32_bf16 v[88:91], v[132:135], v[202:205], v[88:91]
	v_mfma_f32_16x16x32_bf16 v[76:79], v[124:127], v[210:213], v[76:79]
	v_mfma_f32_16x16x32_bf16 v[72:75], v[132:135], v[210:213], v[72:75]
	v_mfma_f32_16x16x32_bf16 v[116:119], v[160:163], v[182:185], v[116:119]
	v_mfma_f32_16x16x32_bf16 v[112:115], v[174:177], v[182:185], v[112:115]
	v_mfma_f32_16x16x32_bf16 v[100:103], v[160:163], v[190:193], v[100:103]
	v_mfma_f32_16x16x32_bf16 v[96:99], v[174:177], v[190:193], v[96:99]
	v_mfma_f32_16x16x32_bf16 v[84:87], v[160:163], v[198:201], v[84:87]
	v_mfma_f32_16x16x32_bf16 v[80:83], v[174:177], v[198:201], v[80:83]
	v_mfma_f32_16x16x32_bf16 v[68:71], v[160:163], v[206:209], v[68:71]
	v_mfma_f32_16x16x32_bf16 v[64:67], v[174:177], v[206:209], v[64:67]
	v_mfma_f32_16x16x32_bf16 v[116:119], v[170:173], v[186:189], v[116:119]
	v_mfma_f32_16x16x32_bf16 v[112:115], v[178:181], v[186:189], v[112:115]
	v_mfma_f32_16x16x32_bf16 v[100:103], v[170:173], v[194:197], v[100:103]
	v_mfma_f32_16x16x32_bf16 v[96:99], v[178:181], v[194:197], v[96:99]
	v_mfma_f32_16x16x32_bf16 v[84:87], v[170:173], v[202:205], v[84:87]
	v_mfma_f32_16x16x32_bf16 v[80:83], v[178:181], v[202:205], v[80:83]
	v_mfma_f32_16x16x32_bf16 v[68:71], v[170:173], v[210:213], v[68:71]
	v_mfma_f32_16x16x32_bf16 v[64:67], v[178:181], v[210:213], v[64:67]
	s_barrier
	s_add_i32 s26, s52, s33
	s_mov_b32 m0, s26
	ds_read_b128 v[182:185], v169 offset:49152
	ds_read_b128 v[186:189], v169 offset:50176
	ds_read_b128 v[190:193], v169 offset:51200
	ds_read_b128 v[194:197], v169 offset:52224
	ds_read_b128 v[198:201], v169 offset:53248
	ds_read_b128 v[202:205], v169 offset:54272
	ds_read_b128 v[206:209], v169 offset:55296
	ds_read_b128 v[210:213], v169 offset:56320
	global_load_lds_dwordx4 v146, s[98:99]
	s_add_i32 m0, s26, 0x2000
	s_add_u32 s26, s30, 0xb0080
	s_addc_u32 s27, s31, 0
	s_add_i32 s30, s53, s33
	global_load_lds_dwordx4 v150, s[98:99]
	s_mov_b32 m0, s30
	s_nop 0
	global_load_lds_dwordx4 v146, s[26:27]
	s_add_i32 m0, s30, 0x2000
	s_nop 0
	global_load_lds_dwordx4 v150, s[26:27]
	s_mov_b32 m0, s48
	s_nop 0
	global_load_lds_dwordx4 v144, s[100:101]
	s_mov_b32 m0, s49
	s_nop 0
	global_load_lds_dwordx4 v148, s[100:101]
	s_waitcnt vmcnt(8)
	s_barrier
	s_waitcnt lgkmcnt(0)
	v_mfma_f32_16x16x32_bf16 v[60:63], v[120:123], v[182:185], v[60:63]
	v_mfma_f32_16x16x32_bf16 v[56:59], v[128:131], v[182:185], v[56:59]
	v_mfma_f32_16x16x32_bf16 v[44:47], v[120:123], v[190:193], v[44:47]
	v_mfma_f32_16x16x32_bf16 v[40:43], v[128:131], v[190:193], v[40:43]
	v_mfma_f32_16x16x32_bf16 v[28:31], v[120:123], v[198:201], v[28:31]
	v_mfma_f32_16x16x32_bf16 v[24:27], v[128:131], v[198:201], v[24:27]
	v_mfma_f32_16x16x32_bf16 v[12:15], v[120:123], v[206:209], v[12:15]
	v_mfma_f32_16x16x32_bf16 v[8:11], v[128:131], v[206:209], v[8:11]
	v_mfma_f32_16x16x32_bf16 v[60:63], v[124:127], v[186:189], v[60:63]
	v_mfma_f32_16x16x32_bf16 v[56:59], v[132:135], v[186:189], v[56:59]
	v_mfma_f32_16x16x32_bf16 v[44:47], v[124:127], v[194:197], v[44:47]
	v_mfma_f32_16x16x32_bf16 v[40:43], v[132:135], v[194:197], v[40:43]
	v_mfma_f32_16x16x32_bf16 v[28:31], v[124:127], v[202:205], v[28:31]
	v_mfma_f32_16x16x32_bf16 v[24:27], v[132:135], v[202:205], v[24:27]
	v_mfma_f32_16x16x32_bf16 v[12:15], v[124:127], v[210:213], v[12:15]
	v_mfma_f32_16x16x32_bf16 v[8:11], v[132:135], v[210:213], v[8:11]
	v_mfma_f32_16x16x32_bf16 v[52:55], v[160:163], v[182:185], v[52:55]
	v_mfma_f32_16x16x32_bf16 v[48:51], v[174:177], v[182:185], v[48:51]
	v_mfma_f32_16x16x32_bf16 v[36:39], v[160:163], v[190:193], v[36:39]
	v_mfma_f32_16x16x32_bf16 v[32:35], v[174:177], v[190:193], v[32:35]
	v_mfma_f32_16x16x32_bf16 v[20:23], v[160:163], v[198:201], v[20:23]
	v_mfma_f32_16x16x32_bf16 v[16:19], v[174:177], v[198:201], v[16:19]
	v_mfma_f32_16x16x32_bf16 v[4:7], v[160:163], v[206:209], v[4:7]
	v_mfma_f32_16x16x32_bf16 v[0:3], v[174:177], v[206:209], v[0:3]
	v_mfma_f32_16x16x32_bf16 v[52:55], v[170:173], v[186:189], v[52:55]
	v_mfma_f32_16x16x32_bf16 v[48:51], v[178:181], v[186:189], v[48:51]
	v_mfma_f32_16x16x32_bf16 v[36:39], v[170:173], v[194:197], v[36:39]
	v_mfma_f32_16x16x32_bf16 v[32:35], v[178:181], v[194:197], v[32:35]
	v_mfma_f32_16x16x32_bf16 v[20:23], v[170:173], v[202:205], v[20:23]
	v_mfma_f32_16x16x32_bf16 v[16:19], v[178:181], v[202:205], v[16:19]
	v_mfma_f32_16x16x32_bf16 v[4:7], v[170:173], v[210:213], v[4:7]
	v_mfma_f32_16x16x32_bf16 v[0:3], v[178:181], v[210:213], v[0:3]
	s_barrier
	s_add_i32 s63, s63, 2
	s_add_u32 s61, s61, 0x100
	s_addc_u32 s62, s62, 0
	s_cmp_gt_u32 s63, 41
	s_mov_b64 s[26:27], s[28:29]
	s_cbranch_scc0 .LBB0_1697
	s_and_b64 vcc, exec, s[14:15]
	s_cbranch_vccz .LBB0_1700
	s_barrier
